# P1 in_proj epilogue stores transposed through a 2 KiB/wave LDS scratch: each store instruction writes whole 64/128-B row segments (was 16 rows x 16-B pieces per 16 lanes)
# speedup vs baseline: 1.0144x; 1.0144x over previous
;     __device__ __forceinline__ void operator()(const f32x4 (&acc)[2][2][4][2], const Unit& u, int wr, int wc, int fr, int fq) const {
;         const int row0 = u.pm * BM + wr * 64 + fr; const int pn = u.pn;
;         if (pn < 4) {
;             bf16_t* dst = (bf16_t*)(ws + ((pn < 2) ? EW_U : EW_GV)); float* st1 = (float*)ws + EC_ST1; float* st2 = (float*)ws + EC_ST2; const int col0 = (pn & 1) * 256 + wc * 32 + 8 * fq; const bool stats = pn >= 2;
; __global__ void __launch_bounds__(NWAVES * 64, 2) hymba_fwd(Args args) {
;     ...
;     if (IN(1)) {
;         pg8::Gemm g{(const bf16*)(ws + WS_XN), (const bf16*)(ws + WS_WIN), M, NIN, DM}; pg8::StaticOrder S; S.init(M, NIN, F.G, (int)blockIdx.x);
;         pg8::EpiIn E{ws, args.out, args.in[10], args.in[11]};
;         pg8::gemm_phase<pg8::EpiIn, pg8::StaticOrder, PG8_ALIGN, PG8_SP2>(F.lds + RING_OFF, g, S, E);
.LBB0_132:
	s_cmp_lt_i32 s92, 2
	s_cselect_b64 s[0:1], -1, 0
	s_cmp_gt_i32 s93, 1
	s_cselect_b64 s[2:3], -1, 0
	s_and_b64 s[0:1], s[0:1], s[2:3]
	s_andn2_b64 vcc, exec, s[0:1]
	s_cbranch_vccnz .LBB0_640
	v_and_b32_e32 v229, 63, v0
	v_lshrrev_b32_e32 v230, 6, v0
	v_lshlrev_b32_e32 v230, 11, v230
	v_add_u32_e32 v230, 0x24000, v230
	v_and_b32_e32 v231, 15, v229
	v_lshrrev_b32_e32 v232, 4, v229
	v_and_b32_e32 v233, 3, v231
	v_xor_b32_e32 v233, v232, v233
	v_lshlrev_b32_e32 v222, 4, v233
	v_lshl_add_u32 v222, v231, 6, v222
	v_add_u32_e32 v222, v230, v222
	v_lshlrev_b32_e32 v225, 5, v233
	v_lshl_add_u32 v225, v231, 7, v225
	v_add_u32_e32 v225, v230, v225
	v_lshrrev_b32_e32 v231, 2, v229
	v_and_b32_e32 v232, 3, v229
	v_and_b32_e32 v233, 3, v231
	v_xor_b32_e32 v233, v232, v233
	v_lshlrev_b32_e32 v223, 4, v233
	v_lshl_add_u32 v223, v231, 6, v223
	v_add_u32_e32 v223, v230, v223
	v_lshlrev_b32_e32 v224, 4, v232
	v_lshl_add_u32 v224, v231, 10, v224
	v_lshrrev_b32_e32 v231, 3, v229
	v_and_b32_e32 v232, 7, v229
	v_lshlrev_b32_e32 v227, 4, v232
	v_lshl_add_u32 v227, v231, 11, v227
	v_add_u32_e32 v228, 0x4000, v227
	v_lshrrev_b32_e32 v233, 1, v232
	v_and_b32_e32 v232, 1, v232
	v_and_b32_e32 v229, 3, v231
	v_xor_b32_e32 v233, v233, v229
	v_lshl_or_b32 v233, v233, 1, v232
	v_lshlrev_b32_e32 v233, 4, v233
	v_lshl_add_u32 v226, v231, 7, v233
	v_add_u32_e32 v226, v230, v226
	s_cmpk_lt_i32 s96, 0x294
	s_cselect_b64 s[2:3], -1, 0
	s_cmpk_gt_i32 s96, 0x293
	v_readfirstlane_b32 s10, v0
	s_cbranch_scc1 .LBB0_139
	s_ashr_i32 s0, s96, 31
	s_lshr_b32 s0, s0, 29
	s_add_i32 s0, s96, s0
	s_and_b32 s1, s0, -8
	s_sub_i32 s1, s96, s1
	s_cmp_gt_i32 s1, 3
	s_cbranch_scc0 .LBB0_136
	s_mul_i32 s4, s1, 0x52
	s_add_i32 s6, s4, 4
	s_cbranch_execz .LBB0_137
	s_branch .LBB0_138

; __device__ __forceinline__ unsigned cvt_pk_bf16(float lo, float hi) { unsigned r; asm volatile("v_cvt_pk_bf16_f32 %0, %1, %2" : "=v"(r) : "v"(lo), "v"(hi)); return r; }
;     __device__ __forceinline__ void operator()(const f32x4 (&acc)[2][2][4][2], const Unit& u, int wr, int wc, int fr, int fq) const {
;     ...
;             const int sec = pn >> 1, head = 4 * (pn & 1) + wc; const bool prompt = u.pm < (XM_PROMPT / BM);
;             bf16_t* dst = (bf16_t*)(ws + ((sec == 2) ? EW_Q : (sec == 3) ? EW_K : EW_V)); const float* gp = (sec == 2) ? gq : gk;
;             float* fo = (sec == 2) ? nullptr : out + ((sec == 3) ? (prompt ? EO_KP : EO_KS) : (prompt ? EO_VP : EO_VS));
;             f32x4 gv[2][2];
; #pragma unroll
;             for (int bj = 0; bj < 2; ++bj)
; #pragma unroll
;                 for (int n = 0; n < 2; ++n) gv[bj][n] = (sec < 4) ? *(const f32x4*)(gp + 32 * bj + 8 * fq + 4 * n) : (f32x4){1.f, 1.f, 1.f, 1.f};
;             const float post = (sec == 2) ? QSCALE : 1.0f;
; #pragma unroll
;             for (int ai = 0; ai < 2; ++ai)
; #pragma unroll
;                 for (int m = 0; m < 4; ++m) { const int row = row0 + ai * HALF + m * 16; const int orow = prompt ? row : row - XM_PROMPT;
;                     float ss = 0.f;
; #pragma unroll
;                     for (int bj = 0; bj < 2; ++bj)
; #pragma unroll
;                         for (int n = 0; n < 2; ++n) { const f32x4 x = acc[ai][bj][m][n]; ss += (x[0] * x[0] + x[1] * x[1]) + (x[2] * x[2] + x[3] * x[3]); }
;                     ss = quad_sum(ss);
;                     const float rr = (sec < 4) ? post * (1.0f / sqrtf(ss * (1.0f / 64.0f) + 1e-6f)) : 1.0f;
; #pragma unroll
;                     for (int bj = 0; bj < 2; ++bj) { const f32x4 v0 = acc[ai][bj][m][0] * rr * gv[bj][0], v1 = acc[ai][bj][m][1] * rr * gv[bj][1];
;                         const int dcol = 64 * head + 32 * bj + 8 * fq;
;                         u32x4 w; w.x = cvt_pk_bf16(v0[0], v0[1]); w.y = cvt_pk_bf16(v0[2], v0[3]); w.z = cvt_pk_bf16(v1[0], v1[1]); w.w = cvt_pk_bf16(v1[2], v1[3]);
;                         *(u32x4*)(dst + (size_t)row * 512 + dcol) = w;
;                         if (fo) { float* op = fo + (size_t)orow * 512 + dcol; if (prompt) { __builtin_nontemporal_store(v0, (f32x4*)op); __builtin_nontemporal_store(v1, (f32x4*)(op + 4)); } else { *(f32x4*)op = v0; *(f32x4*)(op + 4) = v1; } } } }
.LBB0_167:
	s_lshl_b32 s10, s88, 2
	s_and_b32 s38, s10, 4
	s_cmp_eq_u32 s13, 3
	s_cselect_b64 s[36:37], -1, 0
	s_and_b64 s[10:11], s[36:37], exec
	s_mov_b32 s10, 0x7500000
	s_cselect_b32 s13, s10, 0x8600000
	s_and_b64 s[10:11], s[8:9], exec
	s_cselect_b32 s39, 0x6400000, s13
	s_cmp_lt_i32 s12, 64
	s_cselect_b64 s[10:11], -1, 0
	s_and_b64 s[12:13], s[10:11], exec
	s_mov_b32 s12, 0x1880000
	s_cselect_b32 s40, s12, 0x20c0000
	s_mov_b32 s12, 0x1080000
	s_cselect_b32 s41, s12, 0x2080000
	s_and_b64 s[12:13], s[36:37], exec
	s_cselect_b32 s12, s41, s40
	v_readlane_b32 s40, v251, 6
	s_lshl_b32 s12, s12, 2
	v_readlane_b32 s46, v251, 12
	v_readlane_b32 s41, v251, 7
	v_readlane_b32 s47, v251, 13
	s_add_u32 s12, s46, s12
	s_addc_u32 s13, s47, 0
	s_or_b32 s36, s38, s75
	v_readlane_b32 s40, v251, 4
	v_add_u32_e32 v146, 0xffffc000, v166
	v_readlane_b32 s41, v251, 5
	s_add_u32 s90, s40, s39
	v_cndmask_b32_e64 v146, v146, v166, s[10:11]
	s_addc_u32 s91, s41, 0
	s_and_b64 s[8:9], s[8:9], exec
	s_waitcnt lgkmcnt(0)
	v_ashrrev_i32_e32 v147, 31, v146
	s_cselect_b32 s13, 0, s13
	s_cselect_b32 s12, 0, s12
	v_lshl_or_b32 v171, s36, 6, v158
	v_ashrrev_i32_e32 v167, 31, v166
	v_lshlrev_b64 v[146:147], 11, v[146:147]
	v_lshlrev_b64 v[148:149], 10, v[166:167]
	v_lshl_add_u64 v[172:173], s[12:13], 0, v[146:147]
	v_pk_mul_f32 v[146:147], v[128:129], v[170:171] op_sel_hi:[1,0]
	v_pk_mul_f32 v[150:151], v[126:127], v[170:171] op_sel_hi:[1,0]
	v_lshl_add_u64 v[168:169], s[90:91], 0, v[148:149]
	s_waitcnt vmcnt(0)
	v_pk_mul_f32 v[148:149], v[144:145], v[146:147]
	v_pk_mul_f32 v[146:147], v[142:143], v[150:151]
	v_pk_mul_f32 v[150:151], v[124:125], v[170:171] op_sel_hi:[1,0]
	v_pk_mul_f32 v[174:175], v[122:123], v[170:171] op_sel_hi:[1,0]
	v_lshlrev_b32_e32 v156, 1, v171
	v_cndmask_b32_e64 v167, 0, 1, s[14:15]
	v_pk_mul_f32 v[152:153], v[136:137], v[150:151]
	v_pk_mul_f32 v[150:151], v[134:135], v[174:175]
	v_lshl_add_u64 v[174:175], v[168:169], 0, v[156:157]
	v_cmp_ne_u32_e64 s[8:9], 1, v167
	s_andn2_b64 vcc, exec, s[14:15]
	v_lshlrev_b32_e32 v168, 2, v171
	v_readlane_b32 s42, v251, 8
	v_readlane_b32 s43, v251, 9
	v_readlane_b32 s44, v251, 10
	v_readlane_b32 s45, v251, 11
	v_cvt_pk_bf16_f32 v186, v146, v147
	v_cvt_pk_bf16_f32 v187, v148, v149
	v_cvt_pk_bf16_f32 v188, v150, v151
	v_cvt_pk_bf16_f32 v189, v152, v153
	s_nop 0
	v_readfirstlane_b32 s98, v174
	v_readfirstlane_b32 s99, v175
	ds_write_b128 v222, v[186:189]
	ds_read_b128 v[230:233], v223
	s_waitcnt lgkmcnt(0)
	s_nop 1
	global_store_dwordx4 v224, v[230:233], s[98:99]
	s_cbranch_vccnz .LBB0_169
	v_mov_b32_e32 v169, v157
	v_lshl_add_u64 v[186:187], v[172:173], 0, v[168:169]
	s_nop 0
	v_readfirstlane_b32 s100, v186
	v_readfirstlane_b32 s101, v187
	ds_write_b128 v225, v[146:149]
	ds_write_b128 v225, v[150:153] offset:16
	ds_read_b128 v[234:237], v226
	ds_read_b128 v[238:241], v226 offset:1024
	s_waitcnt lgkmcnt(0)
	global_store_dwordx4 v227, v[234:237], s[100:101]
	global_store_dwordx4 v228, v[238:241], s[100:101]
.LBB0_169:
	v_mov_b32_e32 v171, v170
	s_nop 0
	v_mov_b32_e32 v150, v170
	v_mov_b32_e32 v151, v170
	v_pk_mul_f32 v[146:147], v[120:121], v[150:151]
	v_pk_mul_f32 v[152:153], v[118:119], v[170:171]
	v_pk_mul_f32 v[150:151], v[116:117], v[150:151]
	v_pk_mul_f32 v[170:171], v[114:115], v[170:171]
	v_pk_mul_f32 v[148:149], v[140:141], v[146:147]
	v_pk_mul_f32 v[146:147], v[138:139], v[152:153]
	v_pk_mul_f32 v[152:153], v[132:133], v[150:151]
	v_pk_mul_f32 v[150:151], v[130:131], v[170:171]
	s_and_b64 vcc, exec, s[8:9]
	v_cvt_pk_bf16_f32 v186, v146, v147
	v_cvt_pk_bf16_f32 v187, v148, v149
	v_cvt_pk_bf16_f32 v188, v150, v151
	v_cvt_pk_bf16_f32 v189, v152, v153
	s_nop 0
	v_readfirstlane_b32 s98, v174
	v_readfirstlane_b32 s99, v175
	ds_write_b128 v222, v[186:189]
	ds_read_b128 v[230:233], v223
	s_waitcnt lgkmcnt(0)
	s_nop 1
	global_store_dwordx4 v224, v[230:233], s[98:99] offset:64
	s_cbranch_vccnz .LBB0_171
	v_mov_b32_e32 v169, v157
	v_lshl_add_u64 v[170:171], v[172:173], 0, v[168:169]
	s_nop 0
	v_readfirstlane_b32 s100, v170
	v_readfirstlane_b32 s101, v171
	ds_write_b128 v225, v[146:149]
	ds_write_b128 v225, v[150:153] offset:16
	ds_read_b128 v[234:237], v226
	ds_read_b128 v[238:241], v226 offset:1024
	s_waitcnt lgkmcnt(0)
	global_store_dwordx4 v227, v[234:237], s[100:101] offset:128
	global_store_dwordx4 v228, v[238:241], s[100:101] offset:128

; __device__ __forceinline__ unsigned cvt_pk_bf16(float lo, float hi) { unsigned r; asm volatile("v_cvt_pk_bf16_f32 %0, %1, %2" : "=v"(r) : "v"(lo), "v"(hi)); return r; }
; __device__ __forceinline__ float quad_sum(float s) { s += __shfl_xor(s, 16); s += __shfl_xor(s, 32); return s; }
;     __device__ __forceinline__ void operator()(const f32x4 (&acc)[2][2][4][2], const Unit& u, int wr, int wc, int fr, int fq) const {
;     ...
;                 for (int m = 0; m < 4; ++m) { const int row = row0 + ai * HALF + m * 16; const int orow = prompt ? row : row - XM_PROMPT;
;                     float ss = 0.f;
; #pragma unroll
;                     for (int bj = 0; bj < 2; ++bj)
; #pragma unroll
;                         for (int n = 0; n < 2; ++n) { const f32x4 x = acc[ai][bj][m][n]; ss += (x[0] * x[0] + x[1] * x[1]) + (x[2] * x[2] + x[3] * x[3]); }
;                     ss = quad_sum(ss);
;                     const float rr = (sec < 4) ? post * (1.0f / sqrtf(ss * (1.0f / 64.0f) + 1e-6f)) : 1.0f;
; #pragma unroll
;                     for (int bj = 0; bj < 2; ++bj) { const f32x4 v0 = acc[ai][bj][m][0] * rr * gv[bj][0], v1 = acc[ai][bj][m][1] * rr * gv[bj][1];
;                         const int dcol = 64 * head + 32 * bj + 8 * fq;
;                         u32x4 w; w.x = cvt_pk_bf16(v0[0], v0[1]); w.y = cvt_pk_bf16(v0[2], v0[3]); w.z = cvt_pk_bf16(v1[0], v1[1]); w.w = cvt_pk_bf16(v1[2], v1[3]);
;                         *(u32x4*)(dst + (size_t)row * 512 + dcol) = w;
;                         if (fo) { float* op = fo + (size_t)orow * 512 + dcol; if (prompt) { __builtin_nontemporal_store(v0, (f32x4*)op); __builtin_nontemporal_store(v1, (f32x4*)(op + 4)); } else { *(f32x4*)op = v0; *(f32x4*)(op + 4) = v1; } } } }
.LBB0_173:
	v_or_b32_e32 v146, 16, v166
	s_waitcnt lgkmcnt(0)
	v_add_u32_e32 v147, 0xffffc010, v166
	v_cndmask_b32_e64 v148, v147, v146, s[10:11]
	v_ashrrev_i32_e32 v147, 31, v146
	v_lshlrev_b64 v[146:147], 10, v[146:147]
	v_ashrrev_i32_e32 v149, 31, v148
	v_lshl_add_u64 v[174:175], s[90:91], 0, v[146:147]
	v_lshlrev_b64 v[146:147], 11, v[148:149]
	v_lshl_add_u64 v[170:171], s[12:13], 0, v[146:147]
	v_pk_mul_f32 v[146:147], v[112:113], v[172:173] op_sel_hi:[1,0]
	v_pk_mul_f32 v[150:151], v[110:111], v[172:173] op_sel_hi:[1,0]
	v_pk_mul_f32 v[148:149], v[144:145], v[146:147]
	v_pk_mul_f32 v[146:147], v[142:143], v[150:151]
	v_pk_mul_f32 v[150:151], v[108:109], v[172:173] op_sel_hi:[1,0]
	v_pk_mul_f32 v[186:187], v[106:107], v[172:173] op_sel_hi:[1,0]
	v_pk_mul_f32 v[152:153], v[136:137], v[150:151]
	v_pk_mul_f32 v[150:151], v[134:135], v[186:187]
	v_lshl_add_u64 v[174:175], v[174:175], 0, v[156:157]
	s_and_b64 vcc, exec, s[8:9]
	v_cvt_pk_bf16_f32 v186, v146, v147
	v_cvt_pk_bf16_f32 v187, v148, v149
	v_cvt_pk_bf16_f32 v188, v150, v151
	v_cvt_pk_bf16_f32 v189, v152, v153
	s_nop 0
	v_readfirstlane_b32 s98, v174
	v_readfirstlane_b32 s99, v175
	ds_write_b128 v222, v[186:189]
	ds_read_b128 v[230:233], v223
	s_waitcnt lgkmcnt(0)
	s_nop 1
	global_store_dwordx4 v224, v[230:233], s[98:99]
	s_cbranch_vccnz .LBB0_175
	v_mov_b32_e32 v169, v157
	v_lshl_add_u64 v[186:187], v[170:171], 0, v[168:169]
	s_nop 0
	v_readfirstlane_b32 s100, v186
	v_readfirstlane_b32 s101, v187
	ds_write_b128 v225, v[146:149]
	ds_write_b128 v225, v[150:153] offset:16
	ds_read_b128 v[234:237], v226
	ds_read_b128 v[238:241], v226 offset:1024
	s_waitcnt lgkmcnt(0)
	global_store_dwordx4 v227, v[234:237], s[100:101]
	global_store_dwordx4 v228, v[238:241], s[100:101]
.LBB0_175:
	v_mov_b32_e32 v173, v172
	s_nop 0
	v_mov_b32_e32 v150, v172
	v_mov_b32_e32 v151, v172
	v_pk_mul_f32 v[146:147], v[104:105], v[150:151]
	v_pk_mul_f32 v[152:153], v[102:103], v[172:173]
	v_pk_mul_f32 v[150:151], v[100:101], v[150:151]
	v_pk_mul_f32 v[172:173], v[98:99], v[172:173]
	v_pk_mul_f32 v[148:149], v[140:141], v[146:147]
	v_pk_mul_f32 v[146:147], v[138:139], v[152:153]
	v_pk_mul_f32 v[152:153], v[132:133], v[150:151]
	v_pk_mul_f32 v[150:151], v[130:131], v[172:173]
	s_and_b64 vcc, exec, s[8:9]
	v_cvt_pk_bf16_f32 v186, v146, v147
	v_cvt_pk_bf16_f32 v187, v148, v149
	v_cvt_pk_bf16_f32 v188, v150, v151
	v_cvt_pk_bf16_f32 v189, v152, v153
	s_nop 0
	v_readfirstlane_b32 s98, v174
	v_readfirstlane_b32 s99, v175
	ds_write_b128 v222, v[186:189]
	ds_read_b128 v[230:233], v223
	s_waitcnt lgkmcnt(0)
	s_nop 1
	global_store_dwordx4 v224, v[230:233], s[98:99] offset:64
	s_cbranch_vccnz .LBB0_177
	v_mov_b32_e32 v169, v157
	v_lshl_add_u64 v[170:171], v[170:171], 0, v[168:169]
	s_nop 0
	v_readfirstlane_b32 s100, v170
	v_readfirstlane_b32 s101, v171
	ds_write_b128 v225, v[146:149]
	ds_write_b128 v225, v[150:153] offset:16
	ds_read_b128 v[234:237], v226
	ds_read_b128 v[238:241], v226 offset:1024
	s_waitcnt lgkmcnt(0)
	global_store_dwordx4 v227, v[234:237], s[100:101] offset:128
	global_store_dwordx4 v228, v[238:241], s[100:101] offset:128

; __device__ __forceinline__ unsigned cvt_pk_bf16(float lo, float hi) { unsigned r; asm volatile("v_cvt_pk_bf16_f32 %0, %1, %2" : "=v"(r) : "v"(lo), "v"(hi)); return r; }
; __device__ __forceinline__ float quad_sum(float s) { s += __shfl_xor(s, 16); s += __shfl_xor(s, 32); return s; }
;     __device__ __forceinline__ void operator()(const f32x4 (&acc)[2][2][4][2], const Unit& u, int wr, int wc, int fr, int fq) const {
;     ...
;                 for (int m = 0; m < 4; ++m) { const int row = row0 + ai * HALF + m * 16; const int orow = prompt ? row : row - XM_PROMPT;
;                     float ss = 0.f;
; #pragma unroll
;                     for (int bj = 0; bj < 2; ++bj)
; #pragma unroll
;                         for (int n = 0; n < 2; ++n) { const f32x4 x = acc[ai][bj][m][n]; ss += (x[0] * x[0] + x[1] * x[1]) + (x[2] * x[2] + x[3] * x[3]); }
;                     ss = quad_sum(ss);
;                     const float rr = (sec < 4) ? post * (1.0f / sqrtf(ss * (1.0f / 64.0f) + 1e-6f)) : 1.0f;
; #pragma unroll
;                     for (int bj = 0; bj < 2; ++bj) { const f32x4 v0 = acc[ai][bj][m][0] * rr * gv[bj][0], v1 = acc[ai][bj][m][1] * rr * gv[bj][1];
;                         const int dcol = 64 * head + 32 * bj + 8 * fq;
;                         u32x4 w; w.x = cvt_pk_bf16(v0[0], v0[1]); w.y = cvt_pk_bf16(v0[2], v0[3]); w.z = cvt_pk_bf16(v1[0], v1[1]); w.w = cvt_pk_bf16(v1[2], v1[3]);
;                         *(u32x4*)(dst + (size_t)row * 512 + dcol) = w;
;                         if (fo) { float* op = fo + (size_t)orow * 512 + dcol; if (prompt) { __builtin_nontemporal_store(v0, (f32x4*)op); __builtin_nontemporal_store(v1, (f32x4*)(op + 4)); } else { *(f32x4*)op = v0; *(f32x4*)(op + 4) = v1; } } } }
.LBB0_179:
	v_or_b32_e32 v146, 32, v166
	s_waitcnt lgkmcnt(0)
	v_add_u32_e32 v147, 0xffffc020, v166
	v_cndmask_b32_e64 v148, v147, v146, s[10:11]
	v_ashrrev_i32_e32 v147, 31, v146
	v_lshlrev_b64 v[146:147], 10, v[146:147]
	v_ashrrev_i32_e32 v149, 31, v148
	v_lshl_add_u64 v[174:175], s[90:91], 0, v[146:147]
	v_lshlrev_b64 v[146:147], 11, v[148:149]
	v_lshl_add_u64 v[170:171], s[12:13], 0, v[146:147]
	v_pk_mul_f32 v[146:147], v[96:97], v[172:173] op_sel_hi:[1,0]
	v_pk_mul_f32 v[150:151], v[94:95], v[172:173] op_sel_hi:[1,0]
	v_pk_mul_f32 v[148:149], v[144:145], v[146:147]
	v_pk_mul_f32 v[146:147], v[142:143], v[150:151]
	v_pk_mul_f32 v[150:151], v[92:93], v[172:173] op_sel_hi:[1,0]
	v_pk_mul_f32 v[186:187], v[90:91], v[172:173] op_sel_hi:[1,0]
	v_pk_mul_f32 v[152:153], v[136:137], v[150:151]
	v_pk_mul_f32 v[150:151], v[134:135], v[186:187]
	v_lshl_add_u64 v[174:175], v[174:175], 0, v[156:157]
	s_and_b64 vcc, exec, s[8:9]
	v_cvt_pk_bf16_f32 v186, v146, v147
	v_cvt_pk_bf16_f32 v187, v148, v149
	v_cvt_pk_bf16_f32 v188, v150, v151
	v_cvt_pk_bf16_f32 v189, v152, v153
	s_nop 0
	v_readfirstlane_b32 s98, v174
	v_readfirstlane_b32 s99, v175
	ds_write_b128 v222, v[186:189]
	ds_read_b128 v[230:233], v223
	s_waitcnt lgkmcnt(0)
	s_nop 1
	global_store_dwordx4 v224, v[230:233], s[98:99]
	s_cbranch_vccnz .LBB0_181
	v_mov_b32_e32 v169, v157
	v_lshl_add_u64 v[186:187], v[170:171], 0, v[168:169]
	s_nop 0
	v_readfirstlane_b32 s100, v186
	v_readfirstlane_b32 s101, v187
	ds_write_b128 v225, v[146:149]
	ds_write_b128 v225, v[150:153] offset:16
	ds_read_b128 v[234:237], v226
	ds_read_b128 v[238:241], v226 offset:1024
	s_waitcnt lgkmcnt(0)
	global_store_dwordx4 v227, v[234:237], s[100:101]
	global_store_dwordx4 v228, v[238:241], s[100:101]
.LBB0_181:
	v_mov_b32_e32 v173, v172
	s_nop 0
	v_mov_b32_e32 v150, v172
	v_mov_b32_e32 v151, v172
	v_pk_mul_f32 v[146:147], v[88:89], v[150:151]
	v_pk_mul_f32 v[152:153], v[86:87], v[172:173]
	v_pk_mul_f32 v[150:151], v[84:85], v[150:151]
	v_pk_mul_f32 v[172:173], v[82:83], v[172:173]
	v_pk_mul_f32 v[148:149], v[140:141], v[146:147]
	v_pk_mul_f32 v[146:147], v[138:139], v[152:153]
	v_pk_mul_f32 v[152:153], v[132:133], v[150:151]
	v_pk_mul_f32 v[150:151], v[130:131], v[172:173]
	s_and_b64 vcc, exec, s[8:9]
	v_cvt_pk_bf16_f32 v186, v146, v147
	v_cvt_pk_bf16_f32 v187, v148, v149
	v_cvt_pk_bf16_f32 v188, v150, v151
	v_cvt_pk_bf16_f32 v189, v152, v153
	s_nop 0
	v_readfirstlane_b32 s98, v174
	v_readfirstlane_b32 s99, v175
	ds_write_b128 v222, v[186:189]
	ds_read_b128 v[230:233], v223
	s_waitcnt lgkmcnt(0)
	s_nop 1
	global_store_dwordx4 v224, v[230:233], s[98:99] offset:64
	s_cbranch_vccnz .LBB0_183
	v_mov_b32_e32 v169, v157
	v_lshl_add_u64 v[170:171], v[170:171], 0, v[168:169]
	s_nop 0
	v_readfirstlane_b32 s100, v170
	v_readfirstlane_b32 s101, v171
	ds_write_b128 v225, v[146:149]
	ds_write_b128 v225, v[150:153] offset:16
	ds_read_b128 v[234:237], v226
	ds_read_b128 v[238:241], v226 offset:1024
	s_waitcnt lgkmcnt(0)
	global_store_dwordx4 v227, v[234:237], s[100:101] offset:128
	global_store_dwordx4 v228, v[238:241], s[100:101] offset:128

; __device__ __forceinline__ unsigned cvt_pk_bf16(float lo, float hi) { unsigned r; asm volatile("v_cvt_pk_bf16_f32 %0, %1, %2" : "=v"(r) : "v"(lo), "v"(hi)); return r; }
; __device__ __forceinline__ float quad_sum(float s) { s += __shfl_xor(s, 16); s += __shfl_xor(s, 32); return s; }
;     __device__ __forceinline__ void operator()(const f32x4 (&acc)[2][2][4][2], const Unit& u, int wr, int wc, int fr, int fq) const {
;     ...
;                 for (int m = 0; m < 4; ++m) { const int row = row0 + ai * HALF + m * 16; const int orow = prompt ? row : row - XM_PROMPT;
;                     float ss = 0.f;
; #pragma unroll
;                     for (int bj = 0; bj < 2; ++bj)
; #pragma unroll
;                         for (int n = 0; n < 2; ++n) { const f32x4 x = acc[ai][bj][m][n]; ss += (x[0] * x[0] + x[1] * x[1]) + (x[2] * x[2] + x[3] * x[3]); }
;                     ss = quad_sum(ss);
;                     const float rr = (sec < 4) ? post * (1.0f / sqrtf(ss * (1.0f / 64.0f) + 1e-6f)) : 1.0f;
; #pragma unroll
;                     for (int bj = 0; bj < 2; ++bj) { const f32x4 v0 = acc[ai][bj][m][0] * rr * gv[bj][0], v1 = acc[ai][bj][m][1] * rr * gv[bj][1];
;                         const int dcol = 64 * head + 32 * bj + 8 * fq;
;                         u32x4 w; w.x = cvt_pk_bf16(v0[0], v0[1]); w.y = cvt_pk_bf16(v0[2], v0[3]); w.z = cvt_pk_bf16(v1[0], v1[1]); w.w = cvt_pk_bf16(v1[2], v1[3]);
;                         *(u32x4*)(dst + (size_t)row * 512 + dcol) = w;
;                         if (fo) { float* op = fo + (size_t)orow * 512 + dcol; if (prompt) { __builtin_nontemporal_store(v0, (f32x4*)op); __builtin_nontemporal_store(v1, (f32x4*)(op + 4)); } else { *(f32x4*)op = v0; *(f32x4*)(op + 4) = v1; } } } }
.LBB0_185:
	v_or_b32_e32 v146, 48, v166
	s_waitcnt lgkmcnt(0)
	v_add_u32_e32 v147, 0xffffc030, v166
	v_cndmask_b32_e64 v148, v147, v146, s[10:11]
	v_ashrrev_i32_e32 v147, 31, v146
	v_lshlrev_b64 v[146:147], 10, v[146:147]
	v_ashrrev_i32_e32 v149, 31, v148
	v_lshl_add_u64 v[174:175], s[90:91], 0, v[146:147]
	v_lshlrev_b64 v[146:147], 11, v[148:149]
	v_lshl_add_u64 v[170:171], s[12:13], 0, v[146:147]
	v_pk_mul_f32 v[146:147], v[80:81], v[172:173] op_sel_hi:[1,0]
	v_pk_mul_f32 v[150:151], v[78:79], v[172:173] op_sel_hi:[1,0]
	v_pk_mul_f32 v[148:149], v[144:145], v[146:147]
	v_pk_mul_f32 v[146:147], v[142:143], v[150:151]
	v_pk_mul_f32 v[150:151], v[76:77], v[172:173] op_sel_hi:[1,0]
	v_pk_mul_f32 v[186:187], v[74:75], v[172:173] op_sel_hi:[1,0]
	v_pk_mul_f32 v[152:153], v[136:137], v[150:151]
	v_pk_mul_f32 v[150:151], v[134:135], v[186:187]
	v_lshl_add_u64 v[174:175], v[174:175], 0, v[156:157]
	s_and_b64 vcc, exec, s[8:9]
	v_cvt_pk_bf16_f32 v186, v146, v147
	v_cvt_pk_bf16_f32 v187, v148, v149
	v_cvt_pk_bf16_f32 v188, v150, v151
	v_cvt_pk_bf16_f32 v189, v152, v153
	s_nop 0
	v_readfirstlane_b32 s98, v174
	v_readfirstlane_b32 s99, v175
	ds_write_b128 v222, v[186:189]
	ds_read_b128 v[230:233], v223
	s_waitcnt lgkmcnt(0)
	s_nop 1
	global_store_dwordx4 v224, v[230:233], s[98:99]
	s_cbranch_vccnz .LBB0_187
	v_mov_b32_e32 v169, v157
	v_lshl_add_u64 v[186:187], v[170:171], 0, v[168:169]
	s_nop 0
	v_readfirstlane_b32 s100, v186
	v_readfirstlane_b32 s101, v187
	ds_write_b128 v225, v[146:149]
	ds_write_b128 v225, v[150:153] offset:16
	ds_read_b128 v[234:237], v226
	ds_read_b128 v[238:241], v226 offset:1024
	s_waitcnt lgkmcnt(0)
	global_store_dwordx4 v227, v[234:237], s[100:101]
	global_store_dwordx4 v228, v[238:241], s[100:101]
.LBB0_187:
	v_mov_b32_e32 v173, v172
	s_nop 0
	v_mov_b32_e32 v150, v172
	v_mov_b32_e32 v151, v172
	v_pk_mul_f32 v[146:147], v[72:73], v[150:151]
	v_pk_mul_f32 v[152:153], v[70:71], v[172:173]
	v_pk_mul_f32 v[150:151], v[68:69], v[150:151]
	v_pk_mul_f32 v[172:173], v[66:67], v[172:173]
	v_pk_mul_f32 v[148:149], v[140:141], v[146:147]
	v_pk_mul_f32 v[146:147], v[138:139], v[152:153]
	v_pk_mul_f32 v[152:153], v[132:133], v[150:151]
	v_pk_mul_f32 v[150:151], v[130:131], v[172:173]
	s_and_b64 vcc, exec, s[8:9]
	v_cvt_pk_bf16_f32 v186, v146, v147
	v_cvt_pk_bf16_f32 v187, v148, v149
	v_cvt_pk_bf16_f32 v188, v150, v151
	v_cvt_pk_bf16_f32 v189, v152, v153
	s_nop 0
	v_readfirstlane_b32 s98, v174
	v_readfirstlane_b32 s99, v175
	ds_write_b128 v222, v[186:189]
	ds_read_b128 v[230:233], v223
	s_waitcnt lgkmcnt(0)
	s_nop 1
	global_store_dwordx4 v224, v[230:233], s[98:99] offset:64
	s_cbranch_vccnz .LBB0_189
	v_mov_b32_e32 v169, v157
	v_lshl_add_u64 v[170:171], v[170:171], 0, v[168:169]
	s_nop 0
	v_readfirstlane_b32 s100, v170
	v_readfirstlane_b32 s101, v171
	ds_write_b128 v225, v[146:149]
	ds_write_b128 v225, v[150:153] offset:16
	ds_read_b128 v[234:237], v226
	ds_read_b128 v[238:241], v226 offset:1024
	s_waitcnt lgkmcnt(0)
	global_store_dwordx4 v227, v[234:237], s[100:101] offset:128
	global_store_dwordx4 v228, v[238:241], s[100:101] offset:128

; __device__ __forceinline__ unsigned cvt_pk_bf16(float lo, float hi) { unsigned r; asm volatile("v_cvt_pk_bf16_f32 %0, %1, %2" : "=v"(r) : "v"(lo), "v"(hi)); return r; }
; __device__ __forceinline__ float quad_sum(float s) { s += __shfl_xor(s, 16); s += __shfl_xor(s, 32); return s; }
;     __device__ __forceinline__ void operator()(const f32x4 (&acc)[2][2][4][2], const Unit& u, int wr, int wc, int fr, int fq) const {
;     ...
;                 for (int m = 0; m < 4; ++m) { const int row = row0 + ai * HALF + m * 16; const int orow = prompt ? row : row - XM_PROMPT;
;                     float ss = 0.f;
; #pragma unroll
;                     for (int bj = 0; bj < 2; ++bj)
; #pragma unroll
;                         for (int n = 0; n < 2; ++n) { const f32x4 x = acc[ai][bj][m][n]; ss += (x[0] * x[0] + x[1] * x[1]) + (x[2] * x[2] + x[3] * x[3]); }
;                     ss = quad_sum(ss);
;                     const float rr = (sec < 4) ? post * (1.0f / sqrtf(ss * (1.0f / 64.0f) + 1e-6f)) : 1.0f;
; #pragma unroll
;                     for (int bj = 0; bj < 2; ++bj) { const f32x4 v0 = acc[ai][bj][m][0] * rr * gv[bj][0], v1 = acc[ai][bj][m][1] * rr * gv[bj][1];
;                         const int dcol = 64 * head + 32 * bj + 8 * fq;
;                         u32x4 w; w.x = cvt_pk_bf16(v0[0], v0[1]); w.y = cvt_pk_bf16(v0[2], v0[3]); w.z = cvt_pk_bf16(v1[0], v1[1]); w.w = cvt_pk_bf16(v1[2], v1[3]);
;                         *(u32x4*)(dst + (size_t)row * 512 + dcol) = w;
;                         if (fo) { float* op = fo + (size_t)orow * 512 + dcol; if (prompt) { __builtin_nontemporal_store(v0, (f32x4*)op); __builtin_nontemporal_store(v1, (f32x4*)(op + 4)); } else { *(f32x4*)op = v0; *(f32x4*)(op + 4) = v1; } } } }
.LBB0_191:
	v_add_u32_e32 v146, 0x80, v166
	s_waitcnt lgkmcnt(0)
	v_add_u32_e32 v147, 0xffffc080, v166
	v_cndmask_b32_e64 v148, v147, v146, s[10:11]
	v_ashrrev_i32_e32 v147, 31, v146
	v_lshlrev_b64 v[146:147], 10, v[146:147]
	v_ashrrev_i32_e32 v149, 31, v148
	v_lshl_add_u64 v[174:175], s[90:91], 0, v[146:147]
	v_lshlrev_b64 v[146:147], 11, v[148:149]
	v_lshl_add_u64 v[170:171], s[12:13], 0, v[146:147]
	v_pk_mul_f32 v[146:147], v[64:65], v[172:173] op_sel_hi:[1,0]
	v_pk_mul_f32 v[150:151], v[62:63], v[172:173] op_sel_hi:[1,0]
	v_pk_mul_f32 v[148:149], v[144:145], v[146:147]
	v_pk_mul_f32 v[146:147], v[142:143], v[150:151]
	v_pk_mul_f32 v[150:151], v[60:61], v[172:173] op_sel_hi:[1,0]
	v_pk_mul_f32 v[186:187], v[58:59], v[172:173] op_sel_hi:[1,0]
	v_pk_mul_f32 v[152:153], v[136:137], v[150:151]
	v_pk_mul_f32 v[150:151], v[134:135], v[186:187]
	v_lshl_add_u64 v[174:175], v[174:175], 0, v[156:157]
	s_and_b64 vcc, exec, s[8:9]
	v_cvt_pk_bf16_f32 v186, v146, v147
	v_cvt_pk_bf16_f32 v187, v148, v149
	v_cvt_pk_bf16_f32 v188, v150, v151
	v_cvt_pk_bf16_f32 v189, v152, v153
	s_nop 0
	v_readfirstlane_b32 s98, v174
	v_readfirstlane_b32 s99, v175
	ds_write_b128 v222, v[186:189]
	ds_read_b128 v[230:233], v223
	s_waitcnt lgkmcnt(0)
	s_nop 1
	global_store_dwordx4 v224, v[230:233], s[98:99]
	s_cbranch_vccnz .LBB0_193
	v_mov_b32_e32 v169, v157
	v_lshl_add_u64 v[186:187], v[170:171], 0, v[168:169]
	s_nop 0
	v_readfirstlane_b32 s100, v186
	v_readfirstlane_b32 s101, v187
	ds_write_b128 v225, v[146:149]
	ds_write_b128 v225, v[150:153] offset:16
	ds_read_b128 v[234:237], v226
	ds_read_b128 v[238:241], v226 offset:1024
	s_waitcnt lgkmcnt(0)
	global_store_dwordx4 v227, v[234:237], s[100:101]
	global_store_dwordx4 v228, v[238:241], s[100:101]
.LBB0_193:
	v_mov_b32_e32 v173, v172
	s_nop 0
	v_mov_b32_e32 v150, v172
	v_mov_b32_e32 v151, v172
	v_pk_mul_f32 v[146:147], v[56:57], v[150:151]
	v_pk_mul_f32 v[152:153], v[54:55], v[172:173]
	v_pk_mul_f32 v[150:151], v[52:53], v[150:151]
	v_pk_mul_f32 v[172:173], v[50:51], v[172:173]
	v_pk_mul_f32 v[148:149], v[140:141], v[146:147]
	v_pk_mul_f32 v[146:147], v[138:139], v[152:153]
	v_pk_mul_f32 v[152:153], v[132:133], v[150:151]
	v_pk_mul_f32 v[150:151], v[130:131], v[172:173]
	s_and_b64 vcc, exec, s[8:9]
	v_cvt_pk_bf16_f32 v186, v146, v147
	v_cvt_pk_bf16_f32 v187, v148, v149
	v_cvt_pk_bf16_f32 v188, v150, v151
	v_cvt_pk_bf16_f32 v189, v152, v153
	s_nop 0
	v_readfirstlane_b32 s98, v174
	v_readfirstlane_b32 s99, v175
	ds_write_b128 v222, v[186:189]
	ds_read_b128 v[230:233], v223
	s_waitcnt lgkmcnt(0)
	s_nop 1
	global_store_dwordx4 v224, v[230:233], s[98:99] offset:64
	s_cbranch_vccnz .LBB0_195
	v_mov_b32_e32 v169, v157
	v_lshl_add_u64 v[170:171], v[170:171], 0, v[168:169]
	s_nop 0
	v_readfirstlane_b32 s100, v170
	v_readfirstlane_b32 s101, v171
	ds_write_b128 v225, v[146:149]
	ds_write_b128 v225, v[150:153] offset:16
	ds_read_b128 v[234:237], v226
	ds_read_b128 v[238:241], v226 offset:1024
	s_waitcnt lgkmcnt(0)
	global_store_dwordx4 v227, v[234:237], s[100:101] offset:128
	global_store_dwordx4 v228, v[238:241], s[100:101] offset:128

; __device__ __forceinline__ unsigned cvt_pk_bf16(float lo, float hi) { unsigned r; asm volatile("v_cvt_pk_bf16_f32 %0, %1, %2" : "=v"(r) : "v"(lo), "v"(hi)); return r; }
; __device__ __forceinline__ float quad_sum(float s) { s += __shfl_xor(s, 16); s += __shfl_xor(s, 32); return s; }
;     __device__ __forceinline__ void operator()(const f32x4 (&acc)[2][2][4][2], const Unit& u, int wr, int wc, int fr, int fq) const {
;     ...
;                 for (int m = 0; m < 4; ++m) { const int row = row0 + ai * HALF + m * 16; const int orow = prompt ? row : row - XM_PROMPT;
;                     float ss = 0.f;
; #pragma unroll
;                     for (int bj = 0; bj < 2; ++bj)
; #pragma unroll
;                         for (int n = 0; n < 2; ++n) { const f32x4 x = acc[ai][bj][m][n]; ss += (x[0] * x[0] + x[1] * x[1]) + (x[2] * x[2] + x[3] * x[3]); }
;                     ss = quad_sum(ss);
;                     const float rr = (sec < 4) ? post * (1.0f / sqrtf(ss * (1.0f / 64.0f) + 1e-6f)) : 1.0f;
; #pragma unroll
;                     for (int bj = 0; bj < 2; ++bj) { const f32x4 v0 = acc[ai][bj][m][0] * rr * gv[bj][0], v1 = acc[ai][bj][m][1] * rr * gv[bj][1];
;                         const int dcol = 64 * head + 32 * bj + 8 * fq;
;                         u32x4 w; w.x = cvt_pk_bf16(v0[0], v0[1]); w.y = cvt_pk_bf16(v0[2], v0[3]); w.z = cvt_pk_bf16(v1[0], v1[1]); w.w = cvt_pk_bf16(v1[2], v1[3]);
;                         *(u32x4*)(dst + (size_t)row * 512 + dcol) = w;
;                         if (fo) { float* op = fo + (size_t)orow * 512 + dcol; if (prompt) { __builtin_nontemporal_store(v0, (f32x4*)op); __builtin_nontemporal_store(v1, (f32x4*)(op + 4)); } else { *(f32x4*)op = v0; *(f32x4*)(op + 4) = v1; } } } }
.LBB0_197:
	v_add_u32_e32 v146, 0x90, v166
	s_waitcnt lgkmcnt(0)
	v_add_u32_e32 v147, 0xffffc090, v166
	v_cndmask_b32_e64 v148, v147, v146, s[10:11]
	v_ashrrev_i32_e32 v147, 31, v146
	v_lshlrev_b64 v[146:147], 10, v[146:147]
	v_ashrrev_i32_e32 v149, 31, v148
	v_lshl_add_u64 v[174:175], s[90:91], 0, v[146:147]
	v_lshlrev_b64 v[146:147], 11, v[148:149]
	v_lshl_add_u64 v[170:171], s[12:13], 0, v[146:147]
	v_pk_mul_f32 v[146:147], v[48:49], v[172:173] op_sel_hi:[1,0]
	v_pk_mul_f32 v[150:151], v[46:47], v[172:173] op_sel_hi:[1,0]
	v_pk_mul_f32 v[148:149], v[144:145], v[146:147]
	v_pk_mul_f32 v[146:147], v[142:143], v[150:151]
	v_pk_mul_f32 v[150:151], v[44:45], v[172:173] op_sel_hi:[1,0]
	v_pk_mul_f32 v[186:187], v[42:43], v[172:173] op_sel_hi:[1,0]
	v_pk_mul_f32 v[152:153], v[136:137], v[150:151]
	v_pk_mul_f32 v[150:151], v[134:135], v[186:187]
	v_lshl_add_u64 v[174:175], v[174:175], 0, v[156:157]
	s_and_b64 vcc, exec, s[8:9]
	v_cvt_pk_bf16_f32 v186, v146, v147
	v_cvt_pk_bf16_f32 v187, v148, v149
	v_cvt_pk_bf16_f32 v188, v150, v151
	v_cvt_pk_bf16_f32 v189, v152, v153
	s_nop 0
	v_readfirstlane_b32 s98, v174
	v_readfirstlane_b32 s99, v175
	ds_write_b128 v222, v[186:189]
	ds_read_b128 v[230:233], v223
	s_waitcnt lgkmcnt(0)
	s_nop 1
	global_store_dwordx4 v224, v[230:233], s[98:99]
	s_cbranch_vccnz .LBB0_199
	v_mov_b32_e32 v169, v157
	v_lshl_add_u64 v[186:187], v[170:171], 0, v[168:169]
	s_nop 0
	v_readfirstlane_b32 s100, v186
	v_readfirstlane_b32 s101, v187
	ds_write_b128 v225, v[146:149]
	ds_write_b128 v225, v[150:153] offset:16
	ds_read_b128 v[234:237], v226
	ds_read_b128 v[238:241], v226 offset:1024
	s_waitcnt lgkmcnt(0)
	global_store_dwordx4 v227, v[234:237], s[100:101]
	global_store_dwordx4 v228, v[238:241], s[100:101]
.LBB0_199:
	v_mov_b32_e32 v173, v172
	s_nop 0
	v_mov_b32_e32 v150, v172
	v_mov_b32_e32 v151, v172
	v_pk_mul_f32 v[146:147], v[40:41], v[150:151]
	v_pk_mul_f32 v[152:153], v[38:39], v[172:173]
	v_pk_mul_f32 v[150:151], v[36:37], v[150:151]
	v_pk_mul_f32 v[172:173], v[34:35], v[172:173]
	v_pk_mul_f32 v[148:149], v[140:141], v[146:147]
	v_pk_mul_f32 v[146:147], v[138:139], v[152:153]
	v_pk_mul_f32 v[152:153], v[132:133], v[150:151]
	v_pk_mul_f32 v[150:151], v[130:131], v[172:173]
	s_and_b64 vcc, exec, s[8:9]
	v_cvt_pk_bf16_f32 v186, v146, v147
	v_cvt_pk_bf16_f32 v187, v148, v149
	v_cvt_pk_bf16_f32 v188, v150, v151
	v_cvt_pk_bf16_f32 v189, v152, v153
	s_nop 0
	v_readfirstlane_b32 s98, v174
	v_readfirstlane_b32 s99, v175
	ds_write_b128 v222, v[186:189]
	ds_read_b128 v[230:233], v223
	s_waitcnt lgkmcnt(0)
	s_nop 1
	global_store_dwordx4 v224, v[230:233], s[98:99] offset:64
	s_cbranch_vccnz .LBB0_201
	v_mov_b32_e32 v169, v157
	v_lshl_add_u64 v[170:171], v[170:171], 0, v[168:169]
	s_nop 0
	v_readfirstlane_b32 s100, v170
	v_readfirstlane_b32 s101, v171
	ds_write_b128 v225, v[146:149]
	ds_write_b128 v225, v[150:153] offset:16
	ds_read_b128 v[234:237], v226
	ds_read_b128 v[238:241], v226 offset:1024
	s_waitcnt lgkmcnt(0)
	global_store_dwordx4 v227, v[234:237], s[100:101] offset:128
	global_store_dwordx4 v228, v[238:241], s[100:101] offset:128

; __device__ __forceinline__ unsigned cvt_pk_bf16(float lo, float hi) { unsigned r; asm volatile("v_cvt_pk_bf16_f32 %0, %1, %2" : "=v"(r) : "v"(lo), "v"(hi)); return r; }
; __device__ __forceinline__ float quad_sum(float s) { s += __shfl_xor(s, 16); s += __shfl_xor(s, 32); return s; }
;     __device__ __forceinline__ void operator()(const f32x4 (&acc)[2][2][4][2], const Unit& u, int wr, int wc, int fr, int fq) const {
;     ...
;                 for (int m = 0; m < 4; ++m) { const int row = row0 + ai * HALF + m * 16; const int orow = prompt ? row : row - XM_PROMPT;
;                     float ss = 0.f;
; #pragma unroll
;                     for (int bj = 0; bj < 2; ++bj)
; #pragma unroll
;                         for (int n = 0; n < 2; ++n) { const f32x4 x = acc[ai][bj][m][n]; ss += (x[0] * x[0] + x[1] * x[1]) + (x[2] * x[2] + x[3] * x[3]); }
;                     ss = quad_sum(ss);
;                     const float rr = (sec < 4) ? post * (1.0f / sqrtf(ss * (1.0f / 64.0f) + 1e-6f)) : 1.0f;
; #pragma unroll
;                     for (int bj = 0; bj < 2; ++bj) { const f32x4 v0 = acc[ai][bj][m][0] * rr * gv[bj][0], v1 = acc[ai][bj][m][1] * rr * gv[bj][1];
;                         const int dcol = 64 * head + 32 * bj + 8 * fq;
;                         u32x4 w; w.x = cvt_pk_bf16(v0[0], v0[1]); w.y = cvt_pk_bf16(v0[2], v0[3]); w.z = cvt_pk_bf16(v1[0], v1[1]); w.w = cvt_pk_bf16(v1[2], v1[3]);
;                         *(u32x4*)(dst + (size_t)row * 512 + dcol) = w;
;                         if (fo) { float* op = fo + (size_t)orow * 512 + dcol; if (prompt) { __builtin_nontemporal_store(v0, (f32x4*)op); __builtin_nontemporal_store(v1, (f32x4*)(op + 4)); } else { *(f32x4*)op = v0; *(f32x4*)(op + 4) = v1; } } } }
.LBB0_203:
	v_add_u32_e32 v146, 0xa0, v166
	s_waitcnt lgkmcnt(0)
	v_add_u32_e32 v147, 0xffffc0a0, v166
	v_cndmask_b32_e64 v148, v147, v146, s[10:11]
	v_ashrrev_i32_e32 v147, 31, v146
	v_lshlrev_b64 v[146:147], 10, v[146:147]
	v_ashrrev_i32_e32 v149, 31, v148
	v_lshl_add_u64 v[174:175], s[90:91], 0, v[146:147]
	v_lshlrev_b64 v[146:147], 11, v[148:149]
	v_lshl_add_u64 v[170:171], s[12:13], 0, v[146:147]
	v_pk_mul_f32 v[146:147], v[32:33], v[172:173] op_sel_hi:[1,0]
	v_pk_mul_f32 v[150:151], v[30:31], v[172:173] op_sel_hi:[1,0]
	v_pk_mul_f32 v[148:149], v[144:145], v[146:147]
	v_pk_mul_f32 v[146:147], v[142:143], v[150:151]
	v_pk_mul_f32 v[150:151], v[28:29], v[172:173] op_sel_hi:[1,0]
	v_pk_mul_f32 v[186:187], v[26:27], v[172:173] op_sel_hi:[1,0]
	v_pk_mul_f32 v[152:153], v[136:137], v[150:151]
	v_pk_mul_f32 v[150:151], v[134:135], v[186:187]
	v_lshl_add_u64 v[174:175], v[174:175], 0, v[156:157]
	s_and_b64 vcc, exec, s[8:9]
	v_cvt_pk_bf16_f32 v186, v146, v147
	v_cvt_pk_bf16_f32 v187, v148, v149
	v_cvt_pk_bf16_f32 v188, v150, v151
	v_cvt_pk_bf16_f32 v189, v152, v153
	s_nop 0
	v_readfirstlane_b32 s98, v174
	v_readfirstlane_b32 s99, v175
	ds_write_b128 v222, v[186:189]
	ds_read_b128 v[230:233], v223
	s_waitcnt lgkmcnt(0)
	s_nop 1
	global_store_dwordx4 v224, v[230:233], s[98:99]
	s_cbranch_vccnz .LBB0_205
	v_mov_b32_e32 v169, v157
	v_lshl_add_u64 v[186:187], v[170:171], 0, v[168:169]
	s_nop 0
	v_readfirstlane_b32 s100, v186
	v_readfirstlane_b32 s101, v187
	ds_write_b128 v225, v[146:149]
	ds_write_b128 v225, v[150:153] offset:16
	ds_read_b128 v[234:237], v226
	ds_read_b128 v[238:241], v226 offset:1024
	s_waitcnt lgkmcnt(0)
	global_store_dwordx4 v227, v[234:237], s[100:101]
	global_store_dwordx4 v228, v[238:241], s[100:101]
.LBB0_205:
	v_mov_b32_e32 v173, v172
	s_nop 0
	v_mov_b32_e32 v150, v172
	v_mov_b32_e32 v151, v172
	v_pk_mul_f32 v[146:147], v[24:25], v[150:151]
	v_pk_mul_f32 v[152:153], v[22:23], v[172:173]
	v_pk_mul_f32 v[150:151], v[20:21], v[150:151]
	v_pk_mul_f32 v[172:173], v[18:19], v[172:173]
	v_pk_mul_f32 v[148:149], v[140:141], v[146:147]
	v_pk_mul_f32 v[146:147], v[138:139], v[152:153]
	v_pk_mul_f32 v[152:153], v[132:133], v[150:151]
	v_pk_mul_f32 v[150:151], v[130:131], v[172:173]
	s_and_b64 vcc, exec, s[8:9]
	v_cvt_pk_bf16_f32 v186, v146, v147
	v_cvt_pk_bf16_f32 v187, v148, v149
	v_cvt_pk_bf16_f32 v188, v150, v151
	v_cvt_pk_bf16_f32 v189, v152, v153
	s_nop 0
	v_readfirstlane_b32 s98, v174
	v_readfirstlane_b32 s99, v175
	ds_write_b128 v222, v[186:189]
	ds_read_b128 v[230:233], v223
	s_waitcnt lgkmcnt(0)
	s_nop 1
	global_store_dwordx4 v224, v[230:233], s[98:99] offset:64
	s_cbranch_vccnz .LBB0_207
	v_mov_b32_e32 v169, v157
	v_lshl_add_u64 v[170:171], v[170:171], 0, v[168:169]
	s_nop 0
	v_readfirstlane_b32 s100, v170
	v_readfirstlane_b32 s101, v171
	ds_write_b128 v225, v[146:149]
	ds_write_b128 v225, v[150:153] offset:16
	ds_read_b128 v[234:237], v226
	ds_read_b128 v[238:241], v226 offset:1024
	s_waitcnt lgkmcnt(0)
	global_store_dwordx4 v227, v[234:237], s[100:101] offset:128
	global_store_dwordx4 v228, v[238:241], s[100:101] offset:128

; __device__ __forceinline__ unsigned cvt_pk_bf16(float lo, float hi) { unsigned r; asm volatile("v_cvt_pk_bf16_f32 %0, %1, %2" : "=v"(r) : "v"(lo), "v"(hi)); return r; }
; __device__ __forceinline__ float quad_sum(float s) { s += __shfl_xor(s, 16); s += __shfl_xor(s, 32); return s; }
;     __device__ __forceinline__ void operator()(const f32x4 (&acc)[2][2][4][2], const Unit& u, int wr, int wc, int fr, int fq) const {
;     ...
;                 for (int m = 0; m < 4; ++m) { const int row = row0 + ai * HALF + m * 16; const int orow = prompt ? row : row - XM_PROMPT;
;                     float ss = 0.f;
; #pragma unroll
;                     for (int bj = 0; bj < 2; ++bj)
; #pragma unroll
;                         for (int n = 0; n < 2; ++n) { const f32x4 x = acc[ai][bj][m][n]; ss += (x[0] * x[0] + x[1] * x[1]) + (x[2] * x[2] + x[3] * x[3]); }
;                     ss = quad_sum(ss);
;                     const float rr = (sec < 4) ? post * (1.0f / sqrtf(ss * (1.0f / 64.0f) + 1e-6f)) : 1.0f;
; #pragma unroll
;                     for (int bj = 0; bj < 2; ++bj) { const f32x4 v0 = acc[ai][bj][m][0] * rr * gv[bj][0], v1 = acc[ai][bj][m][1] * rr * gv[bj][1];
;                         const int dcol = 64 * head + 32 * bj + 8 * fq;
;                         u32x4 w; w.x = cvt_pk_bf16(v0[0], v0[1]); w.y = cvt_pk_bf16(v0[2], v0[3]); w.z = cvt_pk_bf16(v1[0], v1[1]); w.w = cvt_pk_bf16(v1[2], v1[3]);
;                         *(u32x4*)(dst + (size_t)row * 512 + dcol) = w;
;                         if (fo) { float* op = fo + (size_t)orow * 512 + dcol; if (prompt) { __builtin_nontemporal_store(v0, (f32x4*)op); __builtin_nontemporal_store(v1, (f32x4*)(op + 4)); } else { *(f32x4*)op = v0; *(f32x4*)(op + 4) = v1; } } } }
.LBB0_209:
	v_add_u32_e32 v146, 0xb0, v166
	s_waitcnt lgkmcnt(0)
	v_add_u32_e32 v147, 0xffffc0b0, v166
	v_cndmask_b32_e64 v150, v147, v146, s[10:11]
	v_ashrrev_i32_e32 v147, 31, v146
	v_lshlrev_b64 v[146:147], 10, v[146:147]
	v_ashrrev_i32_e32 v151, 31, v150
	v_lshl_add_u64 v[152:153], s[90:91], 0, v[146:147]
	v_lshlrev_b64 v[146:147], 11, v[150:151]
	v_pk_mul_f32 v[150:151], v[16:17], v[148:149] op_sel_hi:[1,0]
	v_pk_mul_f32 v[170:171], v[14:15], v[148:149] op_sel_hi:[1,0]
	v_pk_mul_f32 v[144:145], v[144:145], v[150:151]
	v_pk_mul_f32 v[142:143], v[142:143], v[170:171]
	v_pk_mul_f32 v[150:151], v[12:13], v[148:149] op_sel_hi:[1,0]
	v_pk_mul_f32 v[170:171], v[10:11], v[148:149] op_sel_hi:[1,0]
	v_lshl_add_u64 v[146:147], s[12:13], 0, v[146:147]
	v_pk_mul_f32 v[136:137], v[136:137], v[150:151]
	v_pk_mul_f32 v[134:135], v[134:135], v[170:171]
	v_lshl_add_u64 v[150:151], v[152:153], 0, v[156:157]
	s_and_b64 vcc, exec, s[8:9]
	v_cvt_pk_bf16_f32 v170, v142, v143
	v_cvt_pk_bf16_f32 v171, v144, v145
	v_cvt_pk_bf16_f32 v172, v134, v135
	v_cvt_pk_bf16_f32 v173, v136, v137
	s_nop 0
	v_readfirstlane_b32 s98, v150
	v_readfirstlane_b32 s99, v151
	ds_write_b128 v222, v[170:173]
	ds_read_b128 v[230:233], v223
	s_waitcnt lgkmcnt(0)
	s_nop 1
	global_store_dwordx4 v224, v[230:233], s[98:99]
	s_cbranch_vccnz .LBB0_211
	v_mov_b32_e32 v169, v157
	v_lshl_add_u64 v[152:153], v[146:147], 0, v[168:169]
	s_nop 0
	v_readfirstlane_b32 s100, v152
	v_readfirstlane_b32 s101, v153
	ds_write_b128 v225, v[142:145]
	ds_write_b128 v225, v[134:137] offset:16
	ds_read_b128 v[234:237], v226
	ds_read_b128 v[238:241], v226 offset:1024
	s_waitcnt lgkmcnt(0)
	global_store_dwordx4 v227, v[234:237], s[100:101]
	global_store_dwordx4 v228, v[238:241], s[100:101]
.LBB0_211:
	v_mov_b32_e32 v149, v148
	v_mov_b32_e32 v142, v148
	v_mov_b32_e32 v143, v148
	v_pk_mul_f32 v[134:135], v[8:9], v[142:143]
	v_pk_mul_f32 v[144:145], v[6:7], v[148:149]
	v_pk_mul_f32 v[136:137], v[140:141], v[134:135]
	v_pk_mul_f32 v[134:135], v[138:139], v[144:145]
	v_pk_mul_f32 v[138:139], v[4:5], v[142:143]
	v_pk_mul_f32 v[140:141], v[2:3], v[148:149]
	v_pk_mul_f32 v[132:133], v[132:133], v[138:139]
	v_pk_mul_f32 v[130:131], v[130:131], v[140:141]
	s_and_b64 vcc, exec, s[8:9]
	v_cvt_pk_bf16_f32 v138, v134, v135
	v_cvt_pk_bf16_f32 v139, v136, v137
	v_cvt_pk_bf16_f32 v140, v130, v131
	v_cvt_pk_bf16_f32 v141, v132, v133
	s_nop 0
	v_readfirstlane_b32 s98, v150
	v_readfirstlane_b32 s99, v151
	ds_write_b128 v222, v[138:141]
	ds_read_b128 v[230:233], v223
	s_waitcnt lgkmcnt(0)
	s_nop 1
	global_store_dwordx4 v224, v[230:233], s[98:99] offset:64
	s_cbranch_vccnz .LBB0_213
	v_mov_b32_e32 v169, v157
	v_lshl_add_u64 v[138:139], v[146:147], 0, v[168:169]
	s_nop 0
	v_readfirstlane_b32 s100, v138
	v_readfirstlane_b32 s101, v139
	ds_write_b128 v225, v[134:137]
	ds_write_b128 v225, v[130:133] offset:16
	ds_read_b128 v[234:237], v226
	ds_read_b128 v[238:241], v226 offset:1024
	s_waitcnt lgkmcnt(0)
	global_store_dwordx4 v227, v[234:237], s[100:101] offset:128
	global_store_dwordx4 v228, v[238:241], s[100:101] offset:128

; __device__ __forceinline__ unsigned cvt_pk_bf16(float lo, float hi) { unsigned r; asm volatile("v_cvt_pk_bf16_f32 %0, %1, %2" : "=v"(r) : "v"(lo), "v"(hi)); return r; }
; __device__ __forceinline__ float gelu_t(float x) { const float u = 0.7978845608028654f * (x + 0.044715f * x * x * x); return x * fast_rcp(1.0f + fast_exp2(-2.8853900817779268f * u)); }
;     __device__ __forceinline__ void operator()(const f32x4 (&acc)[2][2][4][2], const Unit& u, int wr, int wc, int fr, int fq) const {
;     ...
;             for (int ai = 0; ai < 2; ++ai)
; #pragma unroll
;                 for (int m = 0; m < 4; ++m) { const int row = row0 + ai * HALF + m * 16; bf16_t* rowp = dst + (size_t)row * 512 + col0; float s1 = 0.f, s2 = 0.f;
; #pragma unroll
;                     for (int bj = 0; bj < 2; ++bj) { f32x4 v0 = acc[ai][bj][m][0], v1 = acc[ai][bj][m][1];
; #pragma unroll
;                         for (int j = 0; j < 4; ++j) { v0[j] = gelu_t(v0[j]); v1[j] = gelu_t(v1[j]); }
;                         s1 += (v0[0] + v0[1]) + (v0[2] + v0[3]) + (v1[0] + v1[1]) + (v1[2] + v1[3]);
;                         s2 += (v0[0] * v0[0] + v0[1] * v0[1]) + (v0[2] * v0[2] + v0[3] * v0[3]) + (v1[0] * v1[0] + v1[1] * v1[1]) + (v1[2] * v1[2] + v1[3] * v1[3]);
;                         u32x4 w; w.x = cvt_pk_bf16(v0[0], v0[1]); w.y = cvt_pk_bf16(v0[2], v0[3]); w.z = cvt_pk_bf16(v1[0], v1[1]); w.w = cvt_pk_bf16(v1[2], v1[3]);
;                         *(u32x4*)(rowp + bj * HALF) = w; }
.LBB0_214:
	v_mul_f32_e32 v134, 0x3d372713, v126
	v_mul_f32_e32 v134, v126, v134
	v_fma_f32 v134, v126, v134, v126
	v_mul_f32_e32 v134, 0x3f4c422a, v134
	v_mul_f32_e32 v134, 0xc038aa3b, v134
	v_exp_f32_e32 v134, v134
	s_cmp_lt_i32 s88, 2
	s_cselect_b64 s[6:7], -1, 0
	s_and_b64 vcc, s[6:7], exec
	v_add_f32_e32 v134, 1.0, v134
	v_rcp_f32_e32 v134, v134
	s_mov_b32 s6, 0x4200000
	s_cselect_b32 s6, s6, 0x5300000
	v_readlane_b32 s8, v251, 4
	v_mul_f32_e32 v126, v126, v134
	v_mul_f32_e32 v134, 0x3d372713, v122
	v_mul_f32_e32 v134, v122, v134
	v_fma_f32 v134, v122, v134, v122
	v_mul_f32_e32 v134, 0x3f4c422a, v134
	v_mul_f32_e32 v134, 0xc038aa3b, v134
	v_exp_f32_e32 v134, v134
	v_readlane_b32 s9, v251, 5
	s_add_u32 s6, s8, s6
	s_addc_u32 s7, s9, 0
	v_add_f32_e32 v134, 1.0, v134
	v_rcp_f32_e32 v134, v134
	s_lshl_b32 s8, s88, 8
	s_and_b32 s8, s8, 0x100
	v_or_b32_e32 v130, s8, v176
	v_mul_f32_e32 v122, v122, v134
	v_mul_f32_e32 v134, 0x3d372713, v127
	v_mul_f32_e32 v134, v127, v134
	v_fma_f32 v134, v127, v134, v127
	v_mul_f32_e32 v134, 0x3f4c422a, v134
	v_mul_f32_e32 v134, 0xc038aa3b, v134
	v_exp_f32_e32 v134, v134
	v_lshlrev_b32_e32 v156, 1, v130
	v_ashrrev_i32_e32 v167, 31, v166
	v_lshl_add_u64 v[130:131], s[6:7], 0, v[156:157]
	v_add_f32_e32 v134, 1.0, v134
	v_rcp_f32_e32 v134, v134
	v_lshlrev_b64 v[132:133], 10, v[166:167]
	v_lshl_add_u64 v[132:133], v[130:131], 0, v[132:133]
	s_cmp_gt_i32 s88, 1
	v_mul_f32_e32 v127, v127, v134
	v_mul_f32_e32 v134, 0x3d372713, v123
	v_mul_f32_e32 v134, v123, v134
	v_fma_f32 v134, v123, v134, v123
	v_mul_f32_e32 v134, 0x3f4c422a, v134
	v_mul_f32_e32 v134, 0xc038aa3b, v134
	v_exp_f32_e32 v134, v134
	s_cselect_b64 s[8:9], -1, 0
	v_add_f32_e32 v134, 1.0, v134
	v_rcp_f32_e32 v134, v134
	s_nop 0
	v_mul_f32_e32 v123, v123, v134
	v_mul_f32_e32 v134, 0x3d372713, v128
	v_mul_f32_e32 v134, v128, v134
	v_fma_f32 v134, v128, v134, v128
	v_mul_f32_e32 v134, 0x3f4c422a, v134
	v_mul_f32_e32 v134, 0xc038aa3b, v134
	v_exp_f32_e32 v134, v134
	s_nop 0
	v_add_f32_e32 v134, 1.0, v134
	v_rcp_f32_e32 v134, v134
	s_nop 0
	v_mul_f32_e32 v128, v128, v134
	v_mul_f32_e32 v134, 0x3d372713, v124
	v_mul_f32_e32 v134, v124, v134
	v_fma_f32 v134, v124, v134, v124
	v_mul_f32_e32 v134, 0x3f4c422a, v134
	v_mul_f32_e32 v134, 0xc038aa3b, v134
	v_exp_f32_e32 v134, v134
	s_nop 0
	v_add_f32_e32 v134, 1.0, v134
	v_rcp_f32_e32 v134, v134
	s_nop 0
	v_mul_f32_e32 v124, v124, v134
	v_mul_f32_e32 v134, 0x3d372713, v129
	v_mul_f32_e32 v134, v129, v134
	v_fma_f32 v134, v129, v134, v129
	v_mul_f32_e32 v134, 0x3f4c422a, v134
	v_mul_f32_e32 v134, 0xc038aa3b, v134
	v_exp_f32_e32 v134, v134
	s_nop 0
	v_add_f32_e32 v134, 1.0, v134
	v_rcp_f32_e32 v134, v134
	s_nop 0
	v_mul_f32_e32 v129, v129, v134
	v_mul_f32_e32 v134, 0x3d372713, v125
	v_mul_f32_e32 v134, v125, v134
	v_fma_f32 v134, v125, v134, v125
	v_mul_f32_e32 v134, 0x3f4c422a, v134
	v_mul_f32_e32 v134, 0xc038aa3b, v134
	v_exp_f32_e32 v134, v134
	s_nop 0
	v_add_f32_e32 v134, 1.0, v134
	v_rcp_f32_e32 v134, v134
	s_nop 0
	v_mul_f32_e32 v125, v125, v134
	v_cvt_pk_bf16_f32 v134, v126, v127
	v_cvt_pk_bf16_f32 v135, v128, v129
	v_cvt_pk_bf16_f32 v136, v122, v123
	v_cvt_pk_bf16_f32 v137, v124, v125
	s_nop 0
	v_readfirstlane_b32 s98, v132
	v_readfirstlane_b32 s99, v133
	ds_write_b128 v222, v[134:137]
	ds_read_b128 v[230:233], v223
	s_waitcnt lgkmcnt(0)
	s_nop 1
	global_store_dwordx4 v224, v[230:233], s[98:99]
	s_nop 1
	v_mul_f32_e32 v134, 0x3d372713, v118
	v_mul_f32_e32 v134, v118, v134
	v_fma_f32 v134, v118, v134, v118
	v_mul_f32_e32 v134, 0x3f4c422a, v134
	v_mul_f32_e32 v134, 0xc038aa3b, v134
	v_exp_f32_e32 v134, v134
	s_nop 0
	v_add_f32_e32 v134, 1.0, v134
	v_rcp_f32_e32 v134, v134
	s_nop 0
	v_mul_f32_e32 v118, v118, v134
	v_mul_f32_e32 v134, 0x3d372713, v114
	v_mul_f32_e32 v134, v114, v134
	v_fma_f32 v134, v114, v134, v114
	v_mul_f32_e32 v134, 0x3f4c422a, v134
	v_mul_f32_e32 v134, 0xc038aa3b, v134
	v_exp_f32_e32 v134, v134
	s_nop 0
	v_add_f32_e32 v134, 1.0, v134
	v_rcp_f32_e32 v134, v134
	s_nop 0
	v_mul_f32_e32 v114, v114, v134
	v_mul_f32_e32 v134, 0x3d372713, v119
	v_mul_f32_e32 v134, v119, v134
	v_fma_f32 v134, v119, v134, v119
	v_mul_f32_e32 v134, 0x3f4c422a, v134
	v_mul_f32_e32 v134, 0xc038aa3b, v134
	v_exp_f32_e32 v134, v134
	s_nop 0
	v_add_f32_e32 v134, 1.0, v134
	v_rcp_f32_e32 v134, v134
	s_nop 0
	v_mul_f32_e32 v119, v119, v134
	v_mul_f32_e32 v134, 0x3d372713, v115
	v_mul_f32_e32 v134, v115, v134
	v_fma_f32 v134, v115, v134, v115
	v_mul_f32_e32 v134, 0x3f4c422a, v134
	v_mul_f32_e32 v134, 0xc038aa3b, v134
	v_exp_f32_e32 v134, v134
	s_nop 0
	v_add_f32_e32 v134, 1.0, v134
	v_rcp_f32_e32 v134, v134
	s_nop 0
	v_mul_f32_e32 v115, v115, v134
	v_mul_f32_e32 v134, 0x3d372713, v120
	v_mul_f32_e32 v134, v120, v134
	v_fma_f32 v134, v120, v134, v120
	v_mul_f32_e32 v134, 0x3f4c422a, v134
	v_mul_f32_e32 v134, 0xc038aa3b, v134
	v_exp_f32_e32 v134, v134
	s_nop 0
	v_add_f32_e32 v134, 1.0, v134
	v_rcp_f32_e32 v134, v134
	s_nop 0
	v_mul_f32_e32 v120, v120, v134
	v_mul_f32_e32 v134, 0x3d372713, v116
	v_mul_f32_e32 v134, v116, v134
	v_fma_f32 v134, v116, v134, v116
	v_mul_f32_e32 v134, 0x3f4c422a, v134
	v_mul_f32_e32 v134, 0xc038aa3b, v134
	v_exp_f32_e32 v134, v134
	s_nop 0
	v_add_f32_e32 v134, 1.0, v134
	v_rcp_f32_e32 v134, v134
	s_nop 0
	v_mul_f32_e32 v116, v116, v134
	v_mul_f32_e32 v134, 0x3d372713, v121
	v_mul_f32_e32 v134, v121, v134
	v_fma_f32 v134, v121, v134, v121
	v_mul_f32_e32 v134, 0x3f4c422a, v134
	v_mul_f32_e32 v134, 0xc038aa3b, v134
	v_exp_f32_e32 v134, v134
	s_nop 0
	v_add_f32_e32 v134, 1.0, v134
	v_rcp_f32_e32 v134, v134
	s_nop 0
	v_mul_f32_e32 v121, v121, v134
	v_mul_f32_e32 v134, 0x3d372713, v117
	v_mul_f32_e32 v134, v117, v134
	v_fma_f32 v134, v117, v134, v117
	v_mul_f32_e32 v134, 0x3f4c422a, v134
	v_mul_f32_e32 v134, 0xc038aa3b, v134
	v_exp_f32_e32 v134, v134
	s_nop 0
	v_add_f32_e32 v134, 1.0, v134
	v_rcp_f32_e32 v134, v134
	s_nop 0
	v_mul_f32_e32 v117, v117, v134
	v_cvt_pk_bf16_f32 v134, v118, v119
	v_cvt_pk_bf16_f32 v135, v120, v121
	v_cvt_pk_bf16_f32 v136, v114, v115
	v_cvt_pk_bf16_f32 v137, v116, v117
	s_nop 0
	v_readfirstlane_b32 s98, v132
	v_readfirstlane_b32 s99, v133
	ds_write_b128 v222, v[134:137]
	ds_read_b128 v[230:233], v223
	s_waitcnt lgkmcnt(0)
	s_nop 1
	global_store_dwordx4 v224, v[230:233], s[98:99] offset:256
	s_cbranch_vccnz .LBB0_218
; __device__ __forceinline__ unsigned cvt_pk_bf16(float lo, float hi) { unsigned r; asm volatile("v_cvt_pk_bf16_f32 %0, %1, %2" : "=v"(r) : "v"(lo), "v"(hi)); return r; }
; __device__ __forceinline__ float quad_sum(float s) { s += __shfl_xor(s, 16); s += __shfl_xor(s, 32); return s; }
;     __device__ __forceinline__ void operator()(const f32x4 (&acc)[2][2][4][2], const Unit& u, int wr, int wc, int fr, int fq) const {
;     ...
;                         s1 += (v0[0] + v0[1]) + (v0[2] + v0[3]) + (v1[0] + v1[1]) + (v1[2] + v1[3]);
;                         s2 += (v0[0] * v0[0] + v0[1] * v0[1]) + (v0[2] * v0[2] + v0[3] * v0[3]) + (v1[0] * v1[0] + v1[1] * v1[1]) + (v1[2] * v1[2] + v1[3] * v1[3]);
;                         u32x4 w; w.x = cvt_pk_bf16(v0[0], v0[1]); w.y = cvt_pk_bf16(v0[2], v0[3]); w.z = cvt_pk_bf16(v1[0], v1[1]); w.w = cvt_pk_bf16(v1[2], v1[3]);
;                         *(u32x4*)(rowp + bj * HALF) = w; }
;                     if (stats) { s1 = quad_sum(s1); s2 = quad_sum(s2); if (fq == 0) { atomicAdd(st1 + row, s1); atomicAdd(st2 + row, s2); } } }
	s_nop 0
	v_mul_f32_e32 v134, v127, v127
	v_mul_f32_e32 v135, v129, v129
	v_mul_f32_e32 v133, v123, v123
	v_fmac_f32_e32 v134, v126, v126
	v_fmac_f32_e32 v135, v128, v128
	v_mul_f32_e32 v132, v125, v125
	v_fmac_f32_e32 v133, v122, v122
	v_add_f32_e32 v134, v134, v135
	v_fmac_f32_e32 v132, v124, v124
	v_add_f32_e32 v133, v134, v133
	v_add_f32_e32 v132, v132, v133
	v_mul_f32_e32 v133, v117, v117
	v_mul_f32_e32 v134, v115, v115
	v_fmac_f32_e32 v133, v116, v116
	v_fmac_f32_e32 v134, v114, v114
	v_add_f32_e32 v116, v116, v117
	v_add_f32_e32 v114, v114, v115
	v_add_f32_e32 v115, v118, v119
	v_add_f32_e32 v117, v120, v121
	v_add_f32_e32 v115, v115, v117
	v_add_f32_e32 v124, v124, v125
	v_add_f32_e32 v122, v122, v123
	v_add_f32_e32 v123, v126, v127
	v_add_f32_e32 v125, v128, v129
	v_add_f32_e32 v114, v115, v114
	v_add_f32_e32 v123, v123, v125
	v_add_f32_e32 v114, v116, v114
	v_and_b32_e32 v116, 64, v183
	v_add_f32_e32 v122, v123, v122
	v_xor_b32_e32 v115, 16, v183
	v_add_u32_e32 v116, 64, v116
	v_mul_f32_e32 v135, v119, v119
	v_mul_f32_e32 v136, v121, v121
	v_add_f32_e32 v122, v124, v122
	v_cmp_lt_i32_e32 vcc, v115, v116
	v_fmac_f32_e32 v135, v118, v118
	v_fmac_f32_e32 v136, v120, v120
	v_add_f32_e32 v122, 0, v122
	v_cndmask_b32_e32 v115, v183, v115, vcc
	v_add_f32_e32 v114, v122, v114
	v_lshlrev_b32_e32 v115, 2, v115
	v_add_f32_e32 v118, v135, v136
	ds_bpermute_b32 v117, v115, v114
	v_add_f32_e32 v118, v118, v134
	v_add_f32_e32 v118, v133, v118
	v_add_f32_e32 v118, v132, v118
	ds_bpermute_b32 v119, v115, v118
	s_waitcnt lgkmcnt(0)
	v_add_f32_e32 v114, v114, v117
	v_xor_b32_e32 v117, 32, v183
	v_cmp_lt_i32_e32 vcc, v117, v116
	v_add_f32_e32 v116, v118, v119
	s_nop 0
	v_cndmask_b32_e32 v115, v183, v117, vcc
	v_lshlrev_b32_e32 v117, 2, v115
	ds_bpermute_b32 v115, v117, v114
	ds_bpermute_b32 v117, v117, v116
	s_and_saveexec_b64 s[6:7], s[2:3]
	s_cbranch_execz .LBB0_217
	v_lshlrev_b64 v[118:119], 2, v[166:167]
	v_lshl_add_u64 v[120:121], s[78:79], 0, v[118:119]
	v_lshl_add_u64 v[118:119], s[76:77], 0, v[118:119]
	s_waitcnt lgkmcnt(0)
	v_add_f32_e32 v114, v114, v115
	v_add_f32_e32 v116, v116, v117
	global_atomic_add_f32 v[118:119], v114, off
	global_atomic_add_f32 v[120:121], v116, off

; __device__ __forceinline__ unsigned cvt_pk_bf16(float lo, float hi) { unsigned r; asm volatile("v_cvt_pk_bf16_f32 %0, %1, %2" : "=v"(r) : "v"(lo), "v"(hi)); return r; }
; __device__ __forceinline__ float gelu_t(float x) { const float u = 0.7978845608028654f * (x + 0.044715f * x * x * x); return x * fast_rcp(1.0f + fast_exp2(-2.8853900817779268f * u)); }
;     __device__ __forceinline__ void operator()(const f32x4 (&acc)[2][2][4][2], const Unit& u, int wr, int wc, int fr, int fq) const {
;     ...
;                 for (int m = 0; m < 4; ++m) { const int row = row0 + ai * HALF + m * 16; bf16_t* rowp = dst + (size_t)row * 512 + col0; float s1 = 0.f, s2 = 0.f;
; #pragma unroll
;                     for (int bj = 0; bj < 2; ++bj) { f32x4 v0 = acc[ai][bj][m][0], v1 = acc[ai][bj][m][1];
; #pragma unroll
;                         for (int j = 0; j < 4; ++j) { v0[j] = gelu_t(v0[j]); v1[j] = gelu_t(v1[j]); }
;                         s1 += (v0[0] + v0[1]) + (v0[2] + v0[3]) + (v1[0] + v1[1]) + (v1[2] + v1[3]);
;                         s2 += (v0[0] * v0[0] + v0[1] * v0[1]) + (v0[2] * v0[2] + v0[3] * v0[3]) + (v1[0] * v1[0] + v1[1] * v1[1]) + (v1[2] * v1[2] + v1[3] * v1[3]);
;                         u32x4 w; w.x = cvt_pk_bf16(v0[0], v0[1]); w.y = cvt_pk_bf16(v0[2], v0[3]); w.z = cvt_pk_bf16(v1[0], v1[1]); w.w = cvt_pk_bf16(v1[2], v1[3]);
;                         *(u32x4*)(rowp + bj * HALF) = w; }
.LBB0_218:
	v_mul_f32_e32 v118, 0x3d372713, v110
	v_mul_f32_e32 v118, v110, v118
	v_fma_f32 v118, v110, v118, v110
	v_mul_f32_e32 v118, 0x3f4c422a, v118
	v_mul_f32_e32 v118, 0xc038aa3b, v118
	v_exp_f32_e32 v118, v118
	v_or_b32_e32 v114, 16, v166
	s_waitcnt lgkmcnt(0)
	v_ashrrev_i32_e32 v115, 31, v114
	v_lshlrev_b64 v[116:117], 10, v[114:115]
	v_add_f32_e32 v118, 1.0, v118
	v_rcp_f32_e32 v118, v118
	v_lshl_add_u64 v[116:117], v[130:131], 0, v[116:117]
	s_andn2_b64 vcc, exec, s[8:9]
	v_mul_f32_e32 v110, v110, v118
	v_mul_f32_e32 v118, 0x3d372713, v106
	v_mul_f32_e32 v118, v106, v118
	v_fma_f32 v118, v106, v118, v106
	v_mul_f32_e32 v118, 0x3f4c422a, v118
	v_mul_f32_e32 v118, 0xc038aa3b, v118
	v_exp_f32_e32 v118, v118
	s_nop 0
	v_add_f32_e32 v118, 1.0, v118
	v_rcp_f32_e32 v118, v118
	s_nop 0
	v_mul_f32_e32 v106, v106, v118
	v_mul_f32_e32 v118, 0x3d372713, v111
	v_mul_f32_e32 v118, v111, v118
	v_fma_f32 v118, v111, v118, v111
	v_mul_f32_e32 v118, 0x3f4c422a, v118
	v_mul_f32_e32 v118, 0xc038aa3b, v118
	v_exp_f32_e32 v118, v118
	s_nop 0
	v_add_f32_e32 v118, 1.0, v118
	v_rcp_f32_e32 v118, v118
	s_nop 0
	v_mul_f32_e32 v111, v111, v118
	v_mul_f32_e32 v118, 0x3d372713, v107
	v_mul_f32_e32 v118, v107, v118
	v_fma_f32 v118, v107, v118, v107
	v_mul_f32_e32 v118, 0x3f4c422a, v118
	v_mul_f32_e32 v118, 0xc038aa3b, v118
	v_exp_f32_e32 v118, v118
	s_nop 0
	v_add_f32_e32 v118, 1.0, v118
	v_rcp_f32_e32 v118, v118
	s_nop 0
	v_mul_f32_e32 v107, v107, v118
	v_mul_f32_e32 v118, 0x3d372713, v112
	v_mul_f32_e32 v118, v112, v118
	v_fma_f32 v118, v112, v118, v112
	v_mul_f32_e32 v118, 0x3f4c422a, v118
	v_mul_f32_e32 v118, 0xc038aa3b, v118
	v_exp_f32_e32 v118, v118
	s_nop 0
	v_add_f32_e32 v118, 1.0, v118
	v_rcp_f32_e32 v118, v118
	s_nop 0
	v_mul_f32_e32 v112, v112, v118
	v_mul_f32_e32 v118, 0x3d372713, v108
	v_mul_f32_e32 v118, v108, v118
	v_fma_f32 v118, v108, v118, v108
	v_mul_f32_e32 v118, 0x3f4c422a, v118
	v_mul_f32_e32 v118, 0xc038aa3b, v118
	v_exp_f32_e32 v118, v118
	s_nop 0
	v_add_f32_e32 v118, 1.0, v118
	v_rcp_f32_e32 v118, v118
	s_nop 0
	v_mul_f32_e32 v108, v108, v118
	v_mul_f32_e32 v118, 0x3d372713, v113
	v_mul_f32_e32 v118, v113, v118
	v_fma_f32 v118, v113, v118, v113
	v_mul_f32_e32 v118, 0x3f4c422a, v118
	v_mul_f32_e32 v118, 0xc038aa3b, v118
	v_exp_f32_e32 v118, v118
	s_nop 0
	v_add_f32_e32 v118, 1.0, v118
	v_rcp_f32_e32 v118, v118
	s_nop 0
	v_mul_f32_e32 v113, v113, v118
	v_mul_f32_e32 v118, 0x3d372713, v109
	v_mul_f32_e32 v118, v109, v118
	v_fma_f32 v118, v109, v118, v109
	v_mul_f32_e32 v118, 0x3f4c422a, v118
	v_mul_f32_e32 v118, 0xc038aa3b, v118
	v_exp_f32_e32 v118, v118
	s_nop 0
	v_add_f32_e32 v118, 1.0, v118
	v_rcp_f32_e32 v118, v118
	s_nop 0
	v_mul_f32_e32 v109, v109, v118
	v_cvt_pk_bf16_f32 v118, v110, v111
	v_cvt_pk_bf16_f32 v119, v112, v113
	v_cvt_pk_bf16_f32 v120, v106, v107
	v_cvt_pk_bf16_f32 v121, v108, v109
	s_nop 0
	v_readfirstlane_b32 s98, v116
	v_readfirstlane_b32 s99, v117
	ds_write_b128 v222, v[118:121]
	ds_read_b128 v[230:233], v223
	s_waitcnt lgkmcnt(0)
	s_nop 1
	global_store_dwordx4 v224, v[230:233], s[98:99]
	s_nop 1
	v_mul_f32_e32 v118, 0x3d372713, v102
	v_mul_f32_e32 v118, v102, v118
	v_fma_f32 v118, v102, v118, v102
	v_mul_f32_e32 v118, 0x3f4c422a, v118
	v_mul_f32_e32 v118, 0xc038aa3b, v118
	v_exp_f32_e32 v118, v118
	s_nop 0
	v_add_f32_e32 v118, 1.0, v118
	v_rcp_f32_e32 v118, v118
	s_nop 0
	v_mul_f32_e32 v102, v102, v118
	v_mul_f32_e32 v118, 0x3d372713, v98
	v_mul_f32_e32 v118, v98, v118
	v_fma_f32 v118, v98, v118, v98
	v_mul_f32_e32 v118, 0x3f4c422a, v118
	v_mul_f32_e32 v118, 0xc038aa3b, v118
	v_exp_f32_e32 v118, v118
	s_nop 0
	v_add_f32_e32 v118, 1.0, v118
	v_rcp_f32_e32 v118, v118
	s_nop 0
	v_mul_f32_e32 v98, v98, v118
	v_mul_f32_e32 v118, 0x3d372713, v103
	v_mul_f32_e32 v118, v103, v118
	v_fma_f32 v118, v103, v118, v103
	v_mul_f32_e32 v118, 0x3f4c422a, v118
	v_mul_f32_e32 v118, 0xc038aa3b, v118
	v_exp_f32_e32 v118, v118
	s_nop 0
	v_add_f32_e32 v118, 1.0, v118
	v_rcp_f32_e32 v118, v118
	s_nop 0
	v_mul_f32_e32 v103, v103, v118
	v_mul_f32_e32 v118, 0x3d372713, v99
	v_mul_f32_e32 v118, v99, v118
	v_fma_f32 v118, v99, v118, v99
	v_mul_f32_e32 v118, 0x3f4c422a, v118
	v_mul_f32_e32 v118, 0xc038aa3b, v118
	v_exp_f32_e32 v118, v118
	s_nop 0
	v_add_f32_e32 v118, 1.0, v118
	v_rcp_f32_e32 v118, v118
	s_nop 0
	v_mul_f32_e32 v99, v99, v118
	v_mul_f32_e32 v118, 0x3d372713, v104
	v_mul_f32_e32 v118, v104, v118
	v_fma_f32 v118, v104, v118, v104
	v_mul_f32_e32 v118, 0x3f4c422a, v118
	v_mul_f32_e32 v118, 0xc038aa3b, v118
	v_exp_f32_e32 v118, v118
	s_nop 0
	v_add_f32_e32 v118, 1.0, v118
	v_rcp_f32_e32 v118, v118
	s_nop 0
	v_mul_f32_e32 v104, v104, v118
	v_mul_f32_e32 v118, 0x3d372713, v100
	v_mul_f32_e32 v118, v100, v118
	v_fma_f32 v118, v100, v118, v100
	v_mul_f32_e32 v118, 0x3f4c422a, v118
	v_mul_f32_e32 v118, 0xc038aa3b, v118
	v_exp_f32_e32 v118, v118
	s_nop 0
	v_add_f32_e32 v118, 1.0, v118
	v_rcp_f32_e32 v118, v118
	s_nop 0
	v_mul_f32_e32 v100, v100, v118
	v_mul_f32_e32 v118, 0x3d372713, v105
	v_mul_f32_e32 v118, v105, v118
	v_fma_f32 v118, v105, v118, v105
	v_mul_f32_e32 v118, 0x3f4c422a, v118
	v_mul_f32_e32 v118, 0xc038aa3b, v118
	v_exp_f32_e32 v118, v118
	s_nop 0
	v_add_f32_e32 v118, 1.0, v118
	v_rcp_f32_e32 v118, v118
	s_nop 0
	v_mul_f32_e32 v105, v105, v118
	v_mul_f32_e32 v118, 0x3d372713, v101
	v_mul_f32_e32 v118, v101, v118
	v_fma_f32 v118, v101, v118, v101
	v_mul_f32_e32 v118, 0x3f4c422a, v118
	v_mul_f32_e32 v118, 0xc038aa3b, v118
	v_exp_f32_e32 v118, v118
	s_nop 0
	v_add_f32_e32 v118, 1.0, v118
	v_rcp_f32_e32 v118, v118
	s_nop 0
	v_mul_f32_e32 v101, v101, v118
	v_cvt_pk_bf16_f32 v118, v102, v103
	v_cvt_pk_bf16_f32 v119, v104, v105
	v_cvt_pk_bf16_f32 v120, v98, v99
	v_cvt_pk_bf16_f32 v121, v100, v101
	s_nop 0
	v_readfirstlane_b32 s98, v116
	v_readfirstlane_b32 s99, v117
	ds_write_b128 v222, v[118:121]
	ds_read_b128 v[230:233], v223
	s_waitcnt lgkmcnt(0)
	s_nop 1
	global_store_dwordx4 v224, v[230:233], s[98:99] offset:256
	v_cndmask_b32_e64 v116, 0, 1, s[8:9]
	v_cmp_ne_u32_e64 s[6:7], 1, v116
	s_cbranch_vccnz .LBB0_222
; __device__ __forceinline__ unsigned cvt_pk_bf16(float lo, float hi) { unsigned r; asm volatile("v_cvt_pk_bf16_f32 %0, %1, %2" : "=v"(r) : "v"(lo), "v"(hi)); return r; }
; __device__ __forceinline__ float quad_sum(float s) { s += __shfl_xor(s, 16); s += __shfl_xor(s, 32); return s; }
;     __device__ __forceinline__ void operator()(const f32x4 (&acc)[2][2][4][2], const Unit& u, int wr, int wc, int fr, int fq) const {
;     ...
;                         s1 += (v0[0] + v0[1]) + (v0[2] + v0[3]) + (v1[0] + v1[1]) + (v1[2] + v1[3]);
;                         s2 += (v0[0] * v0[0] + v0[1] * v0[1]) + (v0[2] * v0[2] + v0[3] * v0[3]) + (v1[0] * v1[0] + v1[1] * v1[1]) + (v1[2] * v1[2] + v1[3] * v1[3]);
;                         u32x4 w; w.x = cvt_pk_bf16(v0[0], v0[1]); w.y = cvt_pk_bf16(v0[2], v0[3]); w.z = cvt_pk_bf16(v1[0], v1[1]); w.w = cvt_pk_bf16(v1[2], v1[3]);
;                         *(u32x4*)(rowp + bj * HALF) = w; }
;                     if (stats) { s1 = quad_sum(s1); s2 = quad_sum(s2); if (fq == 0) { atomicAdd(st1 + row, s1); atomicAdd(st2 + row, s2); } } }
	v_mul_f32_e32 v118, v111, v111
	v_mul_f32_e32 v119, v113, v113
	v_mul_f32_e32 v117, v107, v107
	v_fmac_f32_e32 v118, v110, v110
	v_fmac_f32_e32 v119, v112, v112
	v_mul_f32_e32 v116, v109, v109
	v_fmac_f32_e32 v117, v106, v106
	v_add_f32_e32 v118, v118, v119
	v_fmac_f32_e32 v116, v108, v108
	v_add_f32_e32 v117, v118, v117
	v_add_f32_e32 v116, v116, v117
	v_mul_f32_e32 v117, v101, v101
	v_mul_f32_e32 v118, v99, v99
	v_fmac_f32_e32 v117, v100, v100
	v_fmac_f32_e32 v118, v98, v98
	v_add_f32_e32 v100, v100, v101
	v_add_f32_e32 v98, v98, v99
	v_add_f32_e32 v99, v102, v103
	v_add_f32_e32 v101, v104, v105
	v_add_f32_e32 v99, v99, v101
	v_add_f32_e32 v108, v108, v109
	v_add_f32_e32 v106, v106, v107
	v_add_f32_e32 v107, v110, v111
	v_add_f32_e32 v109, v112, v113
	v_add_f32_e32 v98, v99, v98
	v_add_f32_e32 v107, v107, v109
	v_add_f32_e32 v98, v100, v98
	v_and_b32_e32 v100, 64, v183
	v_add_f32_e32 v106, v107, v106
	v_xor_b32_e32 v99, 16, v183
	v_add_u32_e32 v100, 64, v100
	v_mul_f32_e32 v119, v103, v103
	v_mul_f32_e32 v120, v105, v105
	v_add_f32_e32 v106, v108, v106
	v_cmp_lt_i32_e32 vcc, v99, v100
	v_fmac_f32_e32 v119, v102, v102
	v_fmac_f32_e32 v120, v104, v104
	v_add_f32_e32 v106, 0, v106
	v_cndmask_b32_e32 v99, v183, v99, vcc
	v_add_f32_e32 v98, v106, v98
	v_lshlrev_b32_e32 v99, 2, v99
	v_add_f32_e32 v102, v119, v120
	ds_bpermute_b32 v101, v99, v98
	v_add_f32_e32 v102, v102, v118
	v_add_f32_e32 v102, v117, v102
	v_add_f32_e32 v102, v116, v102
	ds_bpermute_b32 v103, v99, v102
	s_waitcnt lgkmcnt(0)
	v_add_f32_e32 v98, v98, v101
	v_xor_b32_e32 v101, 32, v183
	v_cmp_lt_i32_e32 vcc, v101, v100
	v_add_f32_e32 v100, v102, v103
	s_nop 0
	v_cndmask_b32_e32 v99, v183, v101, vcc
	v_lshlrev_b32_e32 v101, 2, v99
	ds_bpermute_b32 v99, v101, v98
	ds_bpermute_b32 v101, v101, v100
	s_and_saveexec_b64 s[8:9], s[2:3]
	s_cbranch_execz .LBB0_221
	v_lshlrev_b64 v[102:103], 2, v[114:115]
	v_lshl_add_u64 v[104:105], s[78:79], 0, v[102:103]
	v_lshl_add_u64 v[102:103], s[76:77], 0, v[102:103]
	s_waitcnt lgkmcnt(0)
	v_add_f32_e32 v98, v98, v99
	v_add_f32_e32 v100, v100, v101
	global_atomic_add_f32 v[102:103], v98, off
	global_atomic_add_f32 v[104:105], v100, off

; __device__ __forceinline__ unsigned cvt_pk_bf16(float lo, float hi) { unsigned r; asm volatile("v_cvt_pk_bf16_f32 %0, %1, %2" : "=v"(r) : "v"(lo), "v"(hi)); return r; }
; __device__ __forceinline__ float gelu_t(float x) { const float u = 0.7978845608028654f * (x + 0.044715f * x * x * x); return x * fast_rcp(1.0f + fast_exp2(-2.8853900817779268f * u)); }
;     __device__ __forceinline__ void operator()(const f32x4 (&acc)[2][2][4][2], const Unit& u, int wr, int wc, int fr, int fq) const {
;     ...
;                 for (int m = 0; m < 4; ++m) { const int row = row0 + ai * HALF + m * 16; bf16_t* rowp = dst + (size_t)row * 512 + col0; float s1 = 0.f, s2 = 0.f;
; #pragma unroll
;                     for (int bj = 0; bj < 2; ++bj) { f32x4 v0 = acc[ai][bj][m][0], v1 = acc[ai][bj][m][1];
; #pragma unroll
;                         for (int j = 0; j < 4; ++j) { v0[j] = gelu_t(v0[j]); v1[j] = gelu_t(v1[j]); }
;                         s1 += (v0[0] + v0[1]) + (v0[2] + v0[3]) + (v1[0] + v1[1]) + (v1[2] + v1[3]);
;                         s2 += (v0[0] * v0[0] + v0[1] * v0[1]) + (v0[2] * v0[2] + v0[3] * v0[3]) + (v1[0] * v1[0] + v1[1] * v1[1]) + (v1[2] * v1[2] + v1[3] * v1[3]);
;                         u32x4 w; w.x = cvt_pk_bf16(v0[0], v0[1]); w.y = cvt_pk_bf16(v0[2], v0[3]); w.z = cvt_pk_bf16(v1[0], v1[1]); w.w = cvt_pk_bf16(v1[2], v1[3]);
;                         *(u32x4*)(rowp + bj * HALF) = w; }
.LBB0_222:
	v_mul_f32_e32 v102, 0x3d372713, v94
	v_mul_f32_e32 v102, v94, v102
	v_fma_f32 v102, v94, v102, v94
	v_mul_f32_e32 v102, 0x3f4c422a, v102
	v_mul_f32_e32 v102, 0xc038aa3b, v102
	v_exp_f32_e32 v102, v102
	v_or_b32_e32 v98, 32, v166
	s_waitcnt lgkmcnt(0)
	v_ashrrev_i32_e32 v99, 31, v98
	v_lshlrev_b64 v[100:101], 10, v[98:99]
	v_add_f32_e32 v102, 1.0, v102
	v_rcp_f32_e32 v102, v102
	v_lshl_add_u64 v[100:101], v[130:131], 0, v[100:101]
	s_and_b64 vcc, exec, s[6:7]
	v_mul_f32_e32 v94, v94, v102
	v_mul_f32_e32 v102, 0x3d372713, v90
	v_mul_f32_e32 v102, v90, v102
	v_fma_f32 v102, v90, v102, v90
	v_mul_f32_e32 v102, 0x3f4c422a, v102
	v_mul_f32_e32 v102, 0xc038aa3b, v102
	v_exp_f32_e32 v102, v102
	s_nop 0
	v_add_f32_e32 v102, 1.0, v102
	v_rcp_f32_e32 v102, v102
	s_nop 0
	v_mul_f32_e32 v90, v90, v102
	v_mul_f32_e32 v102, 0x3d372713, v95
	v_mul_f32_e32 v102, v95, v102
	v_fma_f32 v102, v95, v102, v95
	v_mul_f32_e32 v102, 0x3f4c422a, v102
	v_mul_f32_e32 v102, 0xc038aa3b, v102
	v_exp_f32_e32 v102, v102
	s_nop 0
	v_add_f32_e32 v102, 1.0, v102
	v_rcp_f32_e32 v102, v102
	s_nop 0
	v_mul_f32_e32 v95, v95, v102
	v_mul_f32_e32 v102, 0x3d372713, v91
	v_mul_f32_e32 v102, v91, v102
	v_fma_f32 v102, v91, v102, v91
	v_mul_f32_e32 v102, 0x3f4c422a, v102
	v_mul_f32_e32 v102, 0xc038aa3b, v102
	v_exp_f32_e32 v102, v102
	s_nop 0
	v_add_f32_e32 v102, 1.0, v102
	v_rcp_f32_e32 v102, v102
	s_nop 0
	v_mul_f32_e32 v91, v91, v102
	v_mul_f32_e32 v102, 0x3d372713, v96
	v_mul_f32_e32 v102, v96, v102
	v_fma_f32 v102, v96, v102, v96
	v_mul_f32_e32 v102, 0x3f4c422a, v102
	v_mul_f32_e32 v102, 0xc038aa3b, v102
	v_exp_f32_e32 v102, v102
	s_nop 0
	v_add_f32_e32 v102, 1.0, v102
	v_rcp_f32_e32 v102, v102
	s_nop 0
	v_mul_f32_e32 v96, v96, v102
	v_mul_f32_e32 v102, 0x3d372713, v92
	v_mul_f32_e32 v102, v92, v102
	v_fma_f32 v102, v92, v102, v92
	v_mul_f32_e32 v102, 0x3f4c422a, v102
	v_mul_f32_e32 v102, 0xc038aa3b, v102
	v_exp_f32_e32 v102, v102
	s_nop 0
	v_add_f32_e32 v102, 1.0, v102
	v_rcp_f32_e32 v102, v102
	s_nop 0
	v_mul_f32_e32 v92, v92, v102
	v_mul_f32_e32 v102, 0x3d372713, v97
	v_mul_f32_e32 v102, v97, v102
	v_fma_f32 v102, v97, v102, v97
	v_mul_f32_e32 v102, 0x3f4c422a, v102
	v_mul_f32_e32 v102, 0xc038aa3b, v102
	v_exp_f32_e32 v102, v102
	s_nop 0
	v_add_f32_e32 v102, 1.0, v102
	v_rcp_f32_e32 v102, v102
	s_nop 0
	v_mul_f32_e32 v97, v97, v102
	v_mul_f32_e32 v102, 0x3d372713, v93
	v_mul_f32_e32 v102, v93, v102
	v_fma_f32 v102, v93, v102, v93
	v_mul_f32_e32 v102, 0x3f4c422a, v102
	v_mul_f32_e32 v102, 0xc038aa3b, v102
	v_exp_f32_e32 v102, v102
	s_nop 0
	v_add_f32_e32 v102, 1.0, v102
	v_rcp_f32_e32 v102, v102
	s_nop 0
	v_mul_f32_e32 v93, v93, v102
	v_cvt_pk_bf16_f32 v102, v94, v95
	v_cvt_pk_bf16_f32 v103, v96, v97
	v_cvt_pk_bf16_f32 v104, v90, v91
	v_cvt_pk_bf16_f32 v105, v92, v93
	s_nop 0
	v_readfirstlane_b32 s98, v100
	v_readfirstlane_b32 s99, v101
	ds_write_b128 v222, v[102:105]
	ds_read_b128 v[230:233], v223
	s_waitcnt lgkmcnt(0)
	s_nop 1
	global_store_dwordx4 v224, v[230:233], s[98:99]
	s_nop 1
	v_mul_f32_e32 v102, 0x3d372713, v86
	v_mul_f32_e32 v102, v86, v102
	v_fma_f32 v102, v86, v102, v86
	v_mul_f32_e32 v102, 0x3f4c422a, v102
	v_mul_f32_e32 v102, 0xc038aa3b, v102
	v_exp_f32_e32 v102, v102
	s_nop 0
	v_add_f32_e32 v102, 1.0, v102
	v_rcp_f32_e32 v102, v102
	s_nop 0
	v_mul_f32_e32 v86, v86, v102
	v_mul_f32_e32 v102, 0x3d372713, v82
	v_mul_f32_e32 v102, v82, v102
	v_fma_f32 v102, v82, v102, v82
	v_mul_f32_e32 v102, 0x3f4c422a, v102
	v_mul_f32_e32 v102, 0xc038aa3b, v102
	v_exp_f32_e32 v102, v102
	s_nop 0
	v_add_f32_e32 v102, 1.0, v102
	v_rcp_f32_e32 v102, v102
	s_nop 0
	v_mul_f32_e32 v82, v82, v102
	v_mul_f32_e32 v102, 0x3d372713, v87
	v_mul_f32_e32 v102, v87, v102
	v_fma_f32 v102, v87, v102, v87
	v_mul_f32_e32 v102, 0x3f4c422a, v102
	v_mul_f32_e32 v102, 0xc038aa3b, v102
	v_exp_f32_e32 v102, v102
	s_nop 0
	v_add_f32_e32 v102, 1.0, v102
	v_rcp_f32_e32 v102, v102
	s_nop 0
	v_mul_f32_e32 v87, v87, v102
	v_mul_f32_e32 v102, 0x3d372713, v83
	v_mul_f32_e32 v102, v83, v102
	v_fma_f32 v102, v83, v102, v83
	v_mul_f32_e32 v102, 0x3f4c422a, v102
	v_mul_f32_e32 v102, 0xc038aa3b, v102
	v_exp_f32_e32 v102, v102
	s_nop 0
	v_add_f32_e32 v102, 1.0, v102
	v_rcp_f32_e32 v102, v102
	s_nop 0
	v_mul_f32_e32 v83, v83, v102
	v_mul_f32_e32 v102, 0x3d372713, v88
	v_mul_f32_e32 v102, v88, v102
	v_fma_f32 v102, v88, v102, v88
	v_mul_f32_e32 v102, 0x3f4c422a, v102
	v_mul_f32_e32 v102, 0xc038aa3b, v102
	v_exp_f32_e32 v102, v102
	s_nop 0
	v_add_f32_e32 v102, 1.0, v102
	v_rcp_f32_e32 v102, v102
	s_nop 0
	v_mul_f32_e32 v88, v88, v102
	v_mul_f32_e32 v102, 0x3d372713, v84
	v_mul_f32_e32 v102, v84, v102
	v_fma_f32 v102, v84, v102, v84
	v_mul_f32_e32 v102, 0x3f4c422a, v102
	v_mul_f32_e32 v102, 0xc038aa3b, v102
	v_exp_f32_e32 v102, v102
	s_nop 0
	v_add_f32_e32 v102, 1.0, v102
	v_rcp_f32_e32 v102, v102
	s_nop 0
	v_mul_f32_e32 v84, v84, v102
	v_mul_f32_e32 v102, 0x3d372713, v89
	v_mul_f32_e32 v102, v89, v102
	v_fma_f32 v102, v89, v102, v89
	v_mul_f32_e32 v102, 0x3f4c422a, v102
	v_mul_f32_e32 v102, 0xc038aa3b, v102
	v_exp_f32_e32 v102, v102
	s_nop 0
	v_add_f32_e32 v102, 1.0, v102
	v_rcp_f32_e32 v102, v102
	s_nop 0
	v_mul_f32_e32 v89, v89, v102
	v_mul_f32_e32 v102, 0x3d372713, v85
	v_mul_f32_e32 v102, v85, v102
	v_fma_f32 v102, v85, v102, v85
	v_mul_f32_e32 v102, 0x3f4c422a, v102
	v_mul_f32_e32 v102, 0xc038aa3b, v102
	v_exp_f32_e32 v102, v102
	s_nop 0
	v_add_f32_e32 v102, 1.0, v102
	v_rcp_f32_e32 v102, v102
	s_nop 0
	v_mul_f32_e32 v85, v85, v102
	v_cvt_pk_bf16_f32 v102, v86, v87
	v_cvt_pk_bf16_f32 v103, v88, v89
	v_cvt_pk_bf16_f32 v104, v82, v83
	v_cvt_pk_bf16_f32 v105, v84, v85
	s_nop 0
	v_readfirstlane_b32 s98, v100
	v_readfirstlane_b32 s99, v101
	ds_write_b128 v222, v[102:105]
	ds_read_b128 v[230:233], v223
	s_waitcnt lgkmcnt(0)
	s_nop 1
	global_store_dwordx4 v224, v[230:233], s[98:99] offset:256
	s_cbranch_vccnz .LBB0_226
; __device__ __forceinline__ unsigned cvt_pk_bf16(float lo, float hi) { unsigned r; asm volatile("v_cvt_pk_bf16_f32 %0, %1, %2" : "=v"(r) : "v"(lo), "v"(hi)); return r; }
; __device__ __forceinline__ float quad_sum(float s) { s += __shfl_xor(s, 16); s += __shfl_xor(s, 32); return s; }
;     __device__ __forceinline__ void operator()(const f32x4 (&acc)[2][2][4][2], const Unit& u, int wr, int wc, int fr, int fq) const {
;     ...
;                         s1 += (v0[0] + v0[1]) + (v0[2] + v0[3]) + (v1[0] + v1[1]) + (v1[2] + v1[3]);
;                         s2 += (v0[0] * v0[0] + v0[1] * v0[1]) + (v0[2] * v0[2] + v0[3] * v0[3]) + (v1[0] * v1[0] + v1[1] * v1[1]) + (v1[2] * v1[2] + v1[3] * v1[3]);
;                         u32x4 w; w.x = cvt_pk_bf16(v0[0], v0[1]); w.y = cvt_pk_bf16(v0[2], v0[3]); w.z = cvt_pk_bf16(v1[0], v1[1]); w.w = cvt_pk_bf16(v1[2], v1[3]);
;                         *(u32x4*)(rowp + bj * HALF) = w; }
;                     if (stats) { s1 = quad_sum(s1); s2 = quad_sum(s2); if (fq == 0) { atomicAdd(st1 + row, s1); atomicAdd(st2 + row, s2); } } }
	s_nop 0
	v_mul_f32_e32 v102, v95, v95
	v_mul_f32_e32 v103, v97, v97
	v_mul_f32_e32 v101, v91, v91
	v_fmac_f32_e32 v102, v94, v94
	v_fmac_f32_e32 v103, v96, v96
	v_mul_f32_e32 v100, v93, v93
	v_fmac_f32_e32 v101, v90, v90
	v_add_f32_e32 v102, v102, v103
	v_fmac_f32_e32 v100, v92, v92
	v_add_f32_e32 v101, v102, v101
	v_add_f32_e32 v100, v100, v101
	v_mul_f32_e32 v101, v85, v85
	v_mul_f32_e32 v102, v83, v83
	v_fmac_f32_e32 v101, v84, v84
	v_fmac_f32_e32 v102, v82, v82
	v_add_f32_e32 v84, v84, v85
	v_add_f32_e32 v82, v82, v83
	v_add_f32_e32 v83, v86, v87
	v_add_f32_e32 v85, v88, v89
	v_add_f32_e32 v83, v83, v85
	v_add_f32_e32 v92, v92, v93
	v_add_f32_e32 v90, v90, v91
	v_add_f32_e32 v91, v94, v95
	v_add_f32_e32 v93, v96, v97
	v_add_f32_e32 v82, v83, v82
	v_add_f32_e32 v91, v91, v93
	v_add_f32_e32 v82, v84, v82
	v_and_b32_e32 v84, 64, v183
	v_add_f32_e32 v90, v91, v90
	v_xor_b32_e32 v83, 16, v183
	v_add_u32_e32 v84, 64, v84
	v_mul_f32_e32 v103, v87, v87
	v_mul_f32_e32 v104, v89, v89
	v_add_f32_e32 v90, v92, v90
	v_cmp_lt_i32_e32 vcc, v83, v84
	v_fmac_f32_e32 v103, v86, v86
	v_fmac_f32_e32 v104, v88, v88
	v_add_f32_e32 v90, 0, v90
	v_cndmask_b32_e32 v83, v183, v83, vcc
	v_add_f32_e32 v82, v90, v82
	v_lshlrev_b32_e32 v83, 2, v83
	v_add_f32_e32 v86, v103, v104
	ds_bpermute_b32 v85, v83, v82
	v_add_f32_e32 v86, v86, v102
	v_add_f32_e32 v86, v101, v86
	v_add_f32_e32 v86, v100, v86
	ds_bpermute_b32 v87, v83, v86
	s_waitcnt lgkmcnt(0)
	v_add_f32_e32 v82, v82, v85
	v_xor_b32_e32 v85, 32, v183
	v_cmp_lt_i32_e32 vcc, v85, v84
	v_add_f32_e32 v84, v86, v87
	s_nop 0
	v_cndmask_b32_e32 v83, v183, v85, vcc
	v_lshlrev_b32_e32 v85, 2, v83
	ds_bpermute_b32 v83, v85, v82
	ds_bpermute_b32 v85, v85, v84
	s_and_saveexec_b64 s[8:9], s[2:3]
	s_cbranch_execz .LBB0_225
	v_lshlrev_b64 v[86:87], 2, v[98:99]
	v_lshl_add_u64 v[88:89], s[78:79], 0, v[86:87]
	v_lshl_add_u64 v[86:87], s[76:77], 0, v[86:87]
	s_waitcnt lgkmcnt(0)
	v_add_f32_e32 v82, v82, v83
	v_add_f32_e32 v84, v84, v85
	global_atomic_add_f32 v[86:87], v82, off
	global_atomic_add_f32 v[88:89], v84, off

; __device__ __forceinline__ unsigned cvt_pk_bf16(float lo, float hi) { unsigned r; asm volatile("v_cvt_pk_bf16_f32 %0, %1, %2" : "=v"(r) : "v"(lo), "v"(hi)); return r; }
; __device__ __forceinline__ float gelu_t(float x) { const float u = 0.7978845608028654f * (x + 0.044715f * x * x * x); return x * fast_rcp(1.0f + fast_exp2(-2.8853900817779268f * u)); }
;     __device__ __forceinline__ void operator()(const f32x4 (&acc)[2][2][4][2], const Unit& u, int wr, int wc, int fr, int fq) const {
;     ...
;                 for (int m = 0; m < 4; ++m) { const int row = row0 + ai * HALF + m * 16; bf16_t* rowp = dst + (size_t)row * 512 + col0; float s1 = 0.f, s2 = 0.f;
; #pragma unroll
;                     for (int bj = 0; bj < 2; ++bj) { f32x4 v0 = acc[ai][bj][m][0], v1 = acc[ai][bj][m][1];
; #pragma unroll
;                         for (int j = 0; j < 4; ++j) { v0[j] = gelu_t(v0[j]); v1[j] = gelu_t(v1[j]); }
;                         s1 += (v0[0] + v0[1]) + (v0[2] + v0[3]) + (v1[0] + v1[1]) + (v1[2] + v1[3]);
;                         s2 += (v0[0] * v0[0] + v0[1] * v0[1]) + (v0[2] * v0[2] + v0[3] * v0[3]) + (v1[0] * v1[0] + v1[1] * v1[1]) + (v1[2] * v1[2] + v1[3] * v1[3]);
;                         u32x4 w; w.x = cvt_pk_bf16(v0[0], v0[1]); w.y = cvt_pk_bf16(v0[2], v0[3]); w.z = cvt_pk_bf16(v1[0], v1[1]); w.w = cvt_pk_bf16(v1[2], v1[3]);
;                         *(u32x4*)(rowp + bj * HALF) = w; }
.LBB0_226:
	v_mul_f32_e32 v86, 0x3d372713, v78
	v_mul_f32_e32 v86, v78, v86
	v_fma_f32 v86, v78, v86, v78
	v_mul_f32_e32 v86, 0x3f4c422a, v86
	v_mul_f32_e32 v86, 0xc038aa3b, v86
	v_exp_f32_e32 v86, v86
	v_or_b32_e32 v82, 48, v166
	s_waitcnt lgkmcnt(0)
	v_ashrrev_i32_e32 v83, 31, v82
	v_lshlrev_b64 v[84:85], 10, v[82:83]
	v_add_f32_e32 v86, 1.0, v86
	v_rcp_f32_e32 v86, v86
	v_lshl_add_u64 v[84:85], v[130:131], 0, v[84:85]
	s_and_b64 vcc, exec, s[6:7]
	v_mul_f32_e32 v78, v78, v86
	v_mul_f32_e32 v86, 0x3d372713, v74
	v_mul_f32_e32 v86, v74, v86
	v_fma_f32 v86, v74, v86, v74
	v_mul_f32_e32 v86, 0x3f4c422a, v86
	v_mul_f32_e32 v86, 0xc038aa3b, v86
	v_exp_f32_e32 v86, v86
	s_nop 0
	v_add_f32_e32 v86, 1.0, v86
	v_rcp_f32_e32 v86, v86
	s_nop 0
	v_mul_f32_e32 v74, v74, v86
	v_mul_f32_e32 v86, 0x3d372713, v79
	v_mul_f32_e32 v86, v79, v86
	v_fma_f32 v86, v79, v86, v79
	v_mul_f32_e32 v86, 0x3f4c422a, v86
	v_mul_f32_e32 v86, 0xc038aa3b, v86
	v_exp_f32_e32 v86, v86
	s_nop 0
	v_add_f32_e32 v86, 1.0, v86
	v_rcp_f32_e32 v86, v86
	s_nop 0
	v_mul_f32_e32 v79, v79, v86
	v_mul_f32_e32 v86, 0x3d372713, v75
	v_mul_f32_e32 v86, v75, v86
	v_fma_f32 v86, v75, v86, v75
	v_mul_f32_e32 v86, 0x3f4c422a, v86
	v_mul_f32_e32 v86, 0xc038aa3b, v86
	v_exp_f32_e32 v86, v86
	s_nop 0
	v_add_f32_e32 v86, 1.0, v86
	v_rcp_f32_e32 v86, v86
	s_nop 0
	v_mul_f32_e32 v75, v75, v86
	v_mul_f32_e32 v86, 0x3d372713, v80
	v_mul_f32_e32 v86, v80, v86
	v_fma_f32 v86, v80, v86, v80
	v_mul_f32_e32 v86, 0x3f4c422a, v86
	v_mul_f32_e32 v86, 0xc038aa3b, v86
	v_exp_f32_e32 v86, v86
	s_nop 0
	v_add_f32_e32 v86, 1.0, v86
	v_rcp_f32_e32 v86, v86
	s_nop 0
	v_mul_f32_e32 v80, v80, v86
	v_mul_f32_e32 v86, 0x3d372713, v76
	v_mul_f32_e32 v86, v76, v86
	v_fma_f32 v86, v76, v86, v76
	v_mul_f32_e32 v86, 0x3f4c422a, v86
	v_mul_f32_e32 v86, 0xc038aa3b, v86
	v_exp_f32_e32 v86, v86
	s_nop 0
	v_add_f32_e32 v86, 1.0, v86
	v_rcp_f32_e32 v86, v86
	s_nop 0
	v_mul_f32_e32 v76, v76, v86
	v_mul_f32_e32 v86, 0x3d372713, v81
	v_mul_f32_e32 v86, v81, v86
	v_fma_f32 v86, v81, v86, v81
	v_mul_f32_e32 v86, 0x3f4c422a, v86
	v_mul_f32_e32 v86, 0xc038aa3b, v86
	v_exp_f32_e32 v86, v86
	s_nop 0
	v_add_f32_e32 v86, 1.0, v86
	v_rcp_f32_e32 v86, v86
	s_nop 0
	v_mul_f32_e32 v81, v81, v86
	v_mul_f32_e32 v86, 0x3d372713, v77
	v_mul_f32_e32 v86, v77, v86
	v_fma_f32 v86, v77, v86, v77
	v_mul_f32_e32 v86, 0x3f4c422a, v86
	v_mul_f32_e32 v86, 0xc038aa3b, v86
	v_exp_f32_e32 v86, v86
	s_nop 0
	v_add_f32_e32 v86, 1.0, v86
	v_rcp_f32_e32 v86, v86
	s_nop 0
	v_mul_f32_e32 v77, v77, v86
	v_cvt_pk_bf16_f32 v86, v78, v79
	v_cvt_pk_bf16_f32 v87, v80, v81
	v_cvt_pk_bf16_f32 v88, v74, v75
	v_cvt_pk_bf16_f32 v89, v76, v77
	s_nop 0
	v_readfirstlane_b32 s98, v84
	v_readfirstlane_b32 s99, v85
	ds_write_b128 v222, v[86:89]
	ds_read_b128 v[230:233], v223
	s_waitcnt lgkmcnt(0)
	s_nop 1
	global_store_dwordx4 v224, v[230:233], s[98:99]
	s_nop 1
	v_mul_f32_e32 v86, 0x3d372713, v70
	v_mul_f32_e32 v86, v70, v86
	v_fma_f32 v86, v70, v86, v70
	v_mul_f32_e32 v86, 0x3f4c422a, v86
	v_mul_f32_e32 v86, 0xc038aa3b, v86
	v_exp_f32_e32 v86, v86
	s_nop 0
	v_add_f32_e32 v86, 1.0, v86
	v_rcp_f32_e32 v86, v86
	s_nop 0
	v_mul_f32_e32 v70, v70, v86
	v_mul_f32_e32 v86, 0x3d372713, v66
	v_mul_f32_e32 v86, v66, v86
	v_fma_f32 v86, v66, v86, v66
	v_mul_f32_e32 v86, 0x3f4c422a, v86
	v_mul_f32_e32 v86, 0xc038aa3b, v86
	v_exp_f32_e32 v86, v86
	s_nop 0
	v_add_f32_e32 v86, 1.0, v86
	v_rcp_f32_e32 v86, v86
	s_nop 0
	v_mul_f32_e32 v66, v66, v86
	v_mul_f32_e32 v86, 0x3d372713, v71
	v_mul_f32_e32 v86, v71, v86
	v_fma_f32 v86, v71, v86, v71
	v_mul_f32_e32 v86, 0x3f4c422a, v86
	v_mul_f32_e32 v86, 0xc038aa3b, v86
	v_exp_f32_e32 v86, v86
	s_nop 0
	v_add_f32_e32 v86, 1.0, v86
	v_rcp_f32_e32 v86, v86
	s_nop 0
	v_mul_f32_e32 v71, v71, v86
	v_mul_f32_e32 v86, 0x3d372713, v67
	v_mul_f32_e32 v86, v67, v86
	v_fma_f32 v86, v67, v86, v67
	v_mul_f32_e32 v86, 0x3f4c422a, v86
	v_mul_f32_e32 v86, 0xc038aa3b, v86
	v_exp_f32_e32 v86, v86
	s_nop 0
	v_add_f32_e32 v86, 1.0, v86
	v_rcp_f32_e32 v86, v86
	s_nop 0
	v_mul_f32_e32 v67, v67, v86
	v_mul_f32_e32 v86, 0x3d372713, v72
	v_mul_f32_e32 v86, v72, v86
	v_fma_f32 v86, v72, v86, v72
	v_mul_f32_e32 v86, 0x3f4c422a, v86
	v_mul_f32_e32 v86, 0xc038aa3b, v86
	v_exp_f32_e32 v86, v86
	s_nop 0
	v_add_f32_e32 v86, 1.0, v86
	v_rcp_f32_e32 v86, v86
	s_nop 0
	v_mul_f32_e32 v72, v72, v86
	v_mul_f32_e32 v86, 0x3d372713, v68
	v_mul_f32_e32 v86, v68, v86
	v_fma_f32 v86, v68, v86, v68
	v_mul_f32_e32 v86, 0x3f4c422a, v86
	v_mul_f32_e32 v86, 0xc038aa3b, v86
	v_exp_f32_e32 v86, v86
	s_nop 0
	v_add_f32_e32 v86, 1.0, v86
	v_rcp_f32_e32 v86, v86
	s_nop 0
	v_mul_f32_e32 v68, v68, v86
	v_mul_f32_e32 v86, 0x3d372713, v73
	v_mul_f32_e32 v86, v73, v86
	v_fma_f32 v86, v73, v86, v73
	v_mul_f32_e32 v86, 0x3f4c422a, v86
	v_mul_f32_e32 v86, 0xc038aa3b, v86
	v_exp_f32_e32 v86, v86
	s_nop 0
	v_add_f32_e32 v86, 1.0, v86
	v_rcp_f32_e32 v86, v86
	s_nop 0
	v_mul_f32_e32 v73, v73, v86
	v_mul_f32_e32 v86, 0x3d372713, v69
	v_mul_f32_e32 v86, v69, v86
	v_fma_f32 v86, v69, v86, v69
	v_mul_f32_e32 v86, 0x3f4c422a, v86
	v_mul_f32_e32 v86, 0xc038aa3b, v86
	v_exp_f32_e32 v86, v86
	s_nop 0
	v_add_f32_e32 v86, 1.0, v86
	v_rcp_f32_e32 v86, v86
	s_nop 0
	v_mul_f32_e32 v69, v69, v86
	v_cvt_pk_bf16_f32 v86, v70, v71
	v_cvt_pk_bf16_f32 v87, v72, v73
	v_cvt_pk_bf16_f32 v88, v66, v67
	v_cvt_pk_bf16_f32 v89, v68, v69
	s_nop 0
	v_readfirstlane_b32 s98, v84
	v_readfirstlane_b32 s99, v85
	ds_write_b128 v222, v[86:89]
	ds_read_b128 v[230:233], v223
	s_waitcnt lgkmcnt(0)
	s_nop 1
	global_store_dwordx4 v224, v[230:233], s[98:99] offset:256
	s_cbranch_vccnz .LBB0_230
; __device__ __forceinline__ unsigned cvt_pk_bf16(float lo, float hi) { unsigned r; asm volatile("v_cvt_pk_bf16_f32 %0, %1, %2" : "=v"(r) : "v"(lo), "v"(hi)); return r; }
; __device__ __forceinline__ float quad_sum(float s) { s += __shfl_xor(s, 16); s += __shfl_xor(s, 32); return s; }
;     __device__ __forceinline__ void operator()(const f32x4 (&acc)[2][2][4][2], const Unit& u, int wr, int wc, int fr, int fq) const {
;     ...
;                         s1 += (v0[0] + v0[1]) + (v0[2] + v0[3]) + (v1[0] + v1[1]) + (v1[2] + v1[3]);
;                         s2 += (v0[0] * v0[0] + v0[1] * v0[1]) + (v0[2] * v0[2] + v0[3] * v0[3]) + (v1[0] * v1[0] + v1[1] * v1[1]) + (v1[2] * v1[2] + v1[3] * v1[3]);
;                         u32x4 w; w.x = cvt_pk_bf16(v0[0], v0[1]); w.y = cvt_pk_bf16(v0[2], v0[3]); w.z = cvt_pk_bf16(v1[0], v1[1]); w.w = cvt_pk_bf16(v1[2], v1[3]);
;                         *(u32x4*)(rowp + bj * HALF) = w; }
;                     if (stats) { s1 = quad_sum(s1); s2 = quad_sum(s2); if (fq == 0) { atomicAdd(st1 + row, s1); atomicAdd(st2 + row, s2); } } }
	s_nop 0
	v_mul_f32_e32 v86, v79, v79
	v_mul_f32_e32 v87, v81, v81
	v_mul_f32_e32 v85, v75, v75
	v_fmac_f32_e32 v86, v78, v78
	v_fmac_f32_e32 v87, v80, v80
	v_mul_f32_e32 v84, v77, v77
	v_fmac_f32_e32 v85, v74, v74
	v_add_f32_e32 v86, v86, v87
	v_fmac_f32_e32 v84, v76, v76
	v_add_f32_e32 v85, v86, v85
	v_add_f32_e32 v84, v84, v85
	v_mul_f32_e32 v85, v69, v69
	v_mul_f32_e32 v86, v67, v67
	v_fmac_f32_e32 v85, v68, v68
	v_fmac_f32_e32 v86, v66, v66
	v_add_f32_e32 v68, v68, v69
	v_add_f32_e32 v66, v66, v67
	v_add_f32_e32 v67, v70, v71
	v_add_f32_e32 v69, v72, v73
	v_add_f32_e32 v67, v67, v69
	v_add_f32_e32 v76, v76, v77
	v_add_f32_e32 v74, v74, v75
	v_add_f32_e32 v75, v78, v79
	v_add_f32_e32 v77, v80, v81
	v_add_f32_e32 v66, v67, v66
	v_add_f32_e32 v75, v75, v77
	v_add_f32_e32 v66, v68, v66
	v_and_b32_e32 v68, 64, v183
	v_add_f32_e32 v74, v75, v74
	v_xor_b32_e32 v67, 16, v183
	v_add_u32_e32 v68, 64, v68
	v_mul_f32_e32 v87, v71, v71
	v_mul_f32_e32 v88, v73, v73
	v_add_f32_e32 v74, v76, v74
	v_cmp_lt_i32_e32 vcc, v67, v68
	v_fmac_f32_e32 v87, v70, v70
	v_fmac_f32_e32 v88, v72, v72
	v_add_f32_e32 v74, 0, v74
	v_cndmask_b32_e32 v67, v183, v67, vcc
	v_add_f32_e32 v66, v74, v66
	v_lshlrev_b32_e32 v67, 2, v67
	v_add_f32_e32 v70, v87, v88
	ds_bpermute_b32 v69, v67, v66
	v_add_f32_e32 v70, v70, v86
	v_add_f32_e32 v70, v85, v70
	v_add_f32_e32 v70, v84, v70
	ds_bpermute_b32 v71, v67, v70
	s_waitcnt lgkmcnt(0)
	v_add_f32_e32 v66, v66, v69
	v_xor_b32_e32 v69, 32, v183
	v_cmp_lt_i32_e32 vcc, v69, v68
	v_add_f32_e32 v68, v70, v71
	s_nop 0
	v_cndmask_b32_e32 v67, v183, v69, vcc
	v_lshlrev_b32_e32 v69, 2, v67
	ds_bpermute_b32 v67, v69, v66
	ds_bpermute_b32 v69, v69, v68
	s_and_saveexec_b64 s[8:9], s[2:3]
	s_cbranch_execz .LBB0_229
	v_lshlrev_b64 v[70:71], 2, v[82:83]
	v_lshl_add_u64 v[72:73], s[78:79], 0, v[70:71]
	v_lshl_add_u64 v[70:71], s[76:77], 0, v[70:71]
	s_waitcnt lgkmcnt(0)
	v_add_f32_e32 v66, v66, v67
	v_add_f32_e32 v68, v68, v69
	global_atomic_add_f32 v[70:71], v66, off
	global_atomic_add_f32 v[72:73], v68, off

; __device__ __forceinline__ unsigned cvt_pk_bf16(float lo, float hi) { unsigned r; asm volatile("v_cvt_pk_bf16_f32 %0, %1, %2" : "=v"(r) : "v"(lo), "v"(hi)); return r; }
; __device__ __forceinline__ float gelu_t(float x) { const float u = 0.7978845608028654f * (x + 0.044715f * x * x * x); return x * fast_rcp(1.0f + fast_exp2(-2.8853900817779268f * u)); }
;     __device__ __forceinline__ void operator()(const f32x4 (&acc)[2][2][4][2], const Unit& u, int wr, int wc, int fr, int fq) const {
;     ...
;                 for (int m = 0; m < 4; ++m) { const int row = row0 + ai * HALF + m * 16; bf16_t* rowp = dst + (size_t)row * 512 + col0; float s1 = 0.f, s2 = 0.f;
; #pragma unroll
;                     for (int bj = 0; bj < 2; ++bj) { f32x4 v0 = acc[ai][bj][m][0], v1 = acc[ai][bj][m][1];
; #pragma unroll
;                         for (int j = 0; j < 4; ++j) { v0[j] = gelu_t(v0[j]); v1[j] = gelu_t(v1[j]); }
;                         s1 += (v0[0] + v0[1]) + (v0[2] + v0[3]) + (v1[0] + v1[1]) + (v1[2] + v1[3]);
;                         s2 += (v0[0] * v0[0] + v0[1] * v0[1]) + (v0[2] * v0[2] + v0[3] * v0[3]) + (v1[0] * v1[0] + v1[1] * v1[1]) + (v1[2] * v1[2] + v1[3] * v1[3]);
;                         u32x4 w; w.x = cvt_pk_bf16(v0[0], v0[1]); w.y = cvt_pk_bf16(v0[2], v0[3]); w.z = cvt_pk_bf16(v1[0], v1[1]); w.w = cvt_pk_bf16(v1[2], v1[3]);
;                         *(u32x4*)(rowp + bj * HALF) = w; }
.LBB0_230:
	v_mul_f32_e32 v70, 0x3d372713, v62
	v_mul_f32_e32 v70, v62, v70
	v_fma_f32 v70, v62, v70, v62
	v_mul_f32_e32 v70, 0x3f4c422a, v70
	v_mul_f32_e32 v70, 0xc038aa3b, v70
	v_exp_f32_e32 v70, v70
	v_add_u32_e32 v66, 0x80, v166
	s_waitcnt lgkmcnt(0)
	v_ashrrev_i32_e32 v67, 31, v66
	v_lshlrev_b64 v[68:69], 10, v[66:67]
	v_add_f32_e32 v70, 1.0, v70
	v_rcp_f32_e32 v70, v70
	v_lshl_add_u64 v[68:69], v[130:131], 0, v[68:69]
	s_and_b64 vcc, exec, s[6:7]
	v_mul_f32_e32 v62, v62, v70
	v_mul_f32_e32 v70, 0x3d372713, v58
	v_mul_f32_e32 v70, v58, v70
	v_fma_f32 v70, v58, v70, v58
	v_mul_f32_e32 v70, 0x3f4c422a, v70
	v_mul_f32_e32 v70, 0xc038aa3b, v70
	v_exp_f32_e32 v70, v70
	s_nop 0
	v_add_f32_e32 v70, 1.0, v70
	v_rcp_f32_e32 v70, v70
	s_nop 0
	v_mul_f32_e32 v58, v58, v70
	v_mul_f32_e32 v70, 0x3d372713, v63
	v_mul_f32_e32 v70, v63, v70
	v_fma_f32 v70, v63, v70, v63
	v_mul_f32_e32 v70, 0x3f4c422a, v70
	v_mul_f32_e32 v70, 0xc038aa3b, v70
	v_exp_f32_e32 v70, v70
	s_nop 0
	v_add_f32_e32 v70, 1.0, v70
	v_rcp_f32_e32 v70, v70
	s_nop 0
	v_mul_f32_e32 v63, v63, v70
	v_mul_f32_e32 v70, 0x3d372713, v59
	v_mul_f32_e32 v70, v59, v70
	v_fma_f32 v70, v59, v70, v59
	v_mul_f32_e32 v70, 0x3f4c422a, v70
	v_mul_f32_e32 v70, 0xc038aa3b, v70
	v_exp_f32_e32 v70, v70
	s_nop 0
	v_add_f32_e32 v70, 1.0, v70
	v_rcp_f32_e32 v70, v70
	s_nop 0
	v_mul_f32_e32 v59, v59, v70
	v_mul_f32_e32 v70, 0x3d372713, v64
	v_mul_f32_e32 v70, v64, v70
	v_fma_f32 v70, v64, v70, v64
	v_mul_f32_e32 v70, 0x3f4c422a, v70
	v_mul_f32_e32 v70, 0xc038aa3b, v70
	v_exp_f32_e32 v70, v70
	s_nop 0
	v_add_f32_e32 v70, 1.0, v70
	v_rcp_f32_e32 v70, v70
	s_nop 0
	v_mul_f32_e32 v64, v64, v70
	v_mul_f32_e32 v70, 0x3d372713, v60
	v_mul_f32_e32 v70, v60, v70
	v_fma_f32 v70, v60, v70, v60
	v_mul_f32_e32 v70, 0x3f4c422a, v70
	v_mul_f32_e32 v70, 0xc038aa3b, v70
	v_exp_f32_e32 v70, v70
	s_nop 0
	v_add_f32_e32 v70, 1.0, v70
	v_rcp_f32_e32 v70, v70
	s_nop 0
	v_mul_f32_e32 v60, v60, v70
	v_mul_f32_e32 v70, 0x3d372713, v65
	v_mul_f32_e32 v70, v65, v70
	v_fma_f32 v70, v65, v70, v65
	v_mul_f32_e32 v70, 0x3f4c422a, v70
	v_mul_f32_e32 v70, 0xc038aa3b, v70
	v_exp_f32_e32 v70, v70
	s_nop 0
	v_add_f32_e32 v70, 1.0, v70
	v_rcp_f32_e32 v70, v70
	s_nop 0
	v_mul_f32_e32 v65, v65, v70
	v_mul_f32_e32 v70, 0x3d372713, v61
	v_mul_f32_e32 v70, v61, v70
	v_fma_f32 v70, v61, v70, v61
	v_mul_f32_e32 v70, 0x3f4c422a, v70
	v_mul_f32_e32 v70, 0xc038aa3b, v70
	v_exp_f32_e32 v70, v70
	s_nop 0
	v_add_f32_e32 v70, 1.0, v70
	v_rcp_f32_e32 v70, v70
	s_nop 0
	v_mul_f32_e32 v61, v61, v70
	v_cvt_pk_bf16_f32 v70, v62, v63
	v_cvt_pk_bf16_f32 v71, v64, v65
	v_cvt_pk_bf16_f32 v72, v58, v59
	v_cvt_pk_bf16_f32 v73, v60, v61
	s_nop 0
	v_readfirstlane_b32 s98, v68
	v_readfirstlane_b32 s99, v69
	ds_write_b128 v222, v[70:73]
	ds_read_b128 v[230:233], v223
	s_waitcnt lgkmcnt(0)
	s_nop 1
	global_store_dwordx4 v224, v[230:233], s[98:99]
	s_nop 1
	v_mul_f32_e32 v70, 0x3d372713, v54
	v_mul_f32_e32 v70, v54, v70
	v_fma_f32 v70, v54, v70, v54
	v_mul_f32_e32 v70, 0x3f4c422a, v70
	v_mul_f32_e32 v70, 0xc038aa3b, v70
	v_exp_f32_e32 v70, v70
	s_nop 0
	v_add_f32_e32 v70, 1.0, v70
	v_rcp_f32_e32 v70, v70
	s_nop 0
	v_mul_f32_e32 v54, v54, v70
	v_mul_f32_e32 v70, 0x3d372713, v50
	v_mul_f32_e32 v70, v50, v70
	v_fma_f32 v70, v50, v70, v50
	v_mul_f32_e32 v70, 0x3f4c422a, v70
	v_mul_f32_e32 v70, 0xc038aa3b, v70
	v_exp_f32_e32 v70, v70
	s_nop 0
	v_add_f32_e32 v70, 1.0, v70
	v_rcp_f32_e32 v70, v70
	s_nop 0
	v_mul_f32_e32 v50, v50, v70
	v_mul_f32_e32 v70, 0x3d372713, v55
	v_mul_f32_e32 v70, v55, v70
	v_fma_f32 v70, v55, v70, v55
	v_mul_f32_e32 v70, 0x3f4c422a, v70
	v_mul_f32_e32 v70, 0xc038aa3b, v70
	v_exp_f32_e32 v70, v70
	s_nop 0
	v_add_f32_e32 v70, 1.0, v70
	v_rcp_f32_e32 v70, v70
	s_nop 0
	v_mul_f32_e32 v55, v55, v70
	v_mul_f32_e32 v70, 0x3d372713, v51
	v_mul_f32_e32 v70, v51, v70
	v_fma_f32 v70, v51, v70, v51
	v_mul_f32_e32 v70, 0x3f4c422a, v70
	v_mul_f32_e32 v70, 0xc038aa3b, v70
	v_exp_f32_e32 v70, v70
	s_nop 0
	v_add_f32_e32 v70, 1.0, v70
	v_rcp_f32_e32 v70, v70
	s_nop 0
	v_mul_f32_e32 v51, v51, v70
	v_mul_f32_e32 v70, 0x3d372713, v56
	v_mul_f32_e32 v70, v56, v70
	v_fma_f32 v70, v56, v70, v56
	v_mul_f32_e32 v70, 0x3f4c422a, v70
	v_mul_f32_e32 v70, 0xc038aa3b, v70
	v_exp_f32_e32 v70, v70
	s_nop 0
	v_add_f32_e32 v70, 1.0, v70
	v_rcp_f32_e32 v70, v70
	s_nop 0
	v_mul_f32_e32 v56, v56, v70
	v_mul_f32_e32 v70, 0x3d372713, v52
	v_mul_f32_e32 v70, v52, v70
	v_fma_f32 v70, v52, v70, v52
	v_mul_f32_e32 v70, 0x3f4c422a, v70
	v_mul_f32_e32 v70, 0xc038aa3b, v70
	v_exp_f32_e32 v70, v70
	s_nop 0
	v_add_f32_e32 v70, 1.0, v70
	v_rcp_f32_e32 v70, v70
	s_nop 0
	v_mul_f32_e32 v52, v52, v70
	v_mul_f32_e32 v70, 0x3d372713, v57
	v_mul_f32_e32 v70, v57, v70
	v_fma_f32 v70, v57, v70, v57
	v_mul_f32_e32 v70, 0x3f4c422a, v70
	v_mul_f32_e32 v70, 0xc038aa3b, v70
	v_exp_f32_e32 v70, v70
	s_nop 0
	v_add_f32_e32 v70, 1.0, v70
	v_rcp_f32_e32 v70, v70
	s_nop 0
	v_mul_f32_e32 v57, v57, v70
	v_mul_f32_e32 v70, 0x3d372713, v53
	v_mul_f32_e32 v70, v53, v70
	v_fma_f32 v70, v53, v70, v53
	v_mul_f32_e32 v70, 0x3f4c422a, v70
	v_mul_f32_e32 v70, 0xc038aa3b, v70
	v_exp_f32_e32 v70, v70
	s_nop 0
	v_add_f32_e32 v70, 1.0, v70
	v_rcp_f32_e32 v70, v70
	s_nop 0
	v_mul_f32_e32 v53, v53, v70
	v_cvt_pk_bf16_f32 v70, v54, v55
	v_cvt_pk_bf16_f32 v71, v56, v57
	v_cvt_pk_bf16_f32 v72, v50, v51
	v_cvt_pk_bf16_f32 v73, v52, v53
	s_nop 0
	v_readfirstlane_b32 s98, v68
	v_readfirstlane_b32 s99, v69
	ds_write_b128 v222, v[70:73]
	ds_read_b128 v[230:233], v223
	s_waitcnt lgkmcnt(0)
	s_nop 1
	global_store_dwordx4 v224, v[230:233], s[98:99] offset:256
	s_cbranch_vccnz .LBB0_234
; __device__ __forceinline__ unsigned cvt_pk_bf16(float lo, float hi) { unsigned r; asm volatile("v_cvt_pk_bf16_f32 %0, %1, %2" : "=v"(r) : "v"(lo), "v"(hi)); return r; }
; __device__ __forceinline__ float quad_sum(float s) { s += __shfl_xor(s, 16); s += __shfl_xor(s, 32); return s; }
;     __device__ __forceinline__ void operator()(const f32x4 (&acc)[2][2][4][2], const Unit& u, int wr, int wc, int fr, int fq) const {
;     ...
;                         s1 += (v0[0] + v0[1]) + (v0[2] + v0[3]) + (v1[0] + v1[1]) + (v1[2] + v1[3]);
;                         s2 += (v0[0] * v0[0] + v0[1] * v0[1]) + (v0[2] * v0[2] + v0[3] * v0[3]) + (v1[0] * v1[0] + v1[1] * v1[1]) + (v1[2] * v1[2] + v1[3] * v1[3]);
;                         u32x4 w; w.x = cvt_pk_bf16(v0[0], v0[1]); w.y = cvt_pk_bf16(v0[2], v0[3]); w.z = cvt_pk_bf16(v1[0], v1[1]); w.w = cvt_pk_bf16(v1[2], v1[3]);
;                         *(u32x4*)(rowp + bj * HALF) = w; }
;                     if (stats) { s1 = quad_sum(s1); s2 = quad_sum(s2); if (fq == 0) { atomicAdd(st1 + row, s1); atomicAdd(st2 + row, s2); } } }
	s_nop 0
	v_mul_f32_e32 v70, v63, v63
	v_mul_f32_e32 v71, v65, v65
	v_mul_f32_e32 v69, v59, v59
	v_fmac_f32_e32 v70, v62, v62
	v_fmac_f32_e32 v71, v64, v64
	v_mul_f32_e32 v68, v61, v61
	v_fmac_f32_e32 v69, v58, v58
	v_add_f32_e32 v70, v70, v71
	v_fmac_f32_e32 v68, v60, v60
	v_add_f32_e32 v69, v70, v69
	v_add_f32_e32 v68, v68, v69
	v_mul_f32_e32 v69, v53, v53
	v_mul_f32_e32 v70, v51, v51
	v_fmac_f32_e32 v69, v52, v52
	v_fmac_f32_e32 v70, v50, v50
	v_add_f32_e32 v52, v52, v53
	v_add_f32_e32 v50, v50, v51
	v_add_f32_e32 v51, v54, v55
	v_add_f32_e32 v53, v56, v57
	v_add_f32_e32 v51, v51, v53
	v_add_f32_e32 v60, v60, v61
	v_add_f32_e32 v58, v58, v59
	v_add_f32_e32 v59, v62, v63
	v_add_f32_e32 v61, v64, v65
	v_add_f32_e32 v50, v51, v50
	v_add_f32_e32 v59, v59, v61
	v_add_f32_e32 v50, v52, v50
	v_and_b32_e32 v52, 64, v183
	v_add_f32_e32 v58, v59, v58
	v_xor_b32_e32 v51, 16, v183
	v_add_u32_e32 v52, 64, v52
	v_mul_f32_e32 v71, v55, v55
	v_mul_f32_e32 v72, v57, v57
	v_add_f32_e32 v58, v60, v58
	v_cmp_lt_i32_e32 vcc, v51, v52
	v_fmac_f32_e32 v71, v54, v54
	v_fmac_f32_e32 v72, v56, v56
	v_add_f32_e32 v58, 0, v58
	v_cndmask_b32_e32 v51, v183, v51, vcc
	v_add_f32_e32 v50, v58, v50
	v_lshlrev_b32_e32 v51, 2, v51
	v_add_f32_e32 v54, v71, v72
	ds_bpermute_b32 v53, v51, v50
	v_add_f32_e32 v54, v54, v70
	v_add_f32_e32 v54, v69, v54
	v_add_f32_e32 v54, v68, v54
	ds_bpermute_b32 v55, v51, v54
	s_waitcnt lgkmcnt(0)
	v_add_f32_e32 v50, v50, v53
	v_xor_b32_e32 v53, 32, v183
	v_cmp_lt_i32_e32 vcc, v53, v52
	v_add_f32_e32 v52, v54, v55
	s_nop 0
	v_cndmask_b32_e32 v51, v183, v53, vcc
	v_lshlrev_b32_e32 v53, 2, v51
	ds_bpermute_b32 v51, v53, v50
	ds_bpermute_b32 v53, v53, v52
	s_and_saveexec_b64 s[8:9], s[2:3]
	s_cbranch_execz .LBB0_233
	v_lshlrev_b64 v[54:55], 2, v[66:67]
	v_lshl_add_u64 v[56:57], s[78:79], 0, v[54:55]
	v_lshl_add_u64 v[54:55], s[76:77], 0, v[54:55]
	s_waitcnt lgkmcnt(0)
	v_add_f32_e32 v50, v50, v51
	v_add_f32_e32 v52, v52, v53
	global_atomic_add_f32 v[54:55], v50, off
	global_atomic_add_f32 v[56:57], v52, off

; __device__ __forceinline__ unsigned cvt_pk_bf16(float lo, float hi) { unsigned r; asm volatile("v_cvt_pk_bf16_f32 %0, %1, %2" : "=v"(r) : "v"(lo), "v"(hi)); return r; }
; __device__ __forceinline__ float gelu_t(float x) { const float u = 0.7978845608028654f * (x + 0.044715f * x * x * x); return x * fast_rcp(1.0f + fast_exp2(-2.8853900817779268f * u)); }
;     __device__ __forceinline__ void operator()(const f32x4 (&acc)[2][2][4][2], const Unit& u, int wr, int wc, int fr, int fq) const {
;     ...
;                 for (int m = 0; m < 4; ++m) { const int row = row0 + ai * HALF + m * 16; bf16_t* rowp = dst + (size_t)row * 512 + col0; float s1 = 0.f, s2 = 0.f;
; #pragma unroll
;                     for (int bj = 0; bj < 2; ++bj) { f32x4 v0 = acc[ai][bj][m][0], v1 = acc[ai][bj][m][1];
; #pragma unroll
;                         for (int j = 0; j < 4; ++j) { v0[j] = gelu_t(v0[j]); v1[j] = gelu_t(v1[j]); }
;                         s1 += (v0[0] + v0[1]) + (v0[2] + v0[3]) + (v1[0] + v1[1]) + (v1[2] + v1[3]);
;                         s2 += (v0[0] * v0[0] + v0[1] * v0[1]) + (v0[2] * v0[2] + v0[3] * v0[3]) + (v1[0] * v1[0] + v1[1] * v1[1]) + (v1[2] * v1[2] + v1[3] * v1[3]);
;                         u32x4 w; w.x = cvt_pk_bf16(v0[0], v0[1]); w.y = cvt_pk_bf16(v0[2], v0[3]); w.z = cvt_pk_bf16(v1[0], v1[1]); w.w = cvt_pk_bf16(v1[2], v1[3]);
;                         *(u32x4*)(rowp + bj * HALF) = w; }
.LBB0_234:
	v_mul_f32_e32 v54, 0x3d372713, v46
	v_mul_f32_e32 v54, v46, v54
	v_fma_f32 v54, v46, v54, v46
	v_mul_f32_e32 v54, 0x3f4c422a, v54
	v_mul_f32_e32 v54, 0xc038aa3b, v54
	v_exp_f32_e32 v54, v54
	v_add_u32_e32 v50, 0x90, v166
	s_waitcnt lgkmcnt(0)
	v_ashrrev_i32_e32 v51, 31, v50
	v_lshlrev_b64 v[52:53], 10, v[50:51]
	v_add_f32_e32 v54, 1.0, v54
	v_rcp_f32_e32 v54, v54
	v_lshl_add_u64 v[52:53], v[130:131], 0, v[52:53]
	s_and_b64 vcc, exec, s[6:7]
	v_mul_f32_e32 v46, v46, v54
	v_mul_f32_e32 v54, 0x3d372713, v42
	v_mul_f32_e32 v54, v42, v54
	v_fma_f32 v54, v42, v54, v42
	v_mul_f32_e32 v54, 0x3f4c422a, v54
	v_mul_f32_e32 v54, 0xc038aa3b, v54
	v_exp_f32_e32 v54, v54
	s_nop 0
	v_add_f32_e32 v54, 1.0, v54
	v_rcp_f32_e32 v54, v54
	s_nop 0
	v_mul_f32_e32 v42, v42, v54
	v_mul_f32_e32 v54, 0x3d372713, v47
	v_mul_f32_e32 v54, v47, v54
	v_fma_f32 v54, v47, v54, v47
	v_mul_f32_e32 v54, 0x3f4c422a, v54
	v_mul_f32_e32 v54, 0xc038aa3b, v54
	v_exp_f32_e32 v54, v54
	s_nop 0
	v_add_f32_e32 v54, 1.0, v54
	v_rcp_f32_e32 v54, v54
	s_nop 0
	v_mul_f32_e32 v47, v47, v54
	v_mul_f32_e32 v54, 0x3d372713, v43
	v_mul_f32_e32 v54, v43, v54
	v_fma_f32 v54, v43, v54, v43
	v_mul_f32_e32 v54, 0x3f4c422a, v54
	v_mul_f32_e32 v54, 0xc038aa3b, v54
	v_exp_f32_e32 v54, v54
	s_nop 0
	v_add_f32_e32 v54, 1.0, v54
	v_rcp_f32_e32 v54, v54
	s_nop 0
	v_mul_f32_e32 v43, v43, v54
	v_mul_f32_e32 v54, 0x3d372713, v48
	v_mul_f32_e32 v54, v48, v54
	v_fma_f32 v54, v48, v54, v48
	v_mul_f32_e32 v54, 0x3f4c422a, v54
	v_mul_f32_e32 v54, 0xc038aa3b, v54
	v_exp_f32_e32 v54, v54
	s_nop 0
	v_add_f32_e32 v54, 1.0, v54
	v_rcp_f32_e32 v54, v54
	s_nop 0
	v_mul_f32_e32 v48, v48, v54
	v_mul_f32_e32 v54, 0x3d372713, v44
	v_mul_f32_e32 v54, v44, v54
	v_fma_f32 v54, v44, v54, v44
	v_mul_f32_e32 v54, 0x3f4c422a, v54
	v_mul_f32_e32 v54, 0xc038aa3b, v54
	v_exp_f32_e32 v54, v54
	s_nop 0
	v_add_f32_e32 v54, 1.0, v54
	v_rcp_f32_e32 v54, v54
	s_nop 0
	v_mul_f32_e32 v44, v44, v54
	v_mul_f32_e32 v54, 0x3d372713, v49
	v_mul_f32_e32 v54, v49, v54
	v_fma_f32 v54, v49, v54, v49
	v_mul_f32_e32 v54, 0x3f4c422a, v54
	v_mul_f32_e32 v54, 0xc038aa3b, v54
	v_exp_f32_e32 v54, v54
	s_nop 0
	v_add_f32_e32 v54, 1.0, v54
	v_rcp_f32_e32 v54, v54
	s_nop 0
	v_mul_f32_e32 v49, v49, v54
	v_mul_f32_e32 v54, 0x3d372713, v45
	v_mul_f32_e32 v54, v45, v54
	v_fma_f32 v54, v45, v54, v45
	v_mul_f32_e32 v54, 0x3f4c422a, v54
	v_mul_f32_e32 v54, 0xc038aa3b, v54
	v_exp_f32_e32 v54, v54
	s_nop 0
	v_add_f32_e32 v54, 1.0, v54
	v_rcp_f32_e32 v54, v54
	s_nop 0
	v_mul_f32_e32 v45, v45, v54
	v_cvt_pk_bf16_f32 v54, v46, v47
	v_cvt_pk_bf16_f32 v55, v48, v49
	v_cvt_pk_bf16_f32 v56, v42, v43
	v_cvt_pk_bf16_f32 v57, v44, v45
	s_nop 0
	v_readfirstlane_b32 s98, v52
	v_readfirstlane_b32 s99, v53
	ds_write_b128 v222, v[54:57]
	ds_read_b128 v[230:233], v223
	s_waitcnt lgkmcnt(0)
	s_nop 1
	global_store_dwordx4 v224, v[230:233], s[98:99]
	s_nop 1
	v_mul_f32_e32 v54, 0x3d372713, v38
	v_mul_f32_e32 v54, v38, v54
	v_fma_f32 v54, v38, v54, v38
	v_mul_f32_e32 v54, 0x3f4c422a, v54
	v_mul_f32_e32 v54, 0xc038aa3b, v54
	v_exp_f32_e32 v54, v54
	s_nop 0
	v_add_f32_e32 v54, 1.0, v54
	v_rcp_f32_e32 v54, v54
	s_nop 0
	v_mul_f32_e32 v38, v38, v54
	v_mul_f32_e32 v54, 0x3d372713, v34
	v_mul_f32_e32 v54, v34, v54
	v_fma_f32 v54, v34, v54, v34
	v_mul_f32_e32 v54, 0x3f4c422a, v54
	v_mul_f32_e32 v54, 0xc038aa3b, v54
	v_exp_f32_e32 v54, v54
	s_nop 0
	v_add_f32_e32 v54, 1.0, v54
	v_rcp_f32_e32 v54, v54
	s_nop 0
	v_mul_f32_e32 v34, v34, v54
	v_mul_f32_e32 v54, 0x3d372713, v39
	v_mul_f32_e32 v54, v39, v54
	v_fma_f32 v54, v39, v54, v39
	v_mul_f32_e32 v54, 0x3f4c422a, v54
	v_mul_f32_e32 v54, 0xc038aa3b, v54
	v_exp_f32_e32 v54, v54
	s_nop 0
	v_add_f32_e32 v54, 1.0, v54
	v_rcp_f32_e32 v54, v54
	s_nop 0
	v_mul_f32_e32 v39, v39, v54
	v_mul_f32_e32 v54, 0x3d372713, v35
	v_mul_f32_e32 v54, v35, v54
	v_fma_f32 v54, v35, v54, v35
	v_mul_f32_e32 v54, 0x3f4c422a, v54
	v_mul_f32_e32 v54, 0xc038aa3b, v54
	v_exp_f32_e32 v54, v54
	s_nop 0
	v_add_f32_e32 v54, 1.0, v54
	v_rcp_f32_e32 v54, v54
	s_nop 0
	v_mul_f32_e32 v35, v35, v54
	v_mul_f32_e32 v54, 0x3d372713, v40
	v_mul_f32_e32 v54, v40, v54
	v_fma_f32 v54, v40, v54, v40
	v_mul_f32_e32 v54, 0x3f4c422a, v54
	v_mul_f32_e32 v54, 0xc038aa3b, v54
	v_exp_f32_e32 v54, v54
	s_nop 0
	v_add_f32_e32 v54, 1.0, v54
	v_rcp_f32_e32 v54, v54
	s_nop 0
	v_mul_f32_e32 v40, v40, v54
	v_mul_f32_e32 v54, 0x3d372713, v36
	v_mul_f32_e32 v54, v36, v54
	v_fma_f32 v54, v36, v54, v36
	v_mul_f32_e32 v54, 0x3f4c422a, v54
	v_mul_f32_e32 v54, 0xc038aa3b, v54
	v_exp_f32_e32 v54, v54
	s_nop 0
	v_add_f32_e32 v54, 1.0, v54
	v_rcp_f32_e32 v54, v54
	s_nop 0
	v_mul_f32_e32 v36, v36, v54
	v_mul_f32_e32 v54, 0x3d372713, v41
	v_mul_f32_e32 v54, v41, v54
	v_fma_f32 v54, v41, v54, v41
	v_mul_f32_e32 v54, 0x3f4c422a, v54
	v_mul_f32_e32 v54, 0xc038aa3b, v54
	v_exp_f32_e32 v54, v54
	s_nop 0
	v_add_f32_e32 v54, 1.0, v54
	v_rcp_f32_e32 v54, v54
	s_nop 0
	v_mul_f32_e32 v41, v41, v54
	v_mul_f32_e32 v54, 0x3d372713, v37
	v_mul_f32_e32 v54, v37, v54
	v_fma_f32 v54, v37, v54, v37
	v_mul_f32_e32 v54, 0x3f4c422a, v54
	v_mul_f32_e32 v54, 0xc038aa3b, v54
	v_exp_f32_e32 v54, v54
	s_nop 0
	v_add_f32_e32 v54, 1.0, v54
	v_rcp_f32_e32 v54, v54
	s_nop 0
	v_mul_f32_e32 v37, v37, v54
	v_cvt_pk_bf16_f32 v54, v38, v39
	v_cvt_pk_bf16_f32 v55, v40, v41
	v_cvt_pk_bf16_f32 v56, v34, v35
	v_cvt_pk_bf16_f32 v57, v36, v37
	s_nop 0
	v_readfirstlane_b32 s98, v52
	v_readfirstlane_b32 s99, v53
	ds_write_b128 v222, v[54:57]
	ds_read_b128 v[230:233], v223
	s_waitcnt lgkmcnt(0)
	s_nop 1
	global_store_dwordx4 v224, v[230:233], s[98:99] offset:256
	s_cbranch_vccnz .LBB0_238
; __device__ __forceinline__ float quad_sum(float s) { s += __shfl_xor(s, 16); s += __shfl_xor(s, 32); return s; }
;     __device__ __forceinline__ void operator()(const f32x4 (&acc)[2][2][4][2], const Unit& u, int wr, int wc, int fr, int fq) const {
;     ...
;                         s1 += (v0[0] + v0[1]) + (v0[2] + v0[3]) + (v1[0] + v1[1]) + (v1[2] + v1[3]);
;                         s2 += (v0[0] * v0[0] + v0[1] * v0[1]) + (v0[2] * v0[2] + v0[3] * v0[3]) + (v1[0] * v1[0] + v1[1] * v1[1]) + (v1[2] * v1[2] + v1[3] * v1[3]);
;     ...
;                     if (stats) { s1 = quad_sum(s1); s2 = quad_sum(s2); if (fq == 0) { atomicAdd(st1 + row, s1); atomicAdd(st2 + row, s2); } } }
	s_nop 0
	v_mul_f32_e32 v54, v47, v47
	v_mul_f32_e32 v55, v49, v49
	v_mul_f32_e32 v53, v43, v43
	v_fmac_f32_e32 v54, v46, v46
	v_fmac_f32_e32 v55, v48, v48
	v_mul_f32_e32 v52, v45, v45
	v_fmac_f32_e32 v53, v42, v42
	v_add_f32_e32 v54, v54, v55
	v_fmac_f32_e32 v52, v44, v44
	v_add_f32_e32 v53, v54, v53
	v_add_f32_e32 v52, v52, v53
	v_mul_f32_e32 v53, v37, v37
	v_mul_f32_e32 v54, v35, v35
	v_fmac_f32_e32 v53, v36, v36
	v_fmac_f32_e32 v54, v34, v34
	v_add_f32_e32 v36, v36, v37
	v_add_f32_e32 v34, v34, v35
	v_add_f32_e32 v35, v38, v39
	v_add_f32_e32 v37, v40, v41
	v_add_f32_e32 v35, v35, v37
	v_add_f32_e32 v44, v44, v45
	v_add_f32_e32 v42, v42, v43
	v_add_f32_e32 v43, v46, v47
	v_add_f32_e32 v45, v48, v49
	v_add_f32_e32 v34, v35, v34
	v_add_f32_e32 v43, v43, v45
	v_add_f32_e32 v34, v36, v34
	v_and_b32_e32 v36, 64, v183
	v_add_f32_e32 v42, v43, v42
	v_xor_b32_e32 v35, 16, v183
	v_add_u32_e32 v36, 64, v36
	v_mul_f32_e32 v55, v39, v39
	v_mul_f32_e32 v56, v41, v41
	v_add_f32_e32 v42, v44, v42
	v_cmp_lt_i32_e32 vcc, v35, v36
	v_fmac_f32_e32 v55, v38, v38
	v_fmac_f32_e32 v56, v40, v40
	v_add_f32_e32 v42, 0, v42
	v_cndmask_b32_e32 v35, v183, v35, vcc
	v_add_f32_e32 v34, v42, v34
	v_lshlrev_b32_e32 v35, 2, v35
	v_add_f32_e32 v38, v55, v56
	ds_bpermute_b32 v37, v35, v34
	v_add_f32_e32 v38, v38, v54
	v_add_f32_e32 v38, v53, v38
	v_add_f32_e32 v38, v52, v38
	ds_bpermute_b32 v39, v35, v38
	s_waitcnt lgkmcnt(0)
	v_add_f32_e32 v34, v34, v37
	v_xor_b32_e32 v37, 32, v183
	v_cmp_lt_i32_e32 vcc, v37, v36
	v_add_f32_e32 v36, v38, v39
	s_nop 0
	v_cndmask_b32_e32 v35, v183, v37, vcc
	v_lshlrev_b32_e32 v37, 2, v35
	ds_bpermute_b32 v35, v37, v34
	ds_bpermute_b32 v37, v37, v36
	s_and_saveexec_b64 s[8:9], s[2:3]
	s_cbranch_execz .LBB0_237
	v_lshlrev_b64 v[38:39], 2, v[50:51]
	v_lshl_add_u64 v[40:41], s[78:79], 0, v[38:39]
	v_lshl_add_u64 v[38:39], s[76:77], 0, v[38:39]
	s_waitcnt lgkmcnt(0)
	v_add_f32_e32 v34, v34, v35
	v_add_f32_e32 v36, v36, v37
	global_atomic_add_f32 v[38:39], v34, off
	global_atomic_add_f32 v[40:41], v36, off

; __device__ __forceinline__ unsigned cvt_pk_bf16(float lo, float hi) { unsigned r; asm volatile("v_cvt_pk_bf16_f32 %0, %1, %2" : "=v"(r) : "v"(lo), "v"(hi)); return r; }
; __device__ __forceinline__ float gelu_t(float x) { const float u = 0.7978845608028654f * (x + 0.044715f * x * x * x); return x * fast_rcp(1.0f + fast_exp2(-2.8853900817779268f * u)); }
;     __device__ __forceinline__ void operator()(const f32x4 (&acc)[2][2][4][2], const Unit& u, int wr, int wc, int fr, int fq) const {
;     ...
;                 for (int m = 0; m < 4; ++m) { const int row = row0 + ai * HALF + m * 16; bf16_t* rowp = dst + (size_t)row * 512 + col0; float s1 = 0.f, s2 = 0.f;
; #pragma unroll
;                     for (int bj = 0; bj < 2; ++bj) { f32x4 v0 = acc[ai][bj][m][0], v1 = acc[ai][bj][m][1];
; #pragma unroll
;                         for (int j = 0; j < 4; ++j) { v0[j] = gelu_t(v0[j]); v1[j] = gelu_t(v1[j]); }
;                         s1 += (v0[0] + v0[1]) + (v0[2] + v0[3]) + (v1[0] + v1[1]) + (v1[2] + v1[3]);
;                         s2 += (v0[0] * v0[0] + v0[1] * v0[1]) + (v0[2] * v0[2] + v0[3] * v0[3]) + (v1[0] * v1[0] + v1[1] * v1[1]) + (v1[2] * v1[2] + v1[3] * v1[3]);
;                         u32x4 w; w.x = cvt_pk_bf16(v0[0], v0[1]); w.y = cvt_pk_bf16(v0[2], v0[3]); w.z = cvt_pk_bf16(v1[0], v1[1]); w.w = cvt_pk_bf16(v1[2], v1[3]);
;                         *(u32x4*)(rowp + bj * HALF) = w; }
.LBB0_238:
	v_mul_f32_e32 v38, 0x3d372713, v30
	v_mul_f32_e32 v38, v30, v38
	v_fma_f32 v38, v30, v38, v30
	v_mul_f32_e32 v38, 0x3f4c422a, v38
	v_mul_f32_e32 v38, 0xc038aa3b, v38
	v_exp_f32_e32 v38, v38
	v_add_u32_e32 v34, 0xa0, v166
	s_waitcnt lgkmcnt(0)
	v_ashrrev_i32_e32 v35, 31, v34
	v_lshlrev_b64 v[36:37], 10, v[34:35]
	v_add_f32_e32 v38, 1.0, v38
	v_rcp_f32_e32 v38, v38
	v_lshl_add_u64 v[36:37], v[130:131], 0, v[36:37]
	s_and_b64 vcc, exec, s[6:7]
	v_mul_f32_e32 v30, v30, v38
	v_mul_f32_e32 v38, 0x3d372713, v26
	v_mul_f32_e32 v38, v26, v38
	v_fma_f32 v38, v26, v38, v26
	v_mul_f32_e32 v38, 0x3f4c422a, v38
	v_mul_f32_e32 v38, 0xc038aa3b, v38
	v_exp_f32_e32 v38, v38
	s_nop 0
	v_add_f32_e32 v38, 1.0, v38
	v_rcp_f32_e32 v38, v38
	s_nop 0
	v_mul_f32_e32 v26, v26, v38
	v_mul_f32_e32 v38, 0x3d372713, v31
	v_mul_f32_e32 v38, v31, v38
	v_fma_f32 v38, v31, v38, v31
	v_mul_f32_e32 v38, 0x3f4c422a, v38
	v_mul_f32_e32 v38, 0xc038aa3b, v38
	v_exp_f32_e32 v38, v38
	s_nop 0
	v_add_f32_e32 v38, 1.0, v38
	v_rcp_f32_e32 v38, v38
	s_nop 0
	v_mul_f32_e32 v31, v31, v38
	v_mul_f32_e32 v38, 0x3d372713, v27
	v_mul_f32_e32 v38, v27, v38
	v_fma_f32 v38, v27, v38, v27
	v_mul_f32_e32 v38, 0x3f4c422a, v38
	v_mul_f32_e32 v38, 0xc038aa3b, v38
	v_exp_f32_e32 v38, v38
	s_nop 0
	v_add_f32_e32 v38, 1.0, v38
	v_rcp_f32_e32 v38, v38
	s_nop 0
	v_mul_f32_e32 v27, v27, v38
	v_mul_f32_e32 v38, 0x3d372713, v32
	v_mul_f32_e32 v38, v32, v38
	v_fma_f32 v38, v32, v38, v32
	v_mul_f32_e32 v38, 0x3f4c422a, v38
	v_mul_f32_e32 v38, 0xc038aa3b, v38
	v_exp_f32_e32 v38, v38
	s_nop 0
	v_add_f32_e32 v38, 1.0, v38
	v_rcp_f32_e32 v38, v38
	s_nop 0
	v_mul_f32_e32 v32, v32, v38
	v_mul_f32_e32 v38, 0x3d372713, v28
	v_mul_f32_e32 v38, v28, v38
	v_fma_f32 v38, v28, v38, v28
	v_mul_f32_e32 v38, 0x3f4c422a, v38
	v_mul_f32_e32 v38, 0xc038aa3b, v38
	v_exp_f32_e32 v38, v38
	s_nop 0
	v_add_f32_e32 v38, 1.0, v38
	v_rcp_f32_e32 v38, v38
	s_nop 0
	v_mul_f32_e32 v28, v28, v38
	v_mul_f32_e32 v38, 0x3d372713, v33
	v_mul_f32_e32 v38, v33, v38
	v_fma_f32 v38, v33, v38, v33
	v_mul_f32_e32 v38, 0x3f4c422a, v38
	v_mul_f32_e32 v38, 0xc038aa3b, v38
	v_exp_f32_e32 v38, v38
	s_nop 0
	v_add_f32_e32 v38, 1.0, v38
	v_rcp_f32_e32 v38, v38
	s_nop 0
	v_mul_f32_e32 v33, v33, v38
	v_mul_f32_e32 v38, 0x3d372713, v29
	v_mul_f32_e32 v38, v29, v38
	v_fma_f32 v38, v29, v38, v29
	v_mul_f32_e32 v38, 0x3f4c422a, v38
	v_mul_f32_e32 v38, 0xc038aa3b, v38
	v_exp_f32_e32 v38, v38
	s_nop 0
	v_add_f32_e32 v38, 1.0, v38
	v_rcp_f32_e32 v38, v38
	s_nop 0
	v_mul_f32_e32 v29, v29, v38
	v_cvt_pk_bf16_f32 v38, v30, v31
	v_cvt_pk_bf16_f32 v39, v32, v33
	v_cvt_pk_bf16_f32 v40, v26, v27
	v_cvt_pk_bf16_f32 v41, v28, v29
	s_nop 0
	v_readfirstlane_b32 s98, v36
	v_readfirstlane_b32 s99, v37
	ds_write_b128 v222, v[38:41]
	ds_read_b128 v[230:233], v223
	s_waitcnt lgkmcnt(0)
	s_nop 1
	global_store_dwordx4 v224, v[230:233], s[98:99]
	s_nop 1
	v_mul_f32_e32 v38, 0x3d372713, v22
	v_mul_f32_e32 v38, v22, v38
	v_fma_f32 v38, v22, v38, v22
	v_mul_f32_e32 v38, 0x3f4c422a, v38
	v_mul_f32_e32 v38, 0xc038aa3b, v38
	v_exp_f32_e32 v38, v38
	s_nop 0
	v_add_f32_e32 v38, 1.0, v38
	v_rcp_f32_e32 v38, v38
	s_nop 0
	v_mul_f32_e32 v22, v22, v38
	v_mul_f32_e32 v38, 0x3d372713, v18
	v_mul_f32_e32 v38, v18, v38
	v_fma_f32 v38, v18, v38, v18
	v_mul_f32_e32 v38, 0x3f4c422a, v38
	v_mul_f32_e32 v38, 0xc038aa3b, v38
	v_exp_f32_e32 v38, v38
	s_nop 0
	v_add_f32_e32 v38, 1.0, v38
	v_rcp_f32_e32 v38, v38
	s_nop 0
	v_mul_f32_e32 v18, v18, v38
	v_mul_f32_e32 v38, 0x3d372713, v23
	v_mul_f32_e32 v38, v23, v38
	v_fma_f32 v38, v23, v38, v23
	v_mul_f32_e32 v38, 0x3f4c422a, v38
	v_mul_f32_e32 v38, 0xc038aa3b, v38
	v_exp_f32_e32 v38, v38
	s_nop 0
	v_add_f32_e32 v38, 1.0, v38
	v_rcp_f32_e32 v38, v38
	s_nop 0
	v_mul_f32_e32 v23, v23, v38
	v_mul_f32_e32 v38, 0x3d372713, v19
	v_mul_f32_e32 v38, v19, v38
	v_fma_f32 v38, v19, v38, v19
	v_mul_f32_e32 v38, 0x3f4c422a, v38
	v_mul_f32_e32 v38, 0xc038aa3b, v38
	v_exp_f32_e32 v38, v38
	s_nop 0
	v_add_f32_e32 v38, 1.0, v38
	v_rcp_f32_e32 v38, v38
	s_nop 0
	v_mul_f32_e32 v19, v19, v38
	v_mul_f32_e32 v38, 0x3d372713, v24
	v_mul_f32_e32 v38, v24, v38
	v_fma_f32 v38, v24, v38, v24
	v_mul_f32_e32 v38, 0x3f4c422a, v38
	v_mul_f32_e32 v38, 0xc038aa3b, v38
	v_exp_f32_e32 v38, v38
	s_nop 0
	v_add_f32_e32 v38, 1.0, v38
	v_rcp_f32_e32 v38, v38
	s_nop 0
	v_mul_f32_e32 v24, v24, v38
	v_mul_f32_e32 v38, 0x3d372713, v20
	v_mul_f32_e32 v38, v20, v38
	v_fma_f32 v38, v20, v38, v20
	v_mul_f32_e32 v38, 0x3f4c422a, v38
	v_mul_f32_e32 v38, 0xc038aa3b, v38
	v_exp_f32_e32 v38, v38
	s_nop 0
	v_add_f32_e32 v38, 1.0, v38
	v_rcp_f32_e32 v38, v38
	s_nop 0
	v_mul_f32_e32 v20, v20, v38
	v_mul_f32_e32 v38, 0x3d372713, v25
	v_mul_f32_e32 v38, v25, v38
	v_fma_f32 v38, v25, v38, v25
	v_mul_f32_e32 v38, 0x3f4c422a, v38
	v_mul_f32_e32 v38, 0xc038aa3b, v38
	v_exp_f32_e32 v38, v38
	s_nop 0
	v_add_f32_e32 v38, 1.0, v38
	v_rcp_f32_e32 v38, v38
	s_nop 0
	v_mul_f32_e32 v25, v25, v38
	v_mul_f32_e32 v38, 0x3d372713, v21
	v_mul_f32_e32 v38, v21, v38
	v_fma_f32 v38, v21, v38, v21
	v_mul_f32_e32 v38, 0x3f4c422a, v38
	v_mul_f32_e32 v38, 0xc038aa3b, v38
	v_exp_f32_e32 v38, v38
	s_nop 0
	v_add_f32_e32 v38, 1.0, v38
	v_rcp_f32_e32 v38, v38
	s_nop 0
	v_mul_f32_e32 v21, v21, v38
	v_cvt_pk_bf16_f32 v38, v22, v23
	v_cvt_pk_bf16_f32 v39, v24, v25
	v_cvt_pk_bf16_f32 v40, v18, v19
	v_cvt_pk_bf16_f32 v41, v20, v21
	s_nop 0
	v_readfirstlane_b32 s98, v36
	v_readfirstlane_b32 s99, v37
	ds_write_b128 v222, v[38:41]
	ds_read_b128 v[230:233], v223
	s_waitcnt lgkmcnt(0)
	s_nop 1
	global_store_dwordx4 v224, v[230:233], s[98:99] offset:256
	s_cbranch_vccnz .LBB0_242
; __device__ __forceinline__ float quad_sum(float s) { s += __shfl_xor(s, 16); s += __shfl_xor(s, 32); return s; }
;     __device__ __forceinline__ void operator()(const f32x4 (&acc)[2][2][4][2], const Unit& u, int wr, int wc, int fr, int fq) const {
;     ...
;                         s1 += (v0[0] + v0[1]) + (v0[2] + v0[3]) + (v1[0] + v1[1]) + (v1[2] + v1[3]);
;                         s2 += (v0[0] * v0[0] + v0[1] * v0[1]) + (v0[2] * v0[2] + v0[3] * v0[3]) + (v1[0] * v1[0] + v1[1] * v1[1]) + (v1[2] * v1[2] + v1[3] * v1[3]);
;     ...
;                     if (stats) { s1 = quad_sum(s1); s2 = quad_sum(s2); if (fq == 0) { atomicAdd(st1 + row, s1); atomicAdd(st2 + row, s2); } } }
	s_nop 0
	v_mul_f32_e32 v38, v31, v31
	v_mul_f32_e32 v39, v33, v33
	v_mul_f32_e32 v37, v27, v27
	v_fmac_f32_e32 v38, v30, v30
	v_fmac_f32_e32 v39, v32, v32
	v_mul_f32_e32 v36, v29, v29
	v_fmac_f32_e32 v37, v26, v26
	v_add_f32_e32 v38, v38, v39
	v_fmac_f32_e32 v36, v28, v28
	v_add_f32_e32 v37, v38, v37
	v_add_f32_e32 v36, v36, v37
	v_mul_f32_e32 v37, v21, v21
	v_mul_f32_e32 v38, v19, v19
	v_fmac_f32_e32 v37, v20, v20
	v_fmac_f32_e32 v38, v18, v18
	v_add_f32_e32 v20, v20, v21
	v_add_f32_e32 v18, v18, v19
	v_add_f32_e32 v19, v22, v23
	v_add_f32_e32 v21, v24, v25
	v_add_f32_e32 v19, v19, v21
	v_add_f32_e32 v28, v28, v29
	v_add_f32_e32 v26, v26, v27
	v_add_f32_e32 v27, v30, v31
	v_add_f32_e32 v29, v32, v33
	v_add_f32_e32 v18, v19, v18
	v_add_f32_e32 v27, v27, v29
	v_add_f32_e32 v18, v20, v18
	v_and_b32_e32 v20, 64, v183
	v_add_f32_e32 v26, v27, v26
	v_xor_b32_e32 v19, 16, v183
	v_add_u32_e32 v20, 64, v20
	v_mul_f32_e32 v39, v23, v23
	v_mul_f32_e32 v40, v25, v25
	v_add_f32_e32 v26, v28, v26
	v_cmp_lt_i32_e32 vcc, v19, v20
	v_fmac_f32_e32 v39, v22, v22
	v_fmac_f32_e32 v40, v24, v24
	v_add_f32_e32 v26, 0, v26
	v_cndmask_b32_e32 v19, v183, v19, vcc
	v_add_f32_e32 v18, v26, v18
	v_lshlrev_b32_e32 v19, 2, v19
	v_add_f32_e32 v22, v39, v40
	ds_bpermute_b32 v21, v19, v18
	v_add_f32_e32 v22, v22, v38
	v_add_f32_e32 v22, v37, v22
	v_add_f32_e32 v22, v36, v22
	ds_bpermute_b32 v23, v19, v22
	s_waitcnt lgkmcnt(0)
	v_add_f32_e32 v18, v18, v21
	v_xor_b32_e32 v21, 32, v183
	v_cmp_lt_i32_e32 vcc, v21, v20
	v_add_f32_e32 v20, v22, v23
	s_nop 0
	v_cndmask_b32_e32 v19, v183, v21, vcc
	v_lshlrev_b32_e32 v21, 2, v19
	ds_bpermute_b32 v19, v21, v18
	ds_bpermute_b32 v21, v21, v20
	s_and_saveexec_b64 s[8:9], s[2:3]
	s_cbranch_execz .LBB0_241
	v_lshlrev_b64 v[22:23], 2, v[34:35]
	v_lshl_add_u64 v[24:25], s[78:79], 0, v[22:23]
	v_lshl_add_u64 v[22:23], s[76:77], 0, v[22:23]
	s_waitcnt lgkmcnt(0)
	v_add_f32_e32 v18, v18, v19
	v_add_f32_e32 v20, v20, v21
	global_atomic_add_f32 v[22:23], v18, off
	global_atomic_add_f32 v[24:25], v20, off

; __device__ __forceinline__ unsigned cvt_pk_bf16(float lo, float hi) { unsigned r; asm volatile("v_cvt_pk_bf16_f32 %0, %1, %2" : "=v"(r) : "v"(lo), "v"(hi)); return r; }
; __device__ __forceinline__ float gelu_t(float x) { const float u = 0.7978845608028654f * (x + 0.044715f * x * x * x); return x * fast_rcp(1.0f + fast_exp2(-2.8853900817779268f * u)); }
;     __device__ __forceinline__ void operator()(const f32x4 (&acc)[2][2][4][2], const Unit& u, int wr, int wc, int fr, int fq) const {
;     ...
;                 for (int m = 0; m < 4; ++m) { const int row = row0 + ai * HALF + m * 16; bf16_t* rowp = dst + (size_t)row * 512 + col0; float s1 = 0.f, s2 = 0.f;
; #pragma unroll
;                     for (int bj = 0; bj < 2; ++bj) { f32x4 v0 = acc[ai][bj][m][0], v1 = acc[ai][bj][m][1];
; #pragma unroll
;                         for (int j = 0; j < 4; ++j) { v0[j] = gelu_t(v0[j]); v1[j] = gelu_t(v1[j]); }
;                         s1 += (v0[0] + v0[1]) + (v0[2] + v0[3]) + (v1[0] + v1[1]) + (v1[2] + v1[3]);
;                         s2 += (v0[0] * v0[0] + v0[1] * v0[1]) + (v0[2] * v0[2] + v0[3] * v0[3]) + (v1[0] * v1[0] + v1[1] * v1[1]) + (v1[2] * v1[2] + v1[3] * v1[3]);
;                         u32x4 w; w.x = cvt_pk_bf16(v0[0], v0[1]); w.y = cvt_pk_bf16(v0[2], v0[3]); w.z = cvt_pk_bf16(v1[0], v1[1]); w.w = cvt_pk_bf16(v1[2], v1[3]);
;                         *(u32x4*)(rowp + bj * HALF) = w; }
.LBB0_242:
	v_mul_f32_e32 v22, 0x3d372713, v14
	v_mul_f32_e32 v22, v14, v22
	v_fma_f32 v22, v14, v22, v14
	v_mul_f32_e32 v22, 0x3f4c422a, v22
	v_mul_f32_e32 v22, 0xc038aa3b, v22
	v_exp_f32_e32 v22, v22
	v_add_u32_e32 v18, 0xb0, v166
	s_waitcnt lgkmcnt(0)
	v_ashrrev_i32_e32 v19, 31, v18
	v_lshlrev_b64 v[20:21], 10, v[18:19]
	v_add_f32_e32 v22, 1.0, v22
	v_rcp_f32_e32 v22, v22
	v_lshl_add_u64 v[20:21], v[130:131], 0, v[20:21]
	s_and_b64 vcc, exec, s[6:7]
	v_mul_f32_e32 v14, v14, v22
	v_mul_f32_e32 v22, 0x3d372713, v10
	v_mul_f32_e32 v22, v10, v22
	v_fma_f32 v22, v10, v22, v10
	v_mul_f32_e32 v22, 0x3f4c422a, v22
	v_mul_f32_e32 v22, 0xc038aa3b, v22
	v_exp_f32_e32 v22, v22
	s_nop 0
	v_add_f32_e32 v22, 1.0, v22
	v_rcp_f32_e32 v22, v22
	s_nop 0
	v_mul_f32_e32 v10, v10, v22
	v_mul_f32_e32 v22, 0x3d372713, v15
	v_mul_f32_e32 v22, v15, v22
	v_fma_f32 v22, v15, v22, v15
	v_mul_f32_e32 v22, 0x3f4c422a, v22
	v_mul_f32_e32 v22, 0xc038aa3b, v22
	v_exp_f32_e32 v22, v22
	s_nop 0
	v_add_f32_e32 v22, 1.0, v22
	v_rcp_f32_e32 v22, v22
	s_nop 0
	v_mul_f32_e32 v15, v15, v22
	v_mul_f32_e32 v22, 0x3d372713, v11
	v_mul_f32_e32 v22, v11, v22
	v_fma_f32 v22, v11, v22, v11
	v_mul_f32_e32 v22, 0x3f4c422a, v22
	v_mul_f32_e32 v22, 0xc038aa3b, v22
	v_exp_f32_e32 v22, v22
	s_nop 0
	v_add_f32_e32 v22, 1.0, v22
	v_rcp_f32_e32 v22, v22
	s_nop 0
	v_mul_f32_e32 v11, v11, v22
	v_mul_f32_e32 v22, 0x3d372713, v16
	v_mul_f32_e32 v22, v16, v22
	v_fma_f32 v22, v16, v22, v16
	v_mul_f32_e32 v22, 0x3f4c422a, v22
	v_mul_f32_e32 v22, 0xc038aa3b, v22
	v_exp_f32_e32 v22, v22
	s_nop 0
	v_add_f32_e32 v22, 1.0, v22
	v_rcp_f32_e32 v22, v22
	s_nop 0
	v_mul_f32_e32 v16, v16, v22
	v_mul_f32_e32 v22, 0x3d372713, v12
	v_mul_f32_e32 v22, v12, v22
	v_fma_f32 v22, v12, v22, v12
	v_mul_f32_e32 v22, 0x3f4c422a, v22
	v_mul_f32_e32 v22, 0xc038aa3b, v22
	v_exp_f32_e32 v22, v22
	s_nop 0
	v_add_f32_e32 v22, 1.0, v22
	v_rcp_f32_e32 v22, v22
	s_nop 0
	v_mul_f32_e32 v12, v12, v22
	v_mul_f32_e32 v22, 0x3d372713, v17
	v_mul_f32_e32 v22, v17, v22
	v_fma_f32 v22, v17, v22, v17
	v_mul_f32_e32 v22, 0x3f4c422a, v22
	v_mul_f32_e32 v22, 0xc038aa3b, v22
	v_exp_f32_e32 v22, v22
	s_nop 0
	v_add_f32_e32 v22, 1.0, v22
	v_rcp_f32_e32 v22, v22
	s_nop 0
	v_mul_f32_e32 v17, v17, v22
	v_mul_f32_e32 v22, 0x3d372713, v13
	v_mul_f32_e32 v22, v13, v22
	v_fma_f32 v22, v13, v22, v13
	v_mul_f32_e32 v22, 0x3f4c422a, v22
	v_mul_f32_e32 v22, 0xc038aa3b, v22
	v_exp_f32_e32 v22, v22
	s_nop 0
	v_add_f32_e32 v22, 1.0, v22
	v_rcp_f32_e32 v22, v22
	s_nop 0
	v_mul_f32_e32 v13, v13, v22
	v_cvt_pk_bf16_f32 v22, v14, v15
	v_cvt_pk_bf16_f32 v23, v16, v17
	v_cvt_pk_bf16_f32 v24, v10, v11
	v_cvt_pk_bf16_f32 v25, v12, v13
	s_nop 0
	v_readfirstlane_b32 s98, v20
	v_readfirstlane_b32 s99, v21
	ds_write_b128 v222, v[22:25]
	ds_read_b128 v[230:233], v223
	s_waitcnt lgkmcnt(0)
	s_nop 1
	global_store_dwordx4 v224, v[230:233], s[98:99]
	s_nop 1
	v_mul_f32_e32 v22, 0x3d372713, v6
	v_mul_f32_e32 v22, v6, v22
	v_fma_f32 v22, v6, v22, v6
	v_mul_f32_e32 v22, 0x3f4c422a, v22
	v_mul_f32_e32 v22, 0xc038aa3b, v22
	v_exp_f32_e32 v22, v22
	s_nop 0
	v_add_f32_e32 v22, 1.0, v22
	v_rcp_f32_e32 v22, v22
	s_nop 0
	v_mul_f32_e32 v6, v6, v22
	v_mul_f32_e32 v22, 0x3d372713, v2
	v_mul_f32_e32 v22, v2, v22
	v_fma_f32 v22, v2, v22, v2
	v_mul_f32_e32 v22, 0x3f4c422a, v22
	v_mul_f32_e32 v22, 0xc038aa3b, v22
	v_exp_f32_e32 v22, v22
	s_nop 0
	v_add_f32_e32 v22, 1.0, v22
	v_rcp_f32_e32 v22, v22
	s_nop 0
	v_mul_f32_e32 v2, v2, v22
	v_mul_f32_e32 v22, 0x3d372713, v7
	v_mul_f32_e32 v22, v7, v22
	v_fma_f32 v22, v7, v22, v7
	v_mul_f32_e32 v22, 0x3f4c422a, v22
	v_mul_f32_e32 v22, 0xc038aa3b, v22
	v_exp_f32_e32 v22, v22
	s_nop 0
	v_add_f32_e32 v22, 1.0, v22
	v_rcp_f32_e32 v22, v22
	s_nop 0
	v_mul_f32_e32 v7, v7, v22
	v_mul_f32_e32 v22, 0x3d372713, v3
	v_mul_f32_e32 v22, v3, v22
	v_fma_f32 v22, v3, v22, v3
	v_mul_f32_e32 v22, 0x3f4c422a, v22
	v_mul_f32_e32 v22, 0xc038aa3b, v22
	v_exp_f32_e32 v22, v22
	s_nop 0
	v_add_f32_e32 v22, 1.0, v22
	v_rcp_f32_e32 v22, v22
	s_nop 0
	v_mul_f32_e32 v3, v3, v22
	v_mul_f32_e32 v22, 0x3d372713, v8
	v_mul_f32_e32 v22, v8, v22
	v_fma_f32 v22, v8, v22, v8
	v_mul_f32_e32 v22, 0x3f4c422a, v22
	v_mul_f32_e32 v22, 0xc038aa3b, v22
	v_exp_f32_e32 v22, v22
	s_nop 0
	v_add_f32_e32 v22, 1.0, v22
	v_rcp_f32_e32 v22, v22
	s_nop 0
	v_mul_f32_e32 v8, v8, v22
	v_mul_f32_e32 v22, 0x3d372713, v4
	v_mul_f32_e32 v22, v4, v22
	v_fma_f32 v22, v4, v22, v4
	v_mul_f32_e32 v22, 0x3f4c422a, v22
	v_mul_f32_e32 v22, 0xc038aa3b, v22
	v_exp_f32_e32 v22, v22
	s_nop 0
	v_add_f32_e32 v22, 1.0, v22
	v_rcp_f32_e32 v22, v22
	s_nop 0
	v_mul_f32_e32 v4, v4, v22
	v_mul_f32_e32 v22, 0x3d372713, v9
	v_mul_f32_e32 v22, v9, v22
	v_fma_f32 v22, v9, v22, v9
	v_mul_f32_e32 v22, 0x3f4c422a, v22
	v_mul_f32_e32 v22, 0xc038aa3b, v22
	v_exp_f32_e32 v22, v22
	s_nop 0
	v_add_f32_e32 v22, 1.0, v22
	v_rcp_f32_e32 v22, v22
	s_nop 0
	v_mul_f32_e32 v9, v9, v22
	v_mul_f32_e32 v22, 0x3d372713, v5
	v_mul_f32_e32 v22, v5, v22
	v_fma_f32 v22, v5, v22, v5
	v_mul_f32_e32 v22, 0x3f4c422a, v22
	v_mul_f32_e32 v22, 0xc038aa3b, v22
	v_exp_f32_e32 v22, v22
	s_nop 0
	v_add_f32_e32 v22, 1.0, v22
	v_rcp_f32_e32 v22, v22
	s_nop 0
	v_mul_f32_e32 v5, v5, v22
	v_cvt_pk_bf16_f32 v22, v6, v7
	v_cvt_pk_bf16_f32 v23, v8, v9
	v_cvt_pk_bf16_f32 v24, v2, v3
	v_cvt_pk_bf16_f32 v25, v4, v5
	s_nop 0
	v_readfirstlane_b32 s98, v20
	v_readfirstlane_b32 s99, v21
	ds_write_b128 v222, v[22:25]
	ds_read_b128 v[230:233], v223
	s_waitcnt lgkmcnt(0)
	s_nop 1
	global_store_dwordx4 v224, v[230:233], s[98:99] offset:256
	s_cbranch_vccnz .LBB0_246
; __device__ __forceinline__ float quad_sum(float s) { s += __shfl_xor(s, 16); s += __shfl_xor(s, 32); return s; }
;     __device__ __forceinline__ void operator()(const f32x4 (&acc)[2][2][4][2], const Unit& u, int wr, int wc, int fr, int fq) const {
;     ...
;                         s1 += (v0[0] + v0[1]) + (v0[2] + v0[3]) + (v1[0] + v1[1]) + (v1[2] + v1[3]);
;                         s2 += (v0[0] * v0[0] + v0[1] * v0[1]) + (v0[2] * v0[2] + v0[3] * v0[3]) + (v1[0] * v1[0] + v1[1] * v1[1]) + (v1[2] * v1[2] + v1[3] * v1[3]);
;     ...
;                     if (stats) { s1 = quad_sum(s1); s2 = quad_sum(s2); if (fq == 0) { atomicAdd(st1 + row, s1); atomicAdd(st2 + row, s2); } } }
	s_nop 0
	v_mul_f32_e32 v22, v15, v15
	v_mul_f32_e32 v23, v17, v17
	v_mul_f32_e32 v21, v11, v11
	v_fmac_f32_e32 v22, v14, v14
	v_fmac_f32_e32 v23, v16, v16
	v_mul_f32_e32 v20, v13, v13
	v_fmac_f32_e32 v21, v10, v10
	v_add_f32_e32 v22, v22, v23
	v_fmac_f32_e32 v20, v12, v12
	v_add_f32_e32 v21, v22, v21
	v_add_f32_e32 v20, v20, v21
	v_mul_f32_e32 v21, v5, v5
	v_mul_f32_e32 v22, v3, v3
	v_fmac_f32_e32 v21, v4, v4
	v_fmac_f32_e32 v22, v2, v2
	v_add_f32_e32 v4, v4, v5
	v_add_f32_e32 v2, v2, v3
	v_add_f32_e32 v3, v6, v7
	v_add_f32_e32 v5, v8, v9
	v_add_f32_e32 v3, v3, v5
	v_add_f32_e32 v12, v12, v13
	v_add_f32_e32 v10, v10, v11
	v_add_f32_e32 v11, v14, v15
	v_add_f32_e32 v13, v16, v17
	v_add_f32_e32 v2, v3, v2
	v_add_f32_e32 v11, v11, v13
	v_add_f32_e32 v2, v4, v2
	v_and_b32_e32 v4, 64, v183
	v_add_f32_e32 v10, v11, v10
	v_xor_b32_e32 v3, 16, v183
	v_add_u32_e32 v4, 64, v4
	v_mul_f32_e32 v23, v7, v7
	v_mul_f32_e32 v24, v9, v9
	v_add_f32_e32 v10, v12, v10
	v_cmp_lt_i32_e32 vcc, v3, v4
	v_fmac_f32_e32 v23, v6, v6
	v_fmac_f32_e32 v24, v8, v8
	v_add_f32_e32 v10, 0, v10
	v_cndmask_b32_e32 v3, v183, v3, vcc
	v_add_f32_e32 v2, v10, v2
	v_lshlrev_b32_e32 v3, 2, v3
	v_add_f32_e32 v6, v23, v24
	ds_bpermute_b32 v5, v3, v2
	v_add_f32_e32 v6, v6, v22
	v_add_f32_e32 v6, v21, v6
	v_add_f32_e32 v6, v20, v6
	ds_bpermute_b32 v7, v3, v6
	s_waitcnt lgkmcnt(0)
	v_add_f32_e32 v2, v2, v5
	v_xor_b32_e32 v5, 32, v183
	v_cmp_lt_i32_e32 vcc, v5, v4
	v_add_f32_e32 v4, v6, v7
	s_nop 0
	v_cndmask_b32_e32 v3, v183, v5, vcc
	v_lshlrev_b32_e32 v5, 2, v3
	ds_bpermute_b32 v3, v5, v2
	ds_bpermute_b32 v5, v5, v4
	s_and_saveexec_b64 s[6:7], s[2:3]
	s_cbranch_execz .LBB0_245
	v_lshlrev_b64 v[6:7], 2, v[18:19]
	v_lshl_add_u64 v[8:9], s[78:79], 0, v[6:7]
	v_lshl_add_u64 v[6:7], s[76:77], 0, v[6:7]
	s_waitcnt lgkmcnt(0)
	v_add_f32_e32 v2, v2, v3
	v_add_f32_e32 v4, v4, v5
	global_atomic_add_f32 v[6:7], v2, off
	global_atomic_add_f32 v[8:9], v4, off

; __global__ void __launch_bounds__(NWAVES * 64, 2) hymba_fwd(Args args) {
;     unsigned long long pr_t0 = 0, pr_dt = 0;
;     ...
;     extern __shared__ __attribute__((aligned(16))) unsigned char lds[];
	.amdhsa_kernel _Z9hymba_fwd4Args
		.amdhsa_group_segment_fixed_size 16384
		.amdhsa_private_segment_fixed_size 0
		.amdhsa_kernarg_size 432
		.amdhsa_user_sgpr_count 2
		.amdhsa_user_sgpr_dispatch_ptr 0
		.amdhsa_user_sgpr_queue_ptr 0
		.amdhsa_user_sgpr_kernarg_segment_ptr 1
		.amdhsa_user_sgpr_dispatch_id 0
		.amdhsa_user_sgpr_kernarg_preload_length 0
		.amdhsa_user_sgpr_kernarg_preload_offset 0
		.amdhsa_user_sgpr_private_segment_size 0
		.amdhsa_uses_dynamic_stack 0
		.amdhsa_enable_private_segment 0
		.amdhsa_system_sgpr_workgroup_id_x 1
		.amdhsa_system_sgpr_workgroup_id_y 0
		.amdhsa_system_sgpr_workgroup_id_z 0
		.amdhsa_system_sgpr_workgroup_info 0
		.amdhsa_system_vgpr_workitem_id 0
		.amdhsa_next_free_vgpr 252
		.amdhsa_next_free_sgpr 102
		.amdhsa_accum_offset 252
		.amdhsa_reserve_vcc 1
		.amdhsa_float_round_mode_32 0
		.amdhsa_float_round_mode_16_64 0
		.amdhsa_float_denorm_mode_32 3
		.amdhsa_float_denorm_mode_16_64 3
		.amdhsa_dx10_clamp 1
		.amdhsa_ieee_mode 1
		.amdhsa_fp16_overflow 0
		.amdhsa_tg_split 0
		.amdhsa_exception_fp_ieee_invalid_op 0
		.amdhsa_exception_fp_denorm_src 0
		.amdhsa_exception_fp_ieee_div_zero 0
		.amdhsa_exception_fp_ieee_overflow 0
		.amdhsa_exception_fp_ieee_underflow 0
		.amdhsa_exception_fp_ieee_inexact 0
		.amdhsa_exception_int_div_zero 0
	.end_amdhsa_kernel

; __global__ void __launch_bounds__(NWAVES * 64, 2) hymba_fwd(Args args) {
;     unsigned long long pr_t0 = 0, pr_dt = 0;
;     ...
;     extern __shared__ __attribute__((aligned(16))) unsigned char lds[];
amdhsa.kernels:
  - .agpr_count:     0
    .args:
      - .offset:         0
        .size:           176
        .value_kind:     by_value
      - .offset:         176
        .size:           4
        .value_kind:     hidden_block_count_x
      - .offset:         180
        .size:           4
        .value_kind:     hidden_block_count_y
      - .offset:         184
        .size:           4
        .value_kind:     hidden_block_count_z
      - .offset:         188
        .size:           2
        .value_kind:     hidden_group_size_x
      - .offset:         190
        .size:           2
        .value_kind:     hidden_group_size_y
      - .offset:         192
        .size:           2
        .value_kind:     hidden_group_size_z
      - .offset:         194
        .size:           2
        .value_kind:     hidden_remainder_x
      - .offset:         196
        .size:           2
        .value_kind:     hidden_remainder_y
      - .offset:         198
        .size:           2
        .value_kind:     hidden_remainder_z
      - .offset:         216
        .size:           8
        .value_kind:     hidden_global_offset_x
      - .offset:         224
        .size:           8
        .value_kind:     hidden_global_offset_y
      - .offset:         232
        .size:           8
        .value_kind:     hidden_global_offset_z
      - .offset:         240
        .size:           2
        .value_kind:     hidden_grid_dims
      - .offset:         296
        .size:           4
        .value_kind:     hidden_dynamic_lds_size
    .group_segment_fixed_size: 16384
    .kernarg_segment_align: 8
    .kernarg_segment_size: 432
    .language:       OpenCL C
    .language_version:
      - 2
      - 0
    .max_flat_workgroup_size: 512
    .name:           _Z9hymba_fwd4Args
    .private_segment_fixed_size: 0
    .sgpr_count:     108
    .sgpr_spill_count: 121
    .symbol:         _Z9hymba_fwd4Args.kd
    .uniform_work_group_size: 1
    .uses_dynamic_stack: false
    .vgpr_count:     252
    .vgpr_spill_count: 0
    .wavefront_size: 64
